# loop-edge rotation (docs 7.11) on 20 GEMM K-loops: counter/offset SALU and exit test moved in front of the loop-closing barrier, back edge lands on a barrier copy above the loop head; otherwise v67
# baseline (speedup 1.0000x reference)
; template <class Epi, class Sched, bool ALIGN_EPI = false, bool SP2 = false>
; __device__ __forceinline__ void gemm_phase(PG8_LAS unsigned char* lds, const Gemm g, const Sched& S, const Epi& E, const int wid  ) {
;     ...
;         const bool has_next = S.next(ui + 1, nxt); nxt.same = (has_next && nxt.pm == cur.pm) ? 1 : 0;
;         const unsigned nA = has_next ? (unsigned)g.asel(nxt.pn) * (unsigned)g.a_stride + (unsigned)nxt.pm * tstep : cA, nB = has_next ? (unsigned)nxt.pn * tstep : cB;
;         for (int t = 0; t < nt; t += 2) {
;             const bool last = (t == nt - 2);
;             const unsigned a1 = cA + (unsigned)(t + 1) * kstep;
;             const unsigned a2 = last ? nA : cA + (unsigned)(t + 2) * kstep, b2 = last ? nB : cB + (unsigned)(t + 2) * kstep;
;             const unsigned a3 = a2 + kstep, b3 = b2 + kstep;
;             if (last && has_next) S.a_ready(nxt);
;     ...
; #pragma unroll
;         for (int a = 0; a < 2; ++a)
; #pragma unroll
;             for (int b = 0; b < 2; ++b)
; #pragma unroll
;                 for (int m = 0; m < 4; ++m)
; #pragma unroll
;                     for (int n = 0; n < 2; ++n) acc[a][b][m][n] = (f32x4){0.f, 0.f, 0.f, 0.f};
;         cur = nxt; cA = nA; cB = nB; ++ui;
.LBB0_203:
	s_lshl_b32 s60, s59, 20
	s_and_b64 s[14:15], s[4:5], exec
	s_cselect_b32 s63, s60, s65
	s_lshl_b32 s61, s58, 20
	s_and_b64 s[14:15], s[4:5], exec
	v_mov_b32_e32 v0, 0
	s_cselect_b32 s64, s61, s66
	s_add_i32 s65, s65, 0x80080
	s_addk_i32 s66, 0x100
	s_mov_b32 s67, -2
	v_mov_b32_e32 v1, v0
	s_waitcnt lgkmcnt(7)
	v_mov_b32_e32 v2, v0
	v_mov_b32_e32 v3, v0
	s_waitcnt lgkmcnt(6)
	v_mov_b32_e32 v4, v0
	v_mov_b32_e32 v5, v0
	s_waitcnt lgkmcnt(5)
	v_mov_b32_e32 v6, v0
	v_mov_b32_e32 v7, v0
	s_waitcnt lgkmcnt(2)
	v_mov_b32_e32 v12, v0
	v_mov_b32_e32 v13, v0
	s_waitcnt lgkmcnt(1)
	v_mov_b32_e32 v14, v0
	v_mov_b32_e32 v15, v0
	v_mov_b32_e32 v20, v0
	v_mov_b32_e32 v21, v0
	v_mov_b32_e32 v22, v0
	v_mov_b32_e32 v23, v0
	v_mov_b32_e32 v28, v0
	v_mov_b32_e32 v29, v0
	v_mov_b32_e32 v30, v0
	v_mov_b32_e32 v31, v0
	v_mov_b32_e32 v36, v0
	v_mov_b32_e32 v37, v0
	v_mov_b32_e32 v38, v0
	v_mov_b32_e32 v39, v0
	v_mov_b32_e32 v44, v0
	v_mov_b32_e32 v45, v0
	v_mov_b32_e32 v46, v0
	v_mov_b32_e32 v47, v0
	v_mov_b32_e32 v52, v0
	v_mov_b32_e32 v53, v0
	v_mov_b32_e32 v54, v0
	v_mov_b32_e32 v55, v0
	v_mov_b32_e32 v8, v0
	v_mov_b32_e32 v9, v0
	v_mov_b32_e32 v10, v0
	v_mov_b32_e32 v11, v0
	s_waitcnt lgkmcnt(0)
	v_mov_b32_e32 v16, v0
	v_mov_b32_e32 v17, v0
	s_waitcnt lgkmcnt(0)
	v_mov_b32_e32 v18, v0
	v_mov_b32_e32 v19, v0
	v_mov_b32_e32 v24, v0
	v_mov_b32_e32 v25, v0
	v_mov_b32_e32 v26, v0
	v_mov_b32_e32 v27, v0
	v_mov_b32_e32 v32, v0
	v_mov_b32_e32 v33, v0
	v_mov_b32_e32 v34, v0
	v_mov_b32_e32 v35, v0
	v_mov_b32_e32 v40, v0
	v_mov_b32_e32 v41, v0
	v_mov_b32_e32 v42, v0
	v_mov_b32_e32 v43, v0
	v_mov_b32_e32 v48, v0
	v_mov_b32_e32 v49, v0
	v_mov_b32_e32 v50, v0
	v_mov_b32_e32 v51, v0
	v_mov_b32_e32 v56, v0
	v_mov_b32_e32 v57, v0
	v_mov_b32_e32 v58, v0
	v_mov_b32_e32 v59, v0
	v_mov_b32_e32 v60, v0
	v_mov_b32_e32 v61, v0
	v_mov_b32_e32 v62, v0
	v_mov_b32_e32 v63, v0
	v_mov_b32_e32 v64, v0
	v_mov_b32_e32 v65, v0
	v_mov_b32_e32 v66, v0
	v_mov_b32_e32 v67, v0
	v_mov_b32_e32 v68, v0
	v_mov_b32_e32 v69, v0
	v_mov_b32_e32 v70, v0
	v_mov_b32_e32 v71, v0
	v_mov_b32_e32 v76, v0
	v_mov_b32_e32 v77, v0
	v_mov_b32_e32 v78, v0
	v_mov_b32_e32 v79, v0
	v_mov_b32_e32 v84, v0
	v_mov_b32_e32 v85, v0
	v_mov_b32_e32 v86, v0
	v_mov_b32_e32 v87, v0
	v_mov_b32_e32 v92, v0
	v_mov_b32_e32 v93, v0
	v_mov_b32_e32 v94, v0
	v_mov_b32_e32 v95, v0
	v_mov_b32_e32 v100, v0
	v_mov_b32_e32 v101, v0
	v_mov_b32_e32 v102, v0
	v_mov_b32_e32 v103, v0
	v_mov_b32_e32 v108, v0
	v_mov_b32_e32 v109, v0
	v_mov_b32_e32 v110, v0
	v_mov_b32_e32 v111, v0
	v_mov_b32_e32 v116, v0
	v_mov_b32_e32 v117, v0
	v_mov_b32_e32 v118, v0
	v_mov_b32_e32 v119, v0
	v_mov_b32_e32 v72, v0
	v_mov_b32_e32 v73, v0
	v_mov_b32_e32 v74, v0
	v_mov_b32_e32 v75, v0
	v_mov_b32_e32 v80, v0
	v_mov_b32_e32 v81, v0
	v_mov_b32_e32 v82, v0
	v_mov_b32_e32 v83, v0
	v_mov_b32_e32 v88, v0
	v_mov_b32_e32 v89, v0
	v_mov_b32_e32 v90, v0
	v_mov_b32_e32 v91, v0
	v_mov_b32_e32 v96, v0
	v_mov_b32_e32 v97, v0
	v_mov_b32_e32 v98, v0
	v_mov_b32_e32 v99, v0
	v_mov_b32_e32 v104, v0
	v_mov_b32_e32 v105, v0
	v_mov_b32_e32 v106, v0
	v_mov_b32_e32 v107, v0
	v_mov_b32_e32 v112, v0
	v_mov_b32_e32 v113, v0
	v_mov_b32_e32 v114, v0
	v_mov_b32_e32 v115, v0
	v_mov_b32_e32 v120, v0
	v_mov_b32_e32 v121, v0
	v_mov_b32_e32 v122, v0
	v_mov_b32_e32 v123, v0
	v_mov_b32_e32 v124, v0
	v_mov_b32_e32 v125, v0
	v_mov_b32_e32 v126, v0
	v_mov_b32_e32 v127, v0
	s_branch .LBB0_204

; #define PG8_STAGE(bufoff, soff, voff) do { _Pragma("unroll") for (int _i = 0; _i < 2; ++_i) \
;         __builtin_amdgcn_raw_ptr_buffer_load_lds(rs_##voff, (PG8_LAS unsigned*)(lds + (bufoff) + ldsw + _i * 8192), 16, (int)(voff)[_i], (int)(soff), 0, 0); } while (0)
; #define PG8_LDA(dst, b, h) do { _Pragma("unroll") for (int m = 0; m < 4; ++m) _Pragma("unroll") for (int k = 0; k < 2; ++k) dst[m][k] = *(const PG8_LAS bf16x8*)(lds + PG8_SA(b, h) + aoff + m * 2048 + k * 1024); } while (0)
; #define PG8_LDB(dst, b, h) do { _Pragma("unroll") for (int n = 0; n < 2; ++n) _Pragma("unroll") for (int k = 0; k < 2; ++k) dst[n][k] = *(const PG8_LAS bf16x8*)(lds + PG8_SB(b, h) + boff + n * 2048 + k * 1024); } while (0)
; #define PG8_MMA(ai, bj, At, Bt) do { __builtin_amdgcn_s_setprio(1); _Pragma("unroll") for (int m = 0; m < 4; ++m) _Pragma("unroll") for (int n = 0; n < 2; ++n) _Pragma("unroll") for (int k = 0; k < 2; ++k) \
;         acc[ai][bj][m][n] = __builtin_amdgcn_mfma_f32_16x16x32_bf16(Bt[n][k], At[m][k], acc[ai][bj][m][n], 0, 0, 0); __builtin_amdgcn_s_setprio(0); } while (0)
; #define PG8_WAIT_V(n) asm volatile("s_waitcnt vmcnt(" #n ")" ::: "memory")
; #define PG8_WAIT_L(n) asm volatile("s_waitcnt lgkmcnt(" #n ")" ::: "memory")
; #define PG8_BAR __builtin_amdgcn_s_barrier()
; #define PG8_SCHED __builtin_amdgcn_sched_barrier(0)
; template <class Epi, class Sched, bool ALIGN_EPI = false, bool SP2 = false>
; __device__ __forceinline__ void gemm_phase(PG8_LAS unsigned char* lds, const Gemm g, const Sched& S, const Epi& E, const int wid  ) {
;     ...
;             PG8_LDB(B0, 0, 0); PG8_LDB(B1, 0, 1); PG8_SCHED; PG8_LDA(At, 0, 0); PG8_STAGE(PG8_SA(1, 1), a1 + hstep, voffA);
;             PG8_WAIT_V(8); PG8_WAIT_L(0); PG8_BAR; PG8_MMA(0, 0, At, B0); PG8_MMA(0, 1, At, B1); PG8_BAR; PG8_SCHED;
;             PG8_LDA(At, 0, 1); PG8_STAGE(PG8_SB(0, 0), b2, voffB); PG8_STAGE(PG8_SB(0, 1), b2 + hstep, voffB); PG8_STAGE(PG8_SA(0, 0), a2, voffA);
;             PG8_WAIT_V(8); PG8_WAIT_L(0); PG8_BAR; PG8_MMA(1, 0, At, B0); PG8_MMA(1, 1, At, B1); PG8_BAR; PG8_SCHED;
.LBB0_204:
	ds_read_b128 v[132:135], v144
	ds_read_b128 v[150:153], v144 offset:1024
	ds_read_b128 v[154:157], v144 offset:2048
	ds_read_b128 v[158:161], v144 offset:3072
	ds_read_b128 v[162:165], v145
	ds_read_b128 v[166:169], v145 offset:1024
	ds_read_b128 v[170:173], v145 offset:2048
	ds_read_b128 v[174:177], v145 offset:3072
	s_add_i32 s14, s65, 0xfff80080
	s_cmp_eq_u32 s67, 28
	s_cselect_b32 s70, s63, s14
	s_cselect_b32 s69, s64, s66
	s_or_b32 s68, s70, 0x80
	s_mov_b32 m0, s47
	ds_read_b128 v[178:181], v146
	ds_read_b128 v[182:185], v146 offset:1024
	ds_read_b128 v[186:189], v146 offset:2048
	ds_read_b128 v[190:193], v146 offset:3072
	ds_read_b128 v[194:197], v146 offset:4096
	ds_read_b128 v[198:201], v146 offset:5120
	ds_read_b128 v[202:205], v146 offset:6144
	ds_read_b128 v[206:209], v146 offset:7168
	buffer_load_dwordx4 v138, s[8:11], s65 offen lds
	s_mov_b32 m0, s48
	s_nop 0
	buffer_load_dwordx4 v140, s[8:11], s65 offen lds
	s_waitcnt vmcnt(8)
	s_waitcnt lgkmcnt(0)
	s_barrier
	s_setprio 1
	s_waitcnt lgkmcnt(7)
	v_mfma_f32_16x16x32_bf16 v[124:127], v[132:135], v[178:181], v[124:127]
	v_mfma_f32_16x16x32_bf16 v[120:123], v[154:157], v[178:181], v[120:123]
	s_waitcnt lgkmcnt(5)
	v_mfma_f32_16x16x32_bf16 v[112:115], v[132:135], v[186:189], v[112:115]
	v_mfma_f32_16x16x32_bf16 v[104:107], v[154:157], v[186:189], v[104:107]
	s_waitcnt lgkmcnt(3)
	v_mfma_f32_16x16x32_bf16 v[96:99], v[132:135], v[194:197], v[96:99]
	v_mfma_f32_16x16x32_bf16 v[88:91], v[154:157], v[194:197], v[88:91]
	s_waitcnt lgkmcnt(1)
	v_mfma_f32_16x16x32_bf16 v[80:83], v[132:135], v[202:205], v[80:83]
	v_mfma_f32_16x16x32_bf16 v[72:75], v[154:157], v[202:205], v[72:75]
	v_mfma_f32_16x16x32_bf16 v[124:127], v[150:153], v[182:185], v[124:127]
	v_mfma_f32_16x16x32_bf16 v[120:123], v[158:161], v[182:185], v[120:123]
	v_mfma_f32_16x16x32_bf16 v[112:115], v[150:153], v[190:193], v[112:115]
	v_mfma_f32_16x16x32_bf16 v[104:107], v[158:161], v[190:193], v[104:107]
	v_mfma_f32_16x16x32_bf16 v[96:99], v[150:153], v[198:201], v[96:99]
	v_mfma_f32_16x16x32_bf16 v[88:91], v[158:161], v[198:201], v[88:91]
	s_waitcnt lgkmcnt(0)
	v_mfma_f32_16x16x32_bf16 v[80:83], v[150:153], v[206:209], v[80:83]
	v_mfma_f32_16x16x32_bf16 v[72:75], v[158:161], v[206:209], v[72:75]
	s_setprio 0
	s_setprio 1
	v_mfma_f32_16x16x32_bf16 v[116:119], v[162:165], v[178:181], v[116:119]
	v_mfma_f32_16x16x32_bf16 v[108:111], v[170:173], v[178:181], v[108:111]
	v_mfma_f32_16x16x32_bf16 v[100:103], v[162:165], v[186:189], v[100:103]
	v_mfma_f32_16x16x32_bf16 v[92:95], v[170:173], v[186:189], v[92:95]
	v_mfma_f32_16x16x32_bf16 v[84:87], v[162:165], v[194:197], v[84:87]
	v_mfma_f32_16x16x32_bf16 v[76:79], v[170:173], v[194:197], v[76:79]
	v_mfma_f32_16x16x32_bf16 v[68:71], v[162:165], v[202:205], v[68:71]
	v_mfma_f32_16x16x32_bf16 v[64:67], v[170:173], v[202:205], v[64:67]
	v_mfma_f32_16x16x32_bf16 v[116:119], v[166:169], v[182:185], v[116:119]
	v_mfma_f32_16x16x32_bf16 v[108:111], v[174:177], v[182:185], v[108:111]
	v_mfma_f32_16x16x32_bf16 v[100:103], v[166:169], v[190:193], v[100:103]
	v_mfma_f32_16x16x32_bf16 v[92:95], v[174:177], v[190:193], v[92:95]
	v_mfma_f32_16x16x32_bf16 v[84:87], v[166:169], v[198:201], v[84:87]
	v_mfma_f32_16x16x32_bf16 v[76:79], v[174:177], v[198:201], v[76:79]
	v_mfma_f32_16x16x32_bf16 v[68:71], v[166:169], v[206:209], v[68:71]
	v_mfma_f32_16x16x32_bf16 v[64:67], v[174:177], v[206:209], v[64:67]
	s_setprio 0
	s_barrier
	s_mov_b32 m0, s30
	s_mov_b32 s14, s10
	s_mov_b32 s15, s11
	ds_read_b128 v[178:181], v146 offset:16384
	ds_read_b128 v[182:185], v146 offset:17408
	ds_read_b128 v[186:189], v146 offset:18432
	ds_read_b128 v[190:193], v146 offset:19456
	ds_read_b128 v[194:197], v146 offset:20480
	ds_read_b128 v[198:201], v146 offset:21504
	ds_read_b128 v[202:205], v146 offset:22528
	ds_read_b128 v[206:209], v146 offset:23552
	buffer_load_dwordx4 v139, s[12:15], s69 offen lds
	s_mov_b32 m0, s31
	s_add_i32 s71, s69, 0x80000
	buffer_load_dwordx4 v141, s[12:15], s69 offen lds
	s_mov_b32 m0, s33
	s_nop 0
	buffer_load_dwordx4 v139, s[12:15], s71 offen lds
	s_mov_b32 m0, s34
	s_nop 0
	buffer_load_dwordx4 v141, s[12:15], s71 offen lds
	s_mov_b32 m0, s29
	s_nop 0
	buffer_load_dwordx4 v138, s[8:11], s70 offen lds
	s_mov_b32 m0, s35
	s_nop 0
	buffer_load_dwordx4 v140, s[8:11], s70 offen lds
	s_waitcnt vmcnt(8)
	s_waitcnt lgkmcnt(0)
	s_barrier
	s_setprio 1
	s_waitcnt lgkmcnt(7)
	v_mfma_f32_16x16x32_bf16 v[60:63], v[132:135], v[178:181], v[60:63]
	v_mfma_f32_16x16x32_bf16 v[56:59], v[154:157], v[178:181], v[56:59]
	s_waitcnt lgkmcnt(5)
	v_mfma_f32_16x16x32_bf16 v[48:51], v[132:135], v[186:189], v[48:51]
	v_mfma_f32_16x16x32_bf16 v[40:43], v[154:157], v[186:189], v[40:43]
	s_waitcnt lgkmcnt(3)
	v_mfma_f32_16x16x32_bf16 v[32:35], v[132:135], v[194:197], v[32:35]
	v_mfma_f32_16x16x32_bf16 v[24:27], v[154:157], v[194:197], v[24:27]
	s_waitcnt lgkmcnt(1)
	v_mfma_f32_16x16x32_bf16 v[16:19], v[132:135], v[202:205], v[16:19]
	v_mfma_f32_16x16x32_bf16 v[8:11], v[154:157], v[202:205], v[8:11]
	v_mfma_f32_16x16x32_bf16 v[60:63], v[150:153], v[182:185], v[60:63]
	v_mfma_f32_16x16x32_bf16 v[56:59], v[158:161], v[182:185], v[56:59]
	v_mfma_f32_16x16x32_bf16 v[48:51], v[150:153], v[190:193], v[48:51]
	v_mfma_f32_16x16x32_bf16 v[40:43], v[158:161], v[190:193], v[40:43]
	v_mfma_f32_16x16x32_bf16 v[32:35], v[150:153], v[198:201], v[32:35]
	v_mfma_f32_16x16x32_bf16 v[24:27], v[158:161], v[198:201], v[24:27]
	s_waitcnt lgkmcnt(0)
	v_mfma_f32_16x16x32_bf16 v[16:19], v[150:153], v[206:209], v[16:19]
	v_mfma_f32_16x16x32_bf16 v[8:11], v[158:161], v[206:209], v[8:11]
	s_setprio 0
	s_setprio 1
	v_mfma_f32_16x16x32_bf16 v[52:55], v[162:165], v[178:181], v[52:55]
	v_mfma_f32_16x16x32_bf16 v[44:47], v[170:173], v[178:181], v[44:47]
	v_mfma_f32_16x16x32_bf16 v[36:39], v[162:165], v[186:189], v[36:39]
	v_mfma_f32_16x16x32_bf16 v[28:31], v[170:173], v[186:189], v[28:31]
	v_mfma_f32_16x16x32_bf16 v[20:23], v[162:165], v[194:197], v[20:23]
	v_mfma_f32_16x16x32_bf16 v[12:15], v[170:173], v[194:197], v[12:15]
	v_mfma_f32_16x16x32_bf16 v[4:7], v[162:165], v[202:205], v[4:7]
	v_mfma_f32_16x16x32_bf16 v[0:3], v[170:173], v[202:205], v[0:3]
	v_mfma_f32_16x16x32_bf16 v[52:55], v[166:169], v[182:185], v[52:55]
	v_mfma_f32_16x16x32_bf16 v[44:47], v[174:177], v[182:185], v[44:47]
	v_mfma_f32_16x16x32_bf16 v[36:39], v[166:169], v[190:193], v[36:39]
	v_mfma_f32_16x16x32_bf16 v[28:31], v[174:177], v[190:193], v[28:31]
	v_mfma_f32_16x16x32_bf16 v[20:23], v[166:169], v[198:201], v[20:23]
	v_mfma_f32_16x16x32_bf16 v[12:15], v[174:177], v[198:201], v[12:15]
	v_mfma_f32_16x16x32_bf16 v[4:7], v[166:169], v[206:209], v[4:7]
	v_mfma_f32_16x16x32_bf16 v[0:3], v[174:177], v[206:209], v[0:3]
	s_setprio 0
	s_barrier
; #define PG8_STAGE(bufoff, soff, voff) do { _Pragma("unroll") for (int _i = 0; _i < 2; ++_i) \
;         __builtin_amdgcn_raw_ptr_buffer_load_lds(rs_##voff, (PG8_LAS unsigned*)(lds + (bufoff) + ldsw + _i * 8192), 16, (int)(voff)[_i], (int)(soff), 0, 0); } while (0)
; #define PG8_LDA(dst, b, h) do { _Pragma("unroll") for (int m = 0; m < 4; ++m) _Pragma("unroll") for (int k = 0; k < 2; ++k) dst[m][k] = *(const PG8_LAS bf16x8*)(lds + PG8_SA(b, h) + aoff + m * 2048 + k * 1024); } while (0)
; #define PG8_LDB(dst, b, h) do { _Pragma("unroll") for (int n = 0; n < 2; ++n) _Pragma("unroll") for (int k = 0; k < 2; ++k) dst[n][k] = *(const PG8_LAS bf16x8*)(lds + PG8_SB(b, h) + boff + n * 2048 + k * 1024); } while (0)
; #define PG8_MMA(ai, bj, At, Bt) do { __builtin_amdgcn_s_setprio(1); _Pragma("unroll") for (int m = 0; m < 4; ++m) _Pragma("unroll") for (int n = 0; n < 2; ++n) _Pragma("unroll") for (int k = 0; k < 2; ++k) \
;         acc[ai][bj][m][n] = __builtin_amdgcn_mfma_f32_16x16x32_bf16(Bt[n][k], At[m][k], acc[ai][bj][m][n], 0, 0, 0); __builtin_amdgcn_s_setprio(0); } while (0)
; #define PG8_WAIT_V(n) asm volatile("s_waitcnt vmcnt(" #n ")" ::: "memory")
; #define PG8_WAIT_L(n) asm volatile("s_waitcnt lgkmcnt(" #n ")" ::: "memory")
; #define PG8_BAR __builtin_amdgcn_s_barrier()
; #define PG8_SCHED __builtin_amdgcn_sched_barrier(0)
; template <class Epi, class Sched, bool ALIGN_EPI = false, bool SP2 = false>
; __device__ __forceinline__ void gemm_phase(PG8_LAS unsigned char* lds, const Gemm g, const Sched& S, const Epi& E, const int wid  ) {
;     ...
;             PG8_LDB(B0, 1, 0); PG8_LDB(B1, 1, 1); PG8_SCHED; PG8_LDA(At, 1, 0); PG8_STAGE(PG8_SA(0, 1), a2 + hstep, voffA);
;             PG8_WAIT_V(8); PG8_WAIT_L(0); PG8_BAR; PG8_MMA(0, 0, At, B0); PG8_MMA(0, 1, At, B1); PG8_BAR; PG8_SCHED;
;             PG8_LDA(At, 1, 1); PG8_STAGE(PG8_SB(1, 0), b3, voffB); PG8_STAGE(PG8_SB(1, 1), b3 + hstep, voffB); PG8_STAGE(PG8_SA(1, 0), a3, voffA);
;             PG8_WAIT_V(8); PG8_WAIT_L(0); PG8_BAR; PG8_MMA(1, 0, At, B0); PG8_MMA(1, 1, At, B1); PG8_BAR; PG8_SCHED;
	ds_read_b128 v[132:135], v147
	ds_read_b128 v[150:153], v147 offset:1024
	ds_read_b128 v[154:157], v147 offset:2048
	ds_read_b128 v[158:161], v147 offset:3072
	ds_read_b128 v[162:165], v148
	ds_read_b128 v[166:169], v148 offset:1024
	ds_read_b128 v[170:173], v148 offset:2048
	ds_read_b128 v[174:177], v148 offset:3072
	s_add_i32 s70, s70, 0x80000
	s_mov_b32 m0, s36
	ds_read_b128 v[178:181], v146 offset:32768
	ds_read_b128 v[182:185], v146 offset:33792
	ds_read_b128 v[186:189], v146 offset:34816
	ds_read_b128 v[190:193], v146 offset:35840
	ds_read_b128 v[194:197], v146 offset:36864
	ds_read_b128 v[198:201], v146 offset:37888
	ds_read_b128 v[202:205], v146 offset:38912
	ds_read_b128 v[206:209], v146 offset:39936
	buffer_load_dwordx4 v138, s[8:11], s70 offen lds
	s_mov_b32 m0, s37
	s_nop 0
	buffer_load_dwordx4 v140, s[8:11], s70 offen lds
	s_waitcnt vmcnt(8)
	s_waitcnt lgkmcnt(0)
	s_barrier
	s_setprio 1
	s_waitcnt lgkmcnt(7)
	v_mfma_f32_16x16x32_bf16 v[124:127], v[132:135], v[178:181], v[124:127]
	v_mfma_f32_16x16x32_bf16 v[120:123], v[154:157], v[178:181], v[120:123]
	s_waitcnt lgkmcnt(5)
	v_mfma_f32_16x16x32_bf16 v[112:115], v[132:135], v[186:189], v[112:115]
	v_mfma_f32_16x16x32_bf16 v[104:107], v[154:157], v[186:189], v[104:107]
	s_waitcnt lgkmcnt(3)
	v_mfma_f32_16x16x32_bf16 v[96:99], v[132:135], v[194:197], v[96:99]
	v_mfma_f32_16x16x32_bf16 v[88:91], v[154:157], v[194:197], v[88:91]
	s_waitcnt lgkmcnt(1)
	v_mfma_f32_16x16x32_bf16 v[80:83], v[132:135], v[202:205], v[80:83]
	v_mfma_f32_16x16x32_bf16 v[72:75], v[154:157], v[202:205], v[72:75]
	v_mfma_f32_16x16x32_bf16 v[124:127], v[150:153], v[182:185], v[124:127]
	v_mfma_f32_16x16x32_bf16 v[120:123], v[158:161], v[182:185], v[120:123]
	v_mfma_f32_16x16x32_bf16 v[112:115], v[150:153], v[190:193], v[112:115]
	v_mfma_f32_16x16x32_bf16 v[104:107], v[158:161], v[190:193], v[104:107]
	v_mfma_f32_16x16x32_bf16 v[96:99], v[150:153], v[198:201], v[96:99]
	v_mfma_f32_16x16x32_bf16 v[88:91], v[158:161], v[198:201], v[88:91]
	s_waitcnt lgkmcnt(0)
	v_mfma_f32_16x16x32_bf16 v[80:83], v[150:153], v[206:209], v[80:83]
	v_mfma_f32_16x16x32_bf16 v[72:75], v[158:161], v[206:209], v[72:75]
	s_setprio 0
	s_setprio 1
	v_mfma_f32_16x16x32_bf16 v[116:119], v[162:165], v[178:181], v[116:119]
	v_mfma_f32_16x16x32_bf16 v[108:111], v[170:173], v[178:181], v[108:111]
	v_mfma_f32_16x16x32_bf16 v[100:103], v[162:165], v[186:189], v[100:103]
	v_mfma_f32_16x16x32_bf16 v[92:95], v[170:173], v[186:189], v[92:95]
	v_mfma_f32_16x16x32_bf16 v[84:87], v[162:165], v[194:197], v[84:87]
	v_mfma_f32_16x16x32_bf16 v[76:79], v[170:173], v[194:197], v[76:79]
	v_mfma_f32_16x16x32_bf16 v[68:71], v[162:165], v[202:205], v[68:71]
	v_mfma_f32_16x16x32_bf16 v[64:67], v[170:173], v[202:205], v[64:67]
	v_mfma_f32_16x16x32_bf16 v[116:119], v[166:169], v[182:185], v[116:119]
	v_mfma_f32_16x16x32_bf16 v[108:111], v[174:177], v[182:185], v[108:111]
	v_mfma_f32_16x16x32_bf16 v[100:103], v[166:169], v[190:193], v[100:103]
	v_mfma_f32_16x16x32_bf16 v[92:95], v[174:177], v[190:193], v[92:95]
	v_mfma_f32_16x16x32_bf16 v[84:87], v[166:169], v[198:201], v[84:87]
	v_mfma_f32_16x16x32_bf16 v[76:79], v[174:177], v[198:201], v[76:79]
	v_mfma_f32_16x16x32_bf16 v[68:71], v[166:169], v[206:209], v[68:71]
	v_mfma_f32_16x16x32_bf16 v[64:67], v[174:177], v[206:209], v[64:67]
	s_setprio 0
	s_barrier
	s_mov_b32 m0, s40
	s_or_b32 s70, s69, 0x80
	ds_read_b128 v[178:181], v146 offset:49152
	ds_read_b128 v[182:185], v146 offset:50176
	ds_read_b128 v[186:189], v146 offset:51200
	ds_read_b128 v[190:193], v146 offset:52224
	ds_read_b128 v[194:197], v146 offset:53248
	ds_read_b128 v[198:201], v146 offset:54272
	ds_read_b128 v[202:205], v146 offset:55296
	ds_read_b128 v[206:209], v146 offset:56320
	buffer_load_dwordx4 v139, s[12:15], s70 offen lds
	s_mov_b32 m0, s41
	s_add_i32 s69, s69, 0x80080
	buffer_load_dwordx4 v141, s[12:15], s70 offen lds
	s_mov_b32 m0, s44
	s_nop 0
	buffer_load_dwordx4 v139, s[12:15], s69 offen lds
	s_mov_b32 m0, s45
	s_nop 0
	buffer_load_dwordx4 v141, s[12:15], s69 offen lds
	s_mov_b32 m0, s42
	s_nop 0
	buffer_load_dwordx4 v138, s[8:11], s68 offen lds
	s_mov_b32 m0, s43
	s_nop 0
	buffer_load_dwordx4 v140, s[8:11], s68 offen lds
	s_waitcnt vmcnt(8)
	s_waitcnt lgkmcnt(0)
	s_barrier
	s_setprio 1
	s_waitcnt lgkmcnt(7)
	v_mfma_f32_16x16x32_bf16 v[60:63], v[132:135], v[178:181], v[60:63]
	v_mfma_f32_16x16x32_bf16 v[56:59], v[154:157], v[178:181], v[56:59]
	s_waitcnt lgkmcnt(5)
	v_mfma_f32_16x16x32_bf16 v[48:51], v[132:135], v[186:189], v[48:51]
	v_mfma_f32_16x16x32_bf16 v[40:43], v[154:157], v[186:189], v[40:43]
	s_waitcnt lgkmcnt(3)
	v_mfma_f32_16x16x32_bf16 v[32:35], v[132:135], v[194:197], v[32:35]
	v_mfma_f32_16x16x32_bf16 v[24:27], v[154:157], v[194:197], v[24:27]
	s_waitcnt lgkmcnt(1)
	v_mfma_f32_16x16x32_bf16 v[16:19], v[132:135], v[202:205], v[16:19]
	v_mfma_f32_16x16x32_bf16 v[8:11], v[154:157], v[202:205], v[8:11]
	v_mfma_f32_16x16x32_bf16 v[60:63], v[150:153], v[182:185], v[60:63]
	v_mfma_f32_16x16x32_bf16 v[56:59], v[158:161], v[182:185], v[56:59]
	v_mfma_f32_16x16x32_bf16 v[48:51], v[150:153], v[190:193], v[48:51]
	v_mfma_f32_16x16x32_bf16 v[40:43], v[158:161], v[190:193], v[40:43]
	v_mfma_f32_16x16x32_bf16 v[32:35], v[150:153], v[198:201], v[32:35]
	v_mfma_f32_16x16x32_bf16 v[24:27], v[158:161], v[198:201], v[24:27]
	s_waitcnt lgkmcnt(0)
	v_mfma_f32_16x16x32_bf16 v[16:19], v[150:153], v[206:209], v[16:19]
	v_mfma_f32_16x16x32_bf16 v[8:11], v[158:161], v[206:209], v[8:11]
	s_setprio 0
	s_setprio 1
	v_mfma_f32_16x16x32_bf16 v[52:55], v[162:165], v[178:181], v[52:55]
	v_mfma_f32_16x16x32_bf16 v[44:47], v[170:173], v[178:181], v[44:47]
	v_mfma_f32_16x16x32_bf16 v[36:39], v[162:165], v[186:189], v[36:39]
	v_mfma_f32_16x16x32_bf16 v[28:31], v[170:173], v[186:189], v[28:31]
	v_mfma_f32_16x16x32_bf16 v[20:23], v[162:165], v[194:197], v[20:23]
	v_mfma_f32_16x16x32_bf16 v[12:15], v[170:173], v[194:197], v[12:15]
	v_mfma_f32_16x16x32_bf16 v[4:7], v[162:165], v[202:205], v[4:7]
	v_mfma_f32_16x16x32_bf16 v[0:3], v[170:173], v[202:205], v[0:3]
	v_mfma_f32_16x16x32_bf16 v[52:55], v[166:169], v[182:185], v[52:55]
	v_mfma_f32_16x16x32_bf16 v[44:47], v[174:177], v[182:185], v[44:47]
	v_mfma_f32_16x16x32_bf16 v[36:39], v[166:169], v[190:193], v[36:39]
	v_mfma_f32_16x16x32_bf16 v[28:31], v[174:177], v[190:193], v[28:31]
	v_mfma_f32_16x16x32_bf16 v[20:23], v[166:169], v[198:201], v[20:23]
	v_mfma_f32_16x16x32_bf16 v[12:15], v[174:177], v[198:201], v[12:15]
	v_mfma_f32_16x16x32_bf16 v[4:7], v[166:169], v[206:209], v[4:7]
	v_mfma_f32_16x16x32_bf16 v[0:3], v[174:177], v[206:209], v[0:3]
	s_setprio 0
	s_add_i32 s67, s67, 2
	s_addk_i32 s65, 0x100
	s_addk_i32 s66, 0x100
	s_cmp_gt_u32 s67, 29
	s_cbranch_scc0 .Lrot_204
	s_barrier
	s_and_b64 vcc, exec, s[18:19]
	s_cbranch_vccz .LBB0_207
	s_barrier

; template <class Epi, class Sched, bool ALIGN_EPI = false, bool SP2 = false>
; __device__ __forceinline__ void gemm_phase(PG8_LAS unsigned char* lds, const Gemm g, const Sched& S, const Epi& E, const int wid  ) {
;     ...
;         const bool has_next = S.next(ui + 1, nxt); nxt.same = (has_next && nxt.pm == cur.pm) ? 1 : 0;
;         const unsigned nA = has_next ? (unsigned)g.asel(nxt.pn) * (unsigned)g.a_stride + (unsigned)nxt.pm * tstep : cA, nB = has_next ? (unsigned)nxt.pn * tstep : cB;
;         for (int t = 0; t < nt; t += 2) {
;             const bool last = (t == nt - 2);
;             const unsigned a1 = cA + (unsigned)(t + 1) * kstep;
;             const unsigned a2 = last ? nA : cA + (unsigned)(t + 2) * kstep, b2 = last ? nB : cB + (unsigned)(t + 2) * kstep;
;             const unsigned a3 = a2 + kstep, b3 = b2 + kstep;
;             if (last && has_next) S.a_ready(nxt);
;     ...
; #pragma unroll
;         for (int a = 0; a < 2; ++a)
; #pragma unroll
;             for (int b = 0; b < 2; ++b)
; #pragma unroll
;                 for (int m = 0; m < 4; ++m)
; #pragma unroll
;                     for (int n = 0; n < 2; ++n) acc[a][b][m][n] = (f32x4){0.f, 0.f, 0.f, 0.f};
;         cur = nxt; cA = nA; cB = nB; ++ui;
.LBB0_563:
	s_lshl_b32 s50, s49, 20
	s_and_b64 s[0:1], s[4:5], exec
	s_cselect_b32 s0, s50, s54
	s_lshl_b32 s51, s48, 20
	s_and_b64 s[14:15], s[4:5], exec
	v_mov_b32_e32 v0, 0
	s_cselect_b32 s1, s51, s55
	s_add_i32 s54, s54, 0x80080
	s_addk_i32 s55, 0x100
	s_mov_b32 s58, -2
	s_waitcnt lgkmcnt(0)
	v_mov_b32_e32 v1, v0
	v_mov_b32_e32 v2, v0
	v_mov_b32_e32 v3, v0
	v_mov_b32_e32 v4, v0
	v_mov_b32_e32 v5, v0
	v_mov_b32_e32 v6, v0
	v_mov_b32_e32 v7, v0
	v_mov_b32_e32 v16, v0
	v_mov_b32_e32 v17, v0
	v_mov_b32_e32 v18, v0
	v_mov_b32_e32 v19, v0
	v_mov_b32_e32 v20, v0
	v_mov_b32_e32 v21, v0
	v_mov_b32_e32 v22, v0
	v_mov_b32_e32 v23, v0
	v_mov_b32_e32 v32, v0
	v_mov_b32_e32 v33, v0
	v_mov_b32_e32 v34, v0
	v_mov_b32_e32 v35, v0
	v_mov_b32_e32 v36, v0
	v_mov_b32_e32 v37, v0
	v_mov_b32_e32 v38, v0
	v_mov_b32_e32 v39, v0
	v_mov_b32_e32 v48, v0
	v_mov_b32_e32 v49, v0
	v_mov_b32_e32 v50, v0
	v_mov_b32_e32 v51, v0
	v_mov_b32_e32 v52, v0
	v_mov_b32_e32 v53, v0
	v_mov_b32_e32 v54, v0
	v_mov_b32_e32 v55, v0
	v_mov_b32_e32 v8, v0
	v_mov_b32_e32 v9, v0
	v_mov_b32_e32 v10, v0
	v_mov_b32_e32 v11, v0
	v_mov_b32_e32 v12, v0
	v_mov_b32_e32 v13, v0
	v_mov_b32_e32 v14, v0
	v_mov_b32_e32 v15, v0
	v_mov_b32_e32 v24, v0
	v_mov_b32_e32 v25, v0
	v_mov_b32_e32 v26, v0
	v_mov_b32_e32 v27, v0
	v_mov_b32_e32 v28, v0
	v_mov_b32_e32 v29, v0
	v_mov_b32_e32 v30, v0
	v_mov_b32_e32 v31, v0
	v_mov_b32_e32 v40, v0
	v_mov_b32_e32 v41, v0
	v_mov_b32_e32 v42, v0
	v_mov_b32_e32 v43, v0
	v_mov_b32_e32 v44, v0
	v_mov_b32_e32 v45, v0
	v_mov_b32_e32 v46, v0
	v_mov_b32_e32 v47, v0
	v_mov_b32_e32 v56, v0
	v_mov_b32_e32 v57, v0
	v_mov_b32_e32 v58, v0
	v_mov_b32_e32 v59, v0
	v_mov_b32_e32 v60, v0
	v_mov_b32_e32 v61, v0
	v_mov_b32_e32 v62, v0
	v_mov_b32_e32 v63, v0
	v_mov_b32_e32 v64, v0
	v_mov_b32_e32 v65, v0
	v_mov_b32_e32 v66, v0
	v_mov_b32_e32 v67, v0
	v_mov_b32_e32 v68, v0
	v_mov_b32_e32 v69, v0
	v_mov_b32_e32 v70, v0
	v_mov_b32_e32 v71, v0
	v_mov_b32_e32 v80, v0
	v_mov_b32_e32 v81, v0
	v_mov_b32_e32 v82, v0
	v_mov_b32_e32 v83, v0
	v_mov_b32_e32 v84, v0
	v_mov_b32_e32 v85, v0
	v_mov_b32_e32 v86, v0
	v_mov_b32_e32 v87, v0
	v_mov_b32_e32 v96, v0
	v_mov_b32_e32 v97, v0
	v_mov_b32_e32 v98, v0
	v_mov_b32_e32 v99, v0
	v_mov_b32_e32 v100, v0
	v_mov_b32_e32 v101, v0
	v_mov_b32_e32 v102, v0
	v_mov_b32_e32 v103, v0
	v_mov_b32_e32 v112, v0
	v_mov_b32_e32 v113, v0
	v_mov_b32_e32 v114, v0
	v_mov_b32_e32 v115, v0
	v_mov_b32_e32 v116, v0
	v_mov_b32_e32 v117, v0
	v_mov_b32_e32 v118, v0
	v_mov_b32_e32 v119, v0
	v_mov_b32_e32 v72, v0
	v_mov_b32_e32 v73, v0
	v_mov_b32_e32 v74, v0
	v_mov_b32_e32 v75, v0
	v_mov_b32_e32 v76, v0
	v_mov_b32_e32 v77, v0
	v_mov_b32_e32 v78, v0
	v_mov_b32_e32 v79, v0
	v_mov_b32_e32 v88, v0
	v_mov_b32_e32 v89, v0
	v_mov_b32_e32 v90, v0
	v_mov_b32_e32 v91, v0
	v_mov_b32_e32 v92, v0
	v_mov_b32_e32 v93, v0
	v_mov_b32_e32 v94, v0
	v_mov_b32_e32 v95, v0
	v_mov_b32_e32 v104, v0
	v_mov_b32_e32 v105, v0
	v_mov_b32_e32 v106, v0
	v_mov_b32_e32 v107, v0
	v_mov_b32_e32 v108, v0
	v_mov_b32_e32 v109, v0
	v_mov_b32_e32 v110, v0
	v_mov_b32_e32 v111, v0
	v_mov_b32_e32 v120, v0
	v_mov_b32_e32 v121, v0
	v_mov_b32_e32 v122, v0
	v_mov_b32_e32 v123, v0
	v_mov_b32_e32 v124, v0
	v_mov_b32_e32 v125, v0
	v_mov_b32_e32 v126, v0
	v_mov_b32_e32 v127, v0
	s_branch .LBB0_564

; #define PG8_STAGE(bufoff, soff, voff) do { _Pragma("unroll") for (int _i = 0; _i < 2; ++_i) \
;         __builtin_amdgcn_raw_ptr_buffer_load_lds(rs_##voff, (PG8_LAS unsigned*)(lds + (bufoff) + ldsw + _i * 8192), 16, (int)(voff)[_i], (int)(soff), 0, 0); } while (0)
; #define PG8_LDA(dst, b, h) do { _Pragma("unroll") for (int m = 0; m < 4; ++m) _Pragma("unroll") for (int k = 0; k < 2; ++k) dst[m][k] = *(const PG8_LAS bf16x8*)(lds + PG8_SA(b, h) + aoff + m * 2048 + k * 1024); } while (0)
; #define PG8_LDB(dst, b, h) do { _Pragma("unroll") for (int n = 0; n < 2; ++n) _Pragma("unroll") for (int k = 0; k < 2; ++k) dst[n][k] = *(const PG8_LAS bf16x8*)(lds + PG8_SB(b, h) + boff + n * 2048 + k * 1024); } while (0)
; #define PG8_MMA(ai, bj, At, Bt) do { __builtin_amdgcn_s_setprio(1); _Pragma("unroll") for (int m = 0; m < 4; ++m) _Pragma("unroll") for (int n = 0; n < 2; ++n) _Pragma("unroll") for (int k = 0; k < 2; ++k) \
;         acc[ai][bj][m][n] = __builtin_amdgcn_mfma_f32_16x16x32_bf16(Bt[n][k], At[m][k], acc[ai][bj][m][n], 0, 0, 0); __builtin_amdgcn_s_setprio(0); } while (0)
; #define PG8_WAIT_V(n) asm volatile("s_waitcnt vmcnt(" #n ")" ::: "memory")
; #define PG8_WAIT_L(n) asm volatile("s_waitcnt lgkmcnt(" #n ")" ::: "memory")
; #define PG8_BAR __builtin_amdgcn_s_barrier()
; #define PG8_SCHED __builtin_amdgcn_sched_barrier(0)
; template <class Epi, class Sched, bool ALIGN_EPI = false, bool SP2 = false>
; __device__ __forceinline__ void gemm_phase(PG8_LAS unsigned char* lds, const Gemm g, const Sched& S, const Epi& E, const int wid  ) {
;     ...
;             PG8_LDB(B0, 0, 0); PG8_LDB(B1, 0, 1); PG8_SCHED; PG8_LDA(At, 0, 0); PG8_STAGE(PG8_SA(1, 1), a1 + hstep, voffA);
;             PG8_WAIT_V(8); PG8_WAIT_L(0); PG8_BAR; PG8_MMA(0, 0, At, B0); PG8_MMA(0, 1, At, B1); PG8_BAR; PG8_SCHED;
;             PG8_LDA(At, 0, 1); PG8_STAGE(PG8_SB(0, 0), b2, voffB); PG8_STAGE(PG8_SB(0, 1), b2 + hstep, voffB); PG8_STAGE(PG8_SA(0, 0), a2, voffA);
;             PG8_WAIT_V(8); PG8_WAIT_L(0); PG8_BAR; PG8_MMA(1, 0, At, B0); PG8_MMA(1, 1, At, B1); PG8_BAR; PG8_SCHED;
.LBB0_564:
	ds_read_b128 v[132:135], v140
	ds_read_b128 v[146:149], v140 offset:1024
	ds_read_b128 v[150:153], v140 offset:2048
	ds_read_b128 v[154:157], v140 offset:3072
	ds_read_b128 v[158:161], v141
	ds_read_b128 v[162:165], v141 offset:1024
	ds_read_b128 v[166:169], v141 offset:2048
	ds_read_b128 v[170:173], v141 offset:3072
	s_add_i32 s14, s54, 0xfff80080
	s_cmp_eq_u32 s58, 28
	s_cselect_b32 s61, s0, s14
	s_cselect_b32 s60, s1, s55
	s_or_b32 s59, s61, 0x80
	s_mov_b32 m0, s43
	ds_read_b128 v[174:177], v142
	ds_read_b128 v[178:181], v142 offset:1024
	ds_read_b128 v[182:185], v142 offset:2048
	ds_read_b128 v[186:189], v142 offset:3072
	ds_read_b128 v[190:193], v142 offset:4096
	ds_read_b128 v[194:197], v142 offset:5120
	ds_read_b128 v[198:201], v142 offset:6144
	ds_read_b128 v[202:205], v142 offset:7168
	buffer_load_dwordx4 v136, s[8:11], s54 offen lds
	s_mov_b32 m0, s44
	s_nop 0
	buffer_load_dwordx4 v138, s[8:11], s54 offen lds
	s_waitcnt vmcnt(8)
	s_waitcnt lgkmcnt(0)
	s_barrier
	s_setprio 1
	s_waitcnt lgkmcnt(7)
	v_mfma_f32_16x16x32_bf16 v[124:127], v[132:135], v[174:177], v[124:127]
	v_mfma_f32_16x16x32_bf16 v[120:123], v[150:153], v[174:177], v[120:123]
	s_waitcnt lgkmcnt(5)
	v_mfma_f32_16x16x32_bf16 v[108:111], v[132:135], v[182:185], v[108:111]
	v_mfma_f32_16x16x32_bf16 v[104:107], v[150:153], v[182:185], v[104:107]
	s_waitcnt lgkmcnt(3)
	v_mfma_f32_16x16x32_bf16 v[92:95], v[132:135], v[190:193], v[92:95]
	v_mfma_f32_16x16x32_bf16 v[88:91], v[150:153], v[190:193], v[88:91]
	s_waitcnt lgkmcnt(1)
	v_mfma_f32_16x16x32_bf16 v[76:79], v[132:135], v[198:201], v[76:79]
	v_mfma_f32_16x16x32_bf16 v[72:75], v[150:153], v[198:201], v[72:75]
	v_mfma_f32_16x16x32_bf16 v[124:127], v[146:149], v[178:181], v[124:127]
	v_mfma_f32_16x16x32_bf16 v[120:123], v[154:157], v[178:181], v[120:123]
	v_mfma_f32_16x16x32_bf16 v[108:111], v[146:149], v[186:189], v[108:111]
	v_mfma_f32_16x16x32_bf16 v[104:107], v[154:157], v[186:189], v[104:107]
	v_mfma_f32_16x16x32_bf16 v[92:95], v[146:149], v[194:197], v[92:95]
	v_mfma_f32_16x16x32_bf16 v[88:91], v[154:157], v[194:197], v[88:91]
	s_waitcnt lgkmcnt(0)
	v_mfma_f32_16x16x32_bf16 v[76:79], v[146:149], v[202:205], v[76:79]
	v_mfma_f32_16x16x32_bf16 v[72:75], v[154:157], v[202:205], v[72:75]
	s_setprio 0
	s_setprio 1
	v_mfma_f32_16x16x32_bf16 v[116:119], v[158:161], v[174:177], v[116:119]
	v_mfma_f32_16x16x32_bf16 v[112:115], v[166:169], v[174:177], v[112:115]
	v_mfma_f32_16x16x32_bf16 v[100:103], v[158:161], v[182:185], v[100:103]
	v_mfma_f32_16x16x32_bf16 v[96:99], v[166:169], v[182:185], v[96:99]
	v_mfma_f32_16x16x32_bf16 v[84:87], v[158:161], v[190:193], v[84:87]
	v_mfma_f32_16x16x32_bf16 v[80:83], v[166:169], v[190:193], v[80:83]
	v_mfma_f32_16x16x32_bf16 v[68:71], v[158:161], v[198:201], v[68:71]
	v_mfma_f32_16x16x32_bf16 v[64:67], v[166:169], v[198:201], v[64:67]
	v_mfma_f32_16x16x32_bf16 v[116:119], v[162:165], v[178:181], v[116:119]
	v_mfma_f32_16x16x32_bf16 v[112:115], v[170:173], v[178:181], v[112:115]
	v_mfma_f32_16x16x32_bf16 v[100:103], v[162:165], v[186:189], v[100:103]
	v_mfma_f32_16x16x32_bf16 v[96:99], v[170:173], v[186:189], v[96:99]
	v_mfma_f32_16x16x32_bf16 v[84:87], v[162:165], v[194:197], v[84:87]
	v_mfma_f32_16x16x32_bf16 v[80:83], v[170:173], v[194:197], v[80:83]
	v_mfma_f32_16x16x32_bf16 v[68:71], v[162:165], v[202:205], v[68:71]
	v_mfma_f32_16x16x32_bf16 v[64:67], v[170:173], v[202:205], v[64:67]
	s_setprio 0
	s_barrier
	s_mov_b32 m0, s26
	s_mov_b32 s14, s10
	s_mov_b32 s15, s11
	ds_read_b128 v[174:177], v142 offset:16384
	ds_read_b128 v[178:181], v142 offset:17408
	ds_read_b128 v[182:185], v142 offset:18432
	ds_read_b128 v[186:189], v142 offset:19456
	ds_read_b128 v[190:193], v142 offset:20480
	ds_read_b128 v[194:197], v142 offset:21504
	ds_read_b128 v[198:201], v142 offset:22528
	ds_read_b128 v[202:205], v142 offset:23552
	buffer_load_dwordx4 v137, s[12:15], s60 offen lds
	s_mov_b32 m0, s27
	s_add_i32 s62, s60, 0x80000
	buffer_load_dwordx4 v139, s[12:15], s60 offen lds
	s_mov_b32 m0, s28
	s_nop 0
	buffer_load_dwordx4 v137, s[12:15], s62 offen lds
	s_mov_b32 m0, s29
	s_nop 0
	buffer_load_dwordx4 v139, s[12:15], s62 offen lds
	s_mov_b32 m0, s3
	s_nop 0
	buffer_load_dwordx4 v136, s[8:11], s61 offen lds
	s_mov_b32 m0, s30
	s_nop 0
	buffer_load_dwordx4 v138, s[8:11], s61 offen lds
	s_waitcnt vmcnt(8)
	s_waitcnt lgkmcnt(0)
	s_barrier
	s_setprio 1
	s_waitcnt lgkmcnt(7)
	v_mfma_f32_16x16x32_bf16 v[60:63], v[132:135], v[174:177], v[60:63]
	v_mfma_f32_16x16x32_bf16 v[56:59], v[150:153], v[174:177], v[56:59]
	s_waitcnt lgkmcnt(5)
	v_mfma_f32_16x16x32_bf16 v[44:47], v[132:135], v[182:185], v[44:47]
	v_mfma_f32_16x16x32_bf16 v[40:43], v[150:153], v[182:185], v[40:43]
	s_waitcnt lgkmcnt(3)
	v_mfma_f32_16x16x32_bf16 v[28:31], v[132:135], v[190:193], v[28:31]
	v_mfma_f32_16x16x32_bf16 v[24:27], v[150:153], v[190:193], v[24:27]
	s_waitcnt lgkmcnt(1)
	v_mfma_f32_16x16x32_bf16 v[12:15], v[132:135], v[198:201], v[12:15]
	v_mfma_f32_16x16x32_bf16 v[8:11], v[150:153], v[198:201], v[8:11]
	v_mfma_f32_16x16x32_bf16 v[60:63], v[146:149], v[178:181], v[60:63]
	v_mfma_f32_16x16x32_bf16 v[56:59], v[154:157], v[178:181], v[56:59]
	v_mfma_f32_16x16x32_bf16 v[44:47], v[146:149], v[186:189], v[44:47]
	v_mfma_f32_16x16x32_bf16 v[40:43], v[154:157], v[186:189], v[40:43]
	v_mfma_f32_16x16x32_bf16 v[28:31], v[146:149], v[194:197], v[28:31]
	v_mfma_f32_16x16x32_bf16 v[24:27], v[154:157], v[194:197], v[24:27]
	s_waitcnt lgkmcnt(0)
	v_mfma_f32_16x16x32_bf16 v[12:15], v[146:149], v[202:205], v[12:15]
	v_mfma_f32_16x16x32_bf16 v[8:11], v[154:157], v[202:205], v[8:11]
	s_setprio 0
	s_setprio 1
	v_mfma_f32_16x16x32_bf16 v[52:55], v[158:161], v[174:177], v[52:55]
	v_mfma_f32_16x16x32_bf16 v[48:51], v[166:169], v[174:177], v[48:51]
	v_mfma_f32_16x16x32_bf16 v[36:39], v[158:161], v[182:185], v[36:39]
	v_mfma_f32_16x16x32_bf16 v[32:35], v[166:169], v[182:185], v[32:35]
	v_mfma_f32_16x16x32_bf16 v[20:23], v[158:161], v[190:193], v[20:23]
	v_mfma_f32_16x16x32_bf16 v[16:19], v[166:169], v[190:193], v[16:19]
	v_mfma_f32_16x16x32_bf16 v[4:7], v[158:161], v[198:201], v[4:7]
	v_mfma_f32_16x16x32_bf16 v[0:3], v[166:169], v[198:201], v[0:3]
	v_mfma_f32_16x16x32_bf16 v[52:55], v[162:165], v[178:181], v[52:55]
	v_mfma_f32_16x16x32_bf16 v[48:51], v[170:173], v[178:181], v[48:51]
	v_mfma_f32_16x16x32_bf16 v[36:39], v[162:165], v[186:189], v[36:39]
	v_mfma_f32_16x16x32_bf16 v[32:35], v[170:173], v[186:189], v[32:35]
	v_mfma_f32_16x16x32_bf16 v[20:23], v[162:165], v[194:197], v[20:23]
	v_mfma_f32_16x16x32_bf16 v[16:19], v[170:173], v[194:197], v[16:19]
	v_mfma_f32_16x16x32_bf16 v[4:7], v[162:165], v[202:205], v[4:7]
	v_mfma_f32_16x16x32_bf16 v[0:3], v[170:173], v[202:205], v[0:3]
	s_setprio 0
	s_barrier
; #define PG8_STAGE(bufoff, soff, voff) do { _Pragma("unroll") for (int _i = 0; _i < 2; ++_i) \
;         __builtin_amdgcn_raw_ptr_buffer_load_lds(rs_##voff, (PG8_LAS unsigned*)(lds + (bufoff) + ldsw + _i * 8192), 16, (int)(voff)[_i], (int)(soff), 0, 0); } while (0)
; #define PG8_LDA(dst, b, h) do { _Pragma("unroll") for (int m = 0; m < 4; ++m) _Pragma("unroll") for (int k = 0; k < 2; ++k) dst[m][k] = *(const PG8_LAS bf16x8*)(lds + PG8_SA(b, h) + aoff + m * 2048 + k * 1024); } while (0)
; #define PG8_LDB(dst, b, h) do { _Pragma("unroll") for (int n = 0; n < 2; ++n) _Pragma("unroll") for (int k = 0; k < 2; ++k) dst[n][k] = *(const PG8_LAS bf16x8*)(lds + PG8_SB(b, h) + boff + n * 2048 + k * 1024); } while (0)
; #define PG8_MMA(ai, bj, At, Bt) do { __builtin_amdgcn_s_setprio(1); _Pragma("unroll") for (int m = 0; m < 4; ++m) _Pragma("unroll") for (int n = 0; n < 2; ++n) _Pragma("unroll") for (int k = 0; k < 2; ++k) \
;         acc[ai][bj][m][n] = __builtin_amdgcn_mfma_f32_16x16x32_bf16(Bt[n][k], At[m][k], acc[ai][bj][m][n], 0, 0, 0); __builtin_amdgcn_s_setprio(0); } while (0)
; #define PG8_WAIT_V(n) asm volatile("s_waitcnt vmcnt(" #n ")" ::: "memory")
; #define PG8_WAIT_L(n) asm volatile("s_waitcnt lgkmcnt(" #n ")" ::: "memory")
; #define PG8_BAR __builtin_amdgcn_s_barrier()
; #define PG8_SCHED __builtin_amdgcn_sched_barrier(0)
; template <class Epi, class Sched, bool ALIGN_EPI = false, bool SP2 = false>
; __device__ __forceinline__ void gemm_phase(PG8_LAS unsigned char* lds, const Gemm g, const Sched& S, const Epi& E, const int wid  ) {
;     ...
;             PG8_LDB(B0, 1, 0); PG8_LDB(B1, 1, 1); PG8_SCHED; PG8_LDA(At, 1, 0); PG8_STAGE(PG8_SA(0, 1), a2 + hstep, voffA);
;             PG8_WAIT_V(8); PG8_WAIT_L(0); PG8_BAR; PG8_MMA(0, 0, At, B0); PG8_MMA(0, 1, At, B1); PG8_BAR; PG8_SCHED;
;             PG8_LDA(At, 1, 1); PG8_STAGE(PG8_SB(1, 0), b3, voffB); PG8_STAGE(PG8_SB(1, 1), b3 + hstep, voffB); PG8_STAGE(PG8_SA(1, 0), a3, voffA);
;             PG8_WAIT_V(8); PG8_WAIT_L(0); PG8_BAR; PG8_MMA(1, 0, At, B0); PG8_MMA(1, 1, At, B1); PG8_BAR; PG8_SCHED;
	ds_read_b128 v[132:135], v143
	ds_read_b128 v[146:149], v143 offset:1024
	ds_read_b128 v[150:153], v143 offset:2048
	ds_read_b128 v[154:157], v143 offset:3072
	ds_read_b128 v[158:161], v144
	ds_read_b128 v[162:165], v144 offset:1024
	ds_read_b128 v[166:169], v144 offset:2048
	ds_read_b128 v[170:173], v144 offset:3072
	s_add_i32 s61, s61, 0x80000
	s_mov_b32 m0, s31
	ds_read_b128 v[174:177], v142 offset:32768
	ds_read_b128 v[178:181], v142 offset:33792
	ds_read_b128 v[182:185], v142 offset:34816
	ds_read_b128 v[186:189], v142 offset:35840
	ds_read_b128 v[190:193], v142 offset:36864
	ds_read_b128 v[194:197], v142 offset:37888
	ds_read_b128 v[198:201], v142 offset:38912
	ds_read_b128 v[202:205], v142 offset:39936
	buffer_load_dwordx4 v136, s[8:11], s61 offen lds
	s_mov_b32 m0, s33
	s_nop 0
	buffer_load_dwordx4 v138, s[8:11], s61 offen lds
	s_waitcnt vmcnt(8)
	s_waitcnt lgkmcnt(0)
	s_barrier
	s_setprio 1
	s_waitcnt lgkmcnt(7)
	v_mfma_f32_16x16x32_bf16 v[124:127], v[132:135], v[174:177], v[124:127]
	v_mfma_f32_16x16x32_bf16 v[120:123], v[150:153], v[174:177], v[120:123]
	s_waitcnt lgkmcnt(5)
	v_mfma_f32_16x16x32_bf16 v[108:111], v[132:135], v[182:185], v[108:111]
	v_mfma_f32_16x16x32_bf16 v[104:107], v[150:153], v[182:185], v[104:107]
	s_waitcnt lgkmcnt(3)
	v_mfma_f32_16x16x32_bf16 v[92:95], v[132:135], v[190:193], v[92:95]
	v_mfma_f32_16x16x32_bf16 v[88:91], v[150:153], v[190:193], v[88:91]
	s_waitcnt lgkmcnt(1)
	v_mfma_f32_16x16x32_bf16 v[76:79], v[132:135], v[198:201], v[76:79]
	v_mfma_f32_16x16x32_bf16 v[72:75], v[150:153], v[198:201], v[72:75]
	v_mfma_f32_16x16x32_bf16 v[124:127], v[146:149], v[178:181], v[124:127]
	v_mfma_f32_16x16x32_bf16 v[120:123], v[154:157], v[178:181], v[120:123]
	v_mfma_f32_16x16x32_bf16 v[108:111], v[146:149], v[186:189], v[108:111]
	v_mfma_f32_16x16x32_bf16 v[104:107], v[154:157], v[186:189], v[104:107]
	v_mfma_f32_16x16x32_bf16 v[92:95], v[146:149], v[194:197], v[92:95]
	v_mfma_f32_16x16x32_bf16 v[88:91], v[154:157], v[194:197], v[88:91]
	s_waitcnt lgkmcnt(0)
	v_mfma_f32_16x16x32_bf16 v[76:79], v[146:149], v[202:205], v[76:79]
	v_mfma_f32_16x16x32_bf16 v[72:75], v[154:157], v[202:205], v[72:75]
	s_setprio 0
	s_setprio 1
	v_mfma_f32_16x16x32_bf16 v[116:119], v[158:161], v[174:177], v[116:119]
	v_mfma_f32_16x16x32_bf16 v[112:115], v[166:169], v[174:177], v[112:115]
	v_mfma_f32_16x16x32_bf16 v[100:103], v[158:161], v[182:185], v[100:103]
	v_mfma_f32_16x16x32_bf16 v[96:99], v[166:169], v[182:185], v[96:99]
	v_mfma_f32_16x16x32_bf16 v[84:87], v[158:161], v[190:193], v[84:87]
	v_mfma_f32_16x16x32_bf16 v[80:83], v[166:169], v[190:193], v[80:83]
	v_mfma_f32_16x16x32_bf16 v[68:71], v[158:161], v[198:201], v[68:71]
	v_mfma_f32_16x16x32_bf16 v[64:67], v[166:169], v[198:201], v[64:67]
	v_mfma_f32_16x16x32_bf16 v[116:119], v[162:165], v[178:181], v[116:119]
	v_mfma_f32_16x16x32_bf16 v[112:115], v[170:173], v[178:181], v[112:115]
	v_mfma_f32_16x16x32_bf16 v[100:103], v[162:165], v[186:189], v[100:103]
	v_mfma_f32_16x16x32_bf16 v[96:99], v[170:173], v[186:189], v[96:99]
	v_mfma_f32_16x16x32_bf16 v[84:87], v[162:165], v[194:197], v[84:87]
	v_mfma_f32_16x16x32_bf16 v[80:83], v[170:173], v[194:197], v[80:83]
	v_mfma_f32_16x16x32_bf16 v[68:71], v[162:165], v[202:205], v[68:71]
	v_mfma_f32_16x16x32_bf16 v[64:67], v[170:173], v[202:205], v[64:67]
	s_setprio 0
	s_barrier
	s_mov_b32 m0, s34
	s_or_b32 s61, s60, 0x80
	ds_read_b128 v[174:177], v142 offset:49152
	ds_read_b128 v[178:181], v142 offset:50176
	ds_read_b128 v[182:185], v142 offset:51200
	ds_read_b128 v[186:189], v142 offset:52224
	ds_read_b128 v[190:193], v142 offset:53248
	ds_read_b128 v[194:197], v142 offset:54272
	ds_read_b128 v[198:201], v142 offset:55296
	ds_read_b128 v[202:205], v142 offset:56320
	buffer_load_dwordx4 v137, s[12:15], s61 offen lds
	s_mov_b32 m0, s35
	s_add_i32 s60, s60, 0x80080
	buffer_load_dwordx4 v139, s[12:15], s61 offen lds
	s_mov_b32 m0, s38
	s_nop 0
	buffer_load_dwordx4 v137, s[12:15], s60 offen lds
	s_mov_b32 m0, s39
	s_nop 0
	buffer_load_dwordx4 v139, s[12:15], s60 offen lds
	s_mov_b32 m0, s36
	s_nop 0
	buffer_load_dwordx4 v136, s[8:11], s59 offen lds
	s_mov_b32 m0, s37
	s_nop 0
	buffer_load_dwordx4 v138, s[8:11], s59 offen lds
	s_waitcnt vmcnt(8)
	s_waitcnt lgkmcnt(0)
	s_barrier
	s_setprio 1
	s_waitcnt lgkmcnt(7)
	v_mfma_f32_16x16x32_bf16 v[60:63], v[132:135], v[174:177], v[60:63]
	v_mfma_f32_16x16x32_bf16 v[56:59], v[150:153], v[174:177], v[56:59]
	s_waitcnt lgkmcnt(5)
	v_mfma_f32_16x16x32_bf16 v[44:47], v[132:135], v[182:185], v[44:47]
	v_mfma_f32_16x16x32_bf16 v[40:43], v[150:153], v[182:185], v[40:43]
	s_waitcnt lgkmcnt(3)
	v_mfma_f32_16x16x32_bf16 v[28:31], v[132:135], v[190:193], v[28:31]
	v_mfma_f32_16x16x32_bf16 v[24:27], v[150:153], v[190:193], v[24:27]
	s_waitcnt lgkmcnt(1)
	v_mfma_f32_16x16x32_bf16 v[12:15], v[132:135], v[198:201], v[12:15]
	v_mfma_f32_16x16x32_bf16 v[8:11], v[150:153], v[198:201], v[8:11]
	v_mfma_f32_16x16x32_bf16 v[60:63], v[146:149], v[178:181], v[60:63]
	v_mfma_f32_16x16x32_bf16 v[56:59], v[154:157], v[178:181], v[56:59]
	v_mfma_f32_16x16x32_bf16 v[44:47], v[146:149], v[186:189], v[44:47]
	v_mfma_f32_16x16x32_bf16 v[40:43], v[154:157], v[186:189], v[40:43]
	v_mfma_f32_16x16x32_bf16 v[28:31], v[146:149], v[194:197], v[28:31]
	v_mfma_f32_16x16x32_bf16 v[24:27], v[154:157], v[194:197], v[24:27]
	s_waitcnt lgkmcnt(0)
	v_mfma_f32_16x16x32_bf16 v[12:15], v[146:149], v[202:205], v[12:15]
	v_mfma_f32_16x16x32_bf16 v[8:11], v[154:157], v[202:205], v[8:11]
	s_setprio 0
	s_setprio 1
	v_mfma_f32_16x16x32_bf16 v[52:55], v[158:161], v[174:177], v[52:55]
	v_mfma_f32_16x16x32_bf16 v[48:51], v[166:169], v[174:177], v[48:51]
	v_mfma_f32_16x16x32_bf16 v[36:39], v[158:161], v[182:185], v[36:39]
	v_mfma_f32_16x16x32_bf16 v[32:35], v[166:169], v[182:185], v[32:35]
	v_mfma_f32_16x16x32_bf16 v[20:23], v[158:161], v[190:193], v[20:23]
	v_mfma_f32_16x16x32_bf16 v[16:19], v[166:169], v[190:193], v[16:19]
	v_mfma_f32_16x16x32_bf16 v[4:7], v[158:161], v[198:201], v[4:7]
	v_mfma_f32_16x16x32_bf16 v[0:3], v[166:169], v[198:201], v[0:3]
	v_mfma_f32_16x16x32_bf16 v[52:55], v[162:165], v[178:181], v[52:55]
	v_mfma_f32_16x16x32_bf16 v[48:51], v[170:173], v[178:181], v[48:51]
	v_mfma_f32_16x16x32_bf16 v[36:39], v[162:165], v[186:189], v[36:39]
	v_mfma_f32_16x16x32_bf16 v[32:35], v[170:173], v[186:189], v[32:35]
	v_mfma_f32_16x16x32_bf16 v[20:23], v[162:165], v[194:197], v[20:23]
	v_mfma_f32_16x16x32_bf16 v[16:19], v[170:173], v[194:197], v[16:19]
	v_mfma_f32_16x16x32_bf16 v[4:7], v[162:165], v[202:205], v[4:7]
	v_mfma_f32_16x16x32_bf16 v[0:3], v[170:173], v[202:205], v[0:3]
	s_setprio 0
	s_add_i32 s58, s58, 2
	s_addk_i32 s54, 0x100
	s_addk_i32 s55, 0x100
	s_cmp_gt_u32 s58, 29
	s_cbranch_scc0 .Lrot_564
	s_barrier
	s_and_b64 vcc, exec, s[24:25]
	s_cbranch_vccz .LBB0_567
	s_barrier

; template <class Epi, class Sched, bool ALIGN_EPI = false, bool SP2 = false>
; __device__ __forceinline__ void gemm_phase(PG8_LAS unsigned char* lds, const Gemm g, const Sched& S, const Epi& E, const int wid  ) {
;     ...
;         const bool has_next = S.next(ui + 1, nxt); nxt.same = (has_next && nxt.pm == cur.pm) ? 1 : 0;
;         const unsigned nA = has_next ? (unsigned)g.asel(nxt.pn) * (unsigned)g.a_stride + (unsigned)nxt.pm * tstep : cA, nB = has_next ? (unsigned)nxt.pn * tstep : cB;
;         for (int t = 0; t < nt; t += 2) {
;             const bool last = (t == nt - 2);
;             const unsigned a1 = cA + (unsigned)(t + 1) * kstep;
;             const unsigned a2 = last ? nA : cA + (unsigned)(t + 2) * kstep, b2 = last ? nB : cB + (unsigned)(t + 2) * kstep;
;             const unsigned a3 = a2 + kstep, b3 = b2 + kstep;
;             if (last && has_next) S.a_ready(nxt);
;     ...
; #pragma unroll
;         for (int a = 0; a < 2; ++a)
; #pragma unroll
;             for (int b = 0; b < 2; ++b)
; #pragma unroll
;                 for (int m = 0; m < 4; ++m)
; #pragma unroll
;                     for (int n = 0; n < 2; ++n) acc[a][b][m][n] = (f32x4){0.f, 0.f, 0.f, 0.f};
;         cur = nxt; cA = nA; cB = nB; ++ui;
.LBB0_657:
	s_lshl_b32 s91, s90, 20
	s_and_b64 s[6:7], s[4:5], exec
	s_cselect_b32 s6, s91, s8
	s_lshl_b32 s92, s89, 20
	s_and_b64 s[18:19], s[4:5], exec
	v_mov_b32_e32 v56, 0
	s_cselect_b32 s7, s92, s9
	s_add_i32 s8, s8, 0x80080
	s_addk_i32 s9, 0x100
	s_mov_b32 s46, -2
	v_mov_b32_e32 v57, v56
	v_mov_b32_e32 v58, v56
	v_mov_b32_e32 v59, v56
	v_mov_b32_e32 v60, v56
	v_mov_b32_e32 v61, v56
	v_mov_b32_e32 v62, v56
	v_mov_b32_e32 v63, v56
	v_mov_b32_e32 v64, v56
	v_mov_b32_e32 v65, v56
	v_mov_b32_e32 v66, v56
	v_mov_b32_e32 v67, v56
	v_mov_b32_e32 v68, v56
	v_mov_b32_e32 v69, v56
	v_mov_b32_e32 v70, v56
	v_mov_b32_e32 v71, v56
	v_mov_b32_e32 v72, v56
	v_mov_b32_e32 v73, v56
	v_mov_b32_e32 v74, v56
	v_mov_b32_e32 v75, v56
	v_mov_b32_e32 v80, v56
	v_mov_b32_e32 v81, v56
	v_mov_b32_e32 v82, v56
	v_mov_b32_e32 v83, v56
	v_mov_b32_e32 v0, v56
	v_mov_b32_e32 v1, v56
	s_waitcnt lgkmcnt(7)
	v_mov_b32_e32 v2, v56
	v_mov_b32_e32 v3, v56
	s_waitcnt lgkmcnt(6)
	v_mov_b32_e32 v4, v56
	v_mov_b32_e32 v5, v56
	s_waitcnt lgkmcnt(5)
	v_mov_b32_e32 v6, v56
	v_mov_b32_e32 v7, v56
	v_mov_b32_e32 v48, v56
	v_mov_b32_e32 v49, v56
	v_mov_b32_e32 v50, v56
	v_mov_b32_e32 v51, v56
	v_mov_b32_e32 v92, v56
	v_mov_b32_e32 v93, v56
	v_mov_b32_e32 v94, v56
	v_mov_b32_e32 v95, v56
	v_mov_b32_e32 v76, v56
	v_mov_b32_e32 v77, v56
	v_mov_b32_e32 v78, v56
	v_mov_b32_e32 v79, v56
	v_mov_b32_e32 v84, v56
	v_mov_b32_e32 v85, v56
	v_mov_b32_e32 v86, v56
	v_mov_b32_e32 v87, v56
	v_mov_b32_e32 v88, v56
	v_mov_b32_e32 v89, v56
	v_mov_b32_e32 v90, v56
	v_mov_b32_e32 v91, v56
	v_mov_b32_e32 v96, v56
	v_mov_b32_e32 v97, v56
	v_mov_b32_e32 v98, v56
	v_mov_b32_e32 v99, v56
	v_mov_b32_e32 v100, v56
	v_mov_b32_e32 v101, v56
	v_mov_b32_e32 v102, v56
	v_mov_b32_e32 v103, v56
	v_mov_b32_e32 v104, v56
	v_mov_b32_e32 v105, v56
	v_mov_b32_e32 v106, v56
	v_mov_b32_e32 v107, v56
	v_mov_b32_e32 v108, v56
	v_mov_b32_e32 v109, v56
	v_mov_b32_e32 v110, v56
	v_mov_b32_e32 v111, v56
	v_mov_b32_e32 v112, v56
	v_mov_b32_e32 v113, v56
	v_mov_b32_e32 v114, v56
	v_mov_b32_e32 v115, v56
	v_mov_b32_e32 v116, v56
	v_mov_b32_e32 v117, v56
	v_mov_b32_e32 v118, v56
	v_mov_b32_e32 v119, v56
	v_mov_b32_e32 v124, v56
	v_mov_b32_e32 v125, v56
	v_mov_b32_e32 v126, v56
	v_mov_b32_e32 v127, v56
	v_mov_b32_e32 v128, v56
	v_mov_b32_e32 v129, v56
	v_mov_b32_e32 v130, v56
	v_mov_b32_e32 v131, v56
	v_mov_b32_e32 v136, v56
	v_mov_b32_e32 v137, v56
	v_mov_b32_e32 v138, v56
	v_mov_b32_e32 v139, v56
	s_waitcnt lgkmcnt(4)
	v_mov_b32_e32 v8, v56
	v_mov_b32_e32 v9, v56
	s_waitcnt lgkmcnt(3)
	v_mov_b32_e32 v10, v56
	v_mov_b32_e32 v11, v56
	s_waitcnt lgkmcnt(2)
	v_mov_b32_e32 v12, v56
	v_mov_b32_e32 v13, v56
	s_waitcnt lgkmcnt(1)
	v_mov_b32_e32 v14, v56
	v_mov_b32_e32 v15, v56
	v_mov_b32_e32 v120, v56
	v_mov_b32_e32 v121, v56
	v_mov_b32_e32 v122, v56
	v_mov_b32_e32 v123, v56
	v_mov_b32_e32 v156, v56
	v_mov_b32_e32 v157, v56
	v_mov_b32_e32 v158, v56
	v_mov_b32_e32 v159, v56
	v_mov_b32_e32 v132, v56
	v_mov_b32_e32 v133, v56
	v_mov_b32_e32 v134, v56
	v_mov_b32_e32 v135, v56
	v_mov_b32_e32 v140, v56
	v_mov_b32_e32 v141, v56
	v_mov_b32_e32 v142, v56
	v_mov_b32_e32 v143, v56
	v_mov_b32_e32 v144, v56
	v_mov_b32_e32 v145, v56
	v_mov_b32_e32 v146, v56
	v_mov_b32_e32 v147, v56
	v_mov_b32_e32 v148, v56
	v_mov_b32_e32 v149, v56
	v_mov_b32_e32 v150, v56
	v_mov_b32_e32 v151, v56
	v_mov_b32_e32 v52, v56
	v_mov_b32_e32 v53, v56
	v_mov_b32_e32 v54, v56
	v_mov_b32_e32 v55, v56
	v_mov_b32_e32 v152, v56
	v_mov_b32_e32 v153, v56
	v_mov_b32_e32 v154, v56
	v_mov_b32_e32 v155, v56
	s_branch .LBB0_658

; #define PG8_STAGE(bufoff, soff, voff) do { _Pragma("unroll") for (int _i = 0; _i < 2; ++_i) \
;         __builtin_amdgcn_raw_ptr_buffer_load_lds(rs_##voff, (PG8_LAS unsigned*)(lds + (bufoff) + ldsw + _i * 8192), 16, (int)(voff)[_i], (int)(soff), 0, 0); } while (0)
; #define PG8_LDA(dst, b, h) do { _Pragma("unroll") for (int m = 0; m < 4; ++m) _Pragma("unroll") for (int k = 0; k < 2; ++k) dst[m][k] = *(const PG8_LAS bf16x8*)(lds + PG8_SA(b, h) + aoff + m * 2048 + k * 1024); } while (0)
; #define PG8_LDB(dst, b, h) do { _Pragma("unroll") for (int n = 0; n < 2; ++n) _Pragma("unroll") for (int k = 0; k < 2; ++k) dst[n][k] = *(const PG8_LAS bf16x8*)(lds + PG8_SB(b, h) + boff + n * 2048 + k * 1024); } while (0)
; #define PG8_MMA(ai, bj, At, Bt) do { __builtin_amdgcn_s_setprio(1); _Pragma("unroll") for (int m = 0; m < 4; ++m) _Pragma("unroll") for (int n = 0; n < 2; ++n) _Pragma("unroll") for (int k = 0; k < 2; ++k) \
;         acc[ai][bj][m][n] = __builtin_amdgcn_mfma_f32_16x16x32_bf16(Bt[n][k], At[m][k], acc[ai][bj][m][n], 0, 0, 0); __builtin_amdgcn_s_setprio(0); } while (0)
; #define PG8_WAIT_V(n) asm volatile("s_waitcnt vmcnt(" #n ")" ::: "memory")
; #define PG8_WAIT_L(n) asm volatile("s_waitcnt lgkmcnt(" #n ")" ::: "memory")
; #define PG8_BAR __builtin_amdgcn_s_barrier()
; #define PG8_SCHED __builtin_amdgcn_sched_barrier(0)
; template <class Epi, class Sched, bool ALIGN_EPI = false, bool SP2 = false>
; __device__ __forceinline__ void gemm_phase(PG8_LAS unsigned char* lds, const Gemm g, const Sched& S, const Epi& E, const int wid  ) {
;     ...
;             PG8_LDB(B0, 0, 0); PG8_LDB(B1, 0, 1); PG8_SCHED; PG8_LDA(At, 0, 0); PG8_STAGE(PG8_SA(1, 1), a1 + hstep, voffA);
;             PG8_WAIT_V(8); PG8_WAIT_L(0); PG8_BAR; PG8_MMA(0, 0, At, B0); PG8_MMA(0, 1, At, B1); PG8_BAR; PG8_SCHED;
;             PG8_LDA(At, 0, 1); PG8_STAGE(PG8_SB(0, 0), b2, voffB); PG8_STAGE(PG8_SB(0, 1), b2 + hstep, voffB); PG8_STAGE(PG8_SA(0, 0), a2, voffA);
;             PG8_WAIT_V(8); PG8_WAIT_L(0); PG8_BAR; PG8_MMA(1, 0, At, B0); PG8_MMA(1, 1, At, B1); PG8_BAR; PG8_SCHED;
.LBB0_658:
	s_waitcnt lgkmcnt(0)
	ds_read_b128 v[16:19], v188
	ds_read_b128 v[20:23], v188 offset:1024
	ds_read_b128 v[24:27], v188 offset:2048
	ds_read_b128 v[28:31], v188 offset:3072
	ds_read_b128 v[32:35], v189
	ds_read_b128 v[36:39], v189 offset:1024
	ds_read_b128 v[40:43], v189 offset:2048
	ds_read_b128 v[44:47], v189 offset:3072
	s_add_i32 s18, s8, 0xfff80080
	s_cmp_eq_u32 s46, 28
	s_cselect_b32 s94, s6, s18
	s_cselect_b32 s93, s7, s9
	s_or_b32 s47, s94, 0x80
	s_mov_b32 m0, s75
	ds_read_b128 v[160:163], v190
	ds_read_b128 v[170:173], v190 offset:1024
	ds_read_b128 v[174:177], v190 offset:2048
	ds_read_b128 v[178:181], v190 offset:3072
	ds_read_b128 v[194:197], v190 offset:4096
	ds_read_b128 v[198:201], v190 offset:5120
	ds_read_b128 v[202:205], v190 offset:6144
	ds_read_b128 v[206:209], v190 offset:7168
	buffer_load_dwordx4 v182, s[12:15], s8 offen lds
	s_mov_b32 m0, s77
	s_nop 0
	buffer_load_dwordx4 v184, s[12:15], s8 offen lds
	s_waitcnt vmcnt(8)
	s_waitcnt lgkmcnt(0)
	s_barrier
	s_setprio 1
	s_waitcnt lgkmcnt(7)
	v_mfma_f32_16x16x32_bf16 v[152:155], v[16:19], v[160:163], v[152:155]
	v_mfma_f32_16x16x32_bf16 v[52:55], v[24:27], v[160:163], v[52:55]
	s_waitcnt lgkmcnt(5)
	v_mfma_f32_16x16x32_bf16 v[148:151], v[16:19], v[174:177], v[148:151]
	v_mfma_f32_16x16x32_bf16 v[144:147], v[24:27], v[174:177], v[144:147]
	s_waitcnt lgkmcnt(3)
	v_mfma_f32_16x16x32_bf16 v[140:143], v[16:19], v[194:197], v[140:143]
	v_mfma_f32_16x16x32_bf16 v[132:135], v[24:27], v[194:197], v[132:135]
	s_waitcnt lgkmcnt(1)
	v_mfma_f32_16x16x32_bf16 v[156:159], v[16:19], v[202:205], v[156:159]
	v_mfma_f32_16x16x32_bf16 v[120:123], v[24:27], v[202:205], v[120:123]
	v_mfma_f32_16x16x32_bf16 v[152:155], v[20:23], v[170:173], v[152:155]
	v_mfma_f32_16x16x32_bf16 v[52:55], v[28:31], v[170:173], v[52:55]
	v_mfma_f32_16x16x32_bf16 v[148:151], v[20:23], v[178:181], v[148:151]
	v_mfma_f32_16x16x32_bf16 v[144:147], v[28:31], v[178:181], v[144:147]
	v_mfma_f32_16x16x32_bf16 v[140:143], v[20:23], v[198:201], v[140:143]
	v_mfma_f32_16x16x32_bf16 v[132:135], v[28:31], v[198:201], v[132:135]
	s_waitcnt lgkmcnt(0)
	v_mfma_f32_16x16x32_bf16 v[156:159], v[20:23], v[206:209], v[156:159]
	v_mfma_f32_16x16x32_bf16 v[120:123], v[28:31], v[206:209], v[120:123]
	s_setprio 0
	s_setprio 1
	v_mfma_f32_16x16x32_bf16 v[12:15], v[32:35], v[160:163], v[12:15]
	v_mfma_f32_16x16x32_bf16 v[8:11], v[40:43], v[160:163], v[8:11]
	v_mfma_f32_16x16x32_bf16 v[136:139], v[32:35], v[174:177], v[136:139]
	v_mfma_f32_16x16x32_bf16 v[128:131], v[40:43], v[174:177], v[128:131]
	v_mfma_f32_16x16x32_bf16 v[124:127], v[32:35], v[194:197], v[124:127]
	v_mfma_f32_16x16x32_bf16 v[116:119], v[40:43], v[194:197], v[116:119]
	v_mfma_f32_16x16x32_bf16 v[112:115], v[32:35], v[202:205], v[112:115]
	v_mfma_f32_16x16x32_bf16 v[108:111], v[40:43], v[202:205], v[108:111]
	v_mfma_f32_16x16x32_bf16 v[12:15], v[36:39], v[170:173], v[12:15]
	v_mfma_f32_16x16x32_bf16 v[8:11], v[44:47], v[170:173], v[8:11]
	v_mfma_f32_16x16x32_bf16 v[136:139], v[36:39], v[178:181], v[136:139]
	v_mfma_f32_16x16x32_bf16 v[128:131], v[44:47], v[178:181], v[128:131]
	v_mfma_f32_16x16x32_bf16 v[124:127], v[36:39], v[198:201], v[124:127]
	v_mfma_f32_16x16x32_bf16 v[116:119], v[44:47], v[198:201], v[116:119]
	v_mfma_f32_16x16x32_bf16 v[112:115], v[36:39], v[206:209], v[112:115]
	v_mfma_f32_16x16x32_bf16 v[108:111], v[44:47], v[206:209], v[108:111]
	s_setprio 0
	s_barrier
	s_mov_b32 m0, s33
	s_mov_b32 s18, s14
	s_mov_b32 s19, s15
	ds_read_b128 v[160:163], v190 offset:16384
	ds_read_b128 v[170:173], v190 offset:17408
	ds_read_b128 v[174:177], v190 offset:18432
	ds_read_b128 v[178:181], v190 offset:19456
	ds_read_b128 v[194:197], v190 offset:20480
	ds_read_b128 v[198:201], v190 offset:21504
	ds_read_b128 v[202:205], v190 offset:22528
	ds_read_b128 v[206:209], v190 offset:23552
	buffer_load_dwordx4 v183, s[16:19], s93 offen lds
	s_mov_b32 m0, s50
	s_add_i32 s95, s93, 0x80000
	buffer_load_dwordx4 v185, s[16:19], s93 offen lds
	s_mov_b32 m0, s51
	s_nop 0
	buffer_load_dwordx4 v183, s[16:19], s95 offen lds
	s_mov_b32 m0, s53
	s_nop 0
	buffer_load_dwordx4 v185, s[16:19], s95 offen lds
	s_mov_b32 m0, s3
	s_nop 0
	buffer_load_dwordx4 v182, s[12:15], s94 offen lds
	s_mov_b32 m0, s54
	s_nop 0
	buffer_load_dwordx4 v184, s[12:15], s94 offen lds
	s_waitcnt vmcnt(8)
	s_waitcnt lgkmcnt(0)
	s_barrier
	s_setprio 1
	s_waitcnt lgkmcnt(7)
	v_mfma_f32_16x16x32_bf16 v[104:107], v[16:19], v[160:163], v[104:107]
	v_mfma_f32_16x16x32_bf16 v[100:103], v[24:27], v[160:163], v[100:103]
	s_waitcnt lgkmcnt(5)
	v_mfma_f32_16x16x32_bf16 v[96:99], v[16:19], v[174:177], v[96:99]
	v_mfma_f32_16x16x32_bf16 v[88:91], v[24:27], v[174:177], v[88:91]
	s_waitcnt lgkmcnt(3)
	v_mfma_f32_16x16x32_bf16 v[84:87], v[16:19], v[194:197], v[84:87]
	v_mfma_f32_16x16x32_bf16 v[76:79], v[24:27], v[194:197], v[76:79]
	s_waitcnt lgkmcnt(1)
	v_mfma_f32_16x16x32_bf16 v[16:19], v[16:19], v[202:205], v[92:95]
	v_mfma_f32_16x16x32_bf16 v[104:107], v[20:23], v[170:173], v[104:107]
	v_mfma_f32_16x16x32_bf16 v[100:103], v[28:31], v[170:173], v[100:103]
	v_mfma_f32_16x16x32_bf16 v[96:99], v[20:23], v[178:181], v[96:99]
	v_mfma_f32_16x16x32_bf16 v[88:91], v[28:31], v[178:181], v[88:91]
	v_mfma_f32_16x16x32_bf16 v[84:87], v[20:23], v[198:201], v[84:87]
	v_mfma_f32_16x16x32_bf16 v[76:79], v[28:31], v[198:201], v[76:79]
	s_waitcnt lgkmcnt(0)
	v_mfma_f32_16x16x32_bf16 v[16:19], v[20:23], v[206:209], v[16:19]
	v_mfma_f32_16x16x32_bf16 v[20:23], v[24:27], v[202:205], v[48:51]
	v_mfma_f32_16x16x32_bf16 v[20:23], v[28:31], v[206:209], v[20:23]
	s_setprio 0
	s_setprio 1
	v_mfma_f32_16x16x32_bf16 v[48:51], v[32:35], v[194:197], v[68:71]
	v_mfma_f32_16x16x32_bf16 v[4:7], v[32:35], v[160:163], v[4:7]
	v_mfma_f32_16x16x32_bf16 v[0:3], v[40:43], v[160:163], v[0:3]
	v_mfma_f32_16x16x32_bf16 v[24:27], v[32:35], v[174:177], v[80:83]
	v_mfma_f32_16x16x32_bf16 v[68:71], v[36:39], v[198:201], v[48:51]
	v_mfma_f32_16x16x32_bf16 v[48:51], v[40:43], v[194:197], v[64:67]
	v_mfma_f32_16x16x32_bf16 v[32:35], v[32:35], v[202:205], v[60:63]
	v_mfma_f32_16x16x32_bf16 v[4:7], v[36:39], v[170:173], v[4:7]
	v_mfma_f32_16x16x32_bf16 v[0:3], v[44:47], v[170:173], v[0:3]
	v_mfma_f32_16x16x32_bf16 v[24:27], v[36:39], v[178:181], v[24:27]
	v_mfma_f32_16x16x32_bf16 v[28:31], v[40:43], v[174:177], v[72:75]
	v_mfma_f32_16x16x32_bf16 v[64:67], v[44:47], v[198:201], v[48:51]
	v_mfma_f32_16x16x32_bf16 v[32:35], v[36:39], v[206:209], v[32:35]
	v_mfma_f32_16x16x32_bf16 v[36:39], v[40:43], v[202:205], v[56:59]
	v_mfma_f32_16x16x32_bf16 v[28:31], v[44:47], v[178:181], v[28:31]
	v_mfma_f32_16x16x32_bf16 v[36:39], v[44:47], v[206:209], v[36:39]
	s_setprio 0
	s_barrier
; #define PG8_STAGE(bufoff, soff, voff) do { _Pragma("unroll") for (int _i = 0; _i < 2; ++_i) \
;         __builtin_amdgcn_raw_ptr_buffer_load_lds(rs_##voff, (PG8_LAS unsigned*)(lds + (bufoff) + ldsw + _i * 8192), 16, (int)(voff)[_i], (int)(soff), 0, 0); } while (0)
; #define PG8_LDA(dst, b, h) do { _Pragma("unroll") for (int m = 0; m < 4; ++m) _Pragma("unroll") for (int k = 0; k < 2; ++k) dst[m][k] = *(const PG8_LAS bf16x8*)(lds + PG8_SA(b, h) + aoff + m * 2048 + k * 1024); } while (0)
; #define PG8_LDB(dst, b, h) do { _Pragma("unroll") for (int n = 0; n < 2; ++n) _Pragma("unroll") for (int k = 0; k < 2; ++k) dst[n][k] = *(const PG8_LAS bf16x8*)(lds + PG8_SB(b, h) + boff + n * 2048 + k * 1024); } while (0)
; #define PG8_MMA(ai, bj, At, Bt) do { __builtin_amdgcn_s_setprio(1); _Pragma("unroll") for (int m = 0; m < 4; ++m) _Pragma("unroll") for (int n = 0; n < 2; ++n) _Pragma("unroll") for (int k = 0; k < 2; ++k) \
;         acc[ai][bj][m][n] = __builtin_amdgcn_mfma_f32_16x16x32_bf16(Bt[n][k], At[m][k], acc[ai][bj][m][n], 0, 0, 0); __builtin_amdgcn_s_setprio(0); } while (0)
; #define PG8_WAIT_V(n) asm volatile("s_waitcnt vmcnt(" #n ")" ::: "memory")
; #define PG8_WAIT_L(n) asm volatile("s_waitcnt lgkmcnt(" #n ")" ::: "memory")
; #define PG8_BAR __builtin_amdgcn_s_barrier()
; #define PG8_SCHED __builtin_amdgcn_sched_barrier(0)
; template <class Epi, class Sched, bool ALIGN_EPI = false, bool SP2 = false>
; __device__ __forceinline__ void gemm_phase(PG8_LAS unsigned char* lds, const Gemm g, const Sched& S, const Epi& E, const int wid  ) {
;     ...
;             PG8_LDB(B0, 1, 0); PG8_LDB(B1, 1, 1); PG8_SCHED; PG8_LDA(At, 1, 0); PG8_STAGE(PG8_SA(0, 1), a2 + hstep, voffA);
;             PG8_WAIT_V(8); PG8_WAIT_L(0); PG8_BAR; PG8_MMA(0, 0, At, B0); PG8_MMA(0, 1, At, B1); PG8_BAR; PG8_SCHED;
;             PG8_LDA(At, 1, 1); PG8_STAGE(PG8_SB(1, 0), b3, voffB); PG8_STAGE(PG8_SB(1, 1), b3 + hstep, voffB); PG8_STAGE(PG8_SA(1, 0), a3, voffA);
;             PG8_WAIT_V(8); PG8_WAIT_L(0); PG8_BAR; PG8_MMA(1, 0, At, B0); PG8_MMA(1, 1, At, B1); PG8_BAR; PG8_SCHED;
;     ...
;         if constexpr (ALIGN_EPI) { if (wr == 0) PG8_BAR; }
	ds_read_b128 v[40:43], v191
	ds_read_b128 v[44:47], v191 offset:1024
	ds_read_b128 v[48:51], v191 offset:2048
	ds_read_b128 v[56:59], v191 offset:3072
	ds_read_b128 v[60:63], v192
	ds_read_b128 v[160:163], v192 offset:1024
	ds_read_b128 v[170:173], v192 offset:2048
	ds_read_b128 v[174:177], v192 offset:3072
	s_add_i32 s94, s94, 0x80000
	s_mov_b32 m0, s55
	ds_read_b128 v[72:75], v190 offset:32768
	ds_read_b128 v[80:83], v190 offset:33792
	ds_read_b128 v[92:95], v190 offset:34816
	ds_read_b128 v[178:181], v190 offset:35840
	ds_read_b128 v[194:197], v190 offset:36864
	ds_read_b128 v[198:201], v190 offset:37888
	ds_read_b128 v[202:205], v190 offset:38912
	ds_read_b128 v[206:209], v190 offset:39936
	buffer_load_dwordx4 v182, s[12:15], s94 offen lds
	s_mov_b32 m0, s59
	s_nop 0
	buffer_load_dwordx4 v184, s[12:15], s94 offen lds
	s_waitcnt vmcnt(8)
	s_waitcnt lgkmcnt(0)
	s_barrier
	s_setprio 1
	s_waitcnt lgkmcnt(7)
	v_mfma_f32_16x16x32_bf16 v[152:155], v[40:43], v[72:75], v[152:155]
	v_mfma_f32_16x16x32_bf16 v[52:55], v[48:51], v[72:75], v[52:55]
	s_waitcnt lgkmcnt(5)
	v_mfma_f32_16x16x32_bf16 v[148:151], v[40:43], v[92:95], v[148:151]
	v_mfma_f32_16x16x32_bf16 v[144:147], v[48:51], v[92:95], v[144:147]
	s_waitcnt lgkmcnt(3)
	v_mfma_f32_16x16x32_bf16 v[140:143], v[40:43], v[194:197], v[140:143]
	v_mfma_f32_16x16x32_bf16 v[132:135], v[48:51], v[194:197], v[132:135]
	s_waitcnt lgkmcnt(1)
	v_mfma_f32_16x16x32_bf16 v[156:159], v[40:43], v[202:205], v[156:159]
	v_mfma_f32_16x16x32_bf16 v[120:123], v[48:51], v[202:205], v[120:123]
	v_mfma_f32_16x16x32_bf16 v[152:155], v[44:47], v[80:83], v[152:155]
	v_mfma_f32_16x16x32_bf16 v[52:55], v[56:59], v[80:83], v[52:55]
	v_mfma_f32_16x16x32_bf16 v[148:151], v[44:47], v[178:181], v[148:151]
	v_mfma_f32_16x16x32_bf16 v[144:147], v[56:59], v[178:181], v[144:147]
	v_mfma_f32_16x16x32_bf16 v[140:143], v[44:47], v[198:201], v[140:143]
	v_mfma_f32_16x16x32_bf16 v[132:135], v[56:59], v[198:201], v[132:135]
	s_waitcnt lgkmcnt(0)
	v_mfma_f32_16x16x32_bf16 v[156:159], v[44:47], v[206:209], v[156:159]
	v_mfma_f32_16x16x32_bf16 v[120:123], v[56:59], v[206:209], v[120:123]
	s_setprio 0
	s_setprio 1
	v_mfma_f32_16x16x32_bf16 v[12:15], v[60:63], v[72:75], v[12:15]
	v_mfma_f32_16x16x32_bf16 v[8:11], v[170:173], v[72:75], v[8:11]
	v_mfma_f32_16x16x32_bf16 v[72:75], v[60:63], v[92:95], v[136:139]
	v_mfma_f32_16x16x32_bf16 v[136:139], v[160:163], v[178:181], v[72:75]
	v_mfma_f32_16x16x32_bf16 v[72:75], v[170:173], v[92:95], v[128:131]
	v_mfma_f32_16x16x32_bf16 v[128:131], v[174:177], v[178:181], v[72:75]
	v_mfma_f32_16x16x32_bf16 v[72:75], v[60:63], v[194:197], v[124:127]
	v_mfma_f32_16x16x32_bf16 v[124:127], v[160:163], v[198:201], v[72:75]
	v_mfma_f32_16x16x32_bf16 v[72:75], v[170:173], v[194:197], v[116:119]
	v_mfma_f32_16x16x32_bf16 v[116:119], v[174:177], v[198:201], v[72:75]
	v_mfma_f32_16x16x32_bf16 v[72:75], v[60:63], v[202:205], v[112:115]
	v_mfma_f32_16x16x32_bf16 v[112:115], v[160:163], v[206:209], v[72:75]
	v_mfma_f32_16x16x32_bf16 v[72:75], v[170:173], v[202:205], v[108:111]
	v_mfma_f32_16x16x32_bf16 v[12:15], v[160:163], v[80:83], v[12:15]
	v_mfma_f32_16x16x32_bf16 v[8:11], v[174:177], v[80:83], v[8:11]
	v_mfma_f32_16x16x32_bf16 v[108:111], v[174:177], v[206:209], v[72:75]
	s_setprio 0
	s_barrier
	s_mov_b32 m0, s64
	s_or_b32 s94, s93, 0x80
	s_nop 0
	ds_read_b128 v[72:75], v190 offset:49152
	ds_read_b128 v[80:83], v190 offset:50176
	ds_read_b128 v[178:181], v190 offset:51200
	ds_read_b128 v[194:197], v190 offset:52224
	ds_read_b128 v[198:201], v190 offset:53248
	ds_read_b128 v[202:205], v190 offset:54272
	ds_read_b128 v[206:209], v190 offset:55296
	ds_read_b128 v[210:213], v190 offset:56320
	buffer_load_dwordx4 v183, s[16:19], s94 offen lds
	s_mov_b32 m0, s66
	s_add_i32 s93, s93, 0x80080
	buffer_load_dwordx4 v185, s[16:19], s94 offen lds
	s_mov_b32 m0, s69
	s_nop 0
	buffer_load_dwordx4 v183, s[16:19], s93 offen lds
	s_mov_b32 m0, s70
	s_nop 0
	buffer_load_dwordx4 v185, s[16:19], s93 offen lds
	s_mov_b32 m0, s67
	s_nop 0
	buffer_load_dwordx4 v182, s[12:15], s47 offen lds
	s_mov_b32 m0, s68
	s_nop 0
	buffer_load_dwordx4 v184, s[12:15], s47 offen lds
	s_waitcnt vmcnt(8)
	s_waitcnt lgkmcnt(0)
	s_barrier
	s_setprio 1
	s_waitcnt lgkmcnt(7)
	v_mfma_f32_16x16x32_bf16 v[92:95], v[40:43], v[72:75], v[104:107]
	s_waitcnt lgkmcnt(6)
	v_mfma_f32_16x16x32_bf16 v[104:107], v[44:47], v[80:83], v[92:95]
	v_mfma_f32_16x16x32_bf16 v[92:95], v[48:51], v[72:75], v[100:103]
	v_mfma_f32_16x16x32_bf16 v[100:103], v[56:59], v[80:83], v[92:95]
	s_waitcnt lgkmcnt(5)
	v_mfma_f32_16x16x32_bf16 v[92:95], v[40:43], v[178:181], v[96:99]
	s_waitcnt lgkmcnt(1)
	v_mfma_f32_16x16x32_bf16 v[16:19], v[40:43], v[206:209], v[16:19]
	v_mfma_f32_16x16x32_bf16 v[96:99], v[44:47], v[194:197], v[92:95]
	v_mfma_f32_16x16x32_bf16 v[88:91], v[48:51], v[178:181], v[88:91]
	v_mfma_f32_16x16x32_bf16 v[84:87], v[40:43], v[198:201], v[84:87]
	v_mfma_f32_16x16x32_bf16 v[76:79], v[48:51], v[198:201], v[76:79]
	s_waitcnt lgkmcnt(0)
	v_mfma_f32_16x16x32_bf16 v[92:95], v[44:47], v[210:213], v[16:19]
	v_mfma_f32_16x16x32_bf16 v[16:19], v[48:51], v[206:209], v[20:23]
	v_mfma_f32_16x16x32_bf16 v[88:91], v[56:59], v[194:197], v[88:91]
	v_mfma_f32_16x16x32_bf16 v[84:87], v[44:47], v[202:205], v[84:87]
	v_mfma_f32_16x16x32_bf16 v[76:79], v[56:59], v[202:205], v[76:79]
	v_mfma_f32_16x16x32_bf16 v[48:51], v[56:59], v[210:213], v[16:19]
	s_setprio 0
	s_setprio 1
	v_mfma_f32_16x16x32_bf16 v[4:7], v[60:63], v[72:75], v[4:7]
	v_mfma_f32_16x16x32_bf16 v[0:3], v[170:173], v[72:75], v[0:3]
	v_mfma_f32_16x16x32_bf16 v[16:19], v[60:63], v[178:181], v[24:27]
	v_mfma_f32_16x16x32_bf16 v[4:7], v[160:163], v[80:83], v[4:7]
	v_mfma_f32_16x16x32_bf16 v[0:3], v[174:177], v[80:83], v[0:3]
	v_mfma_f32_16x16x32_bf16 v[80:83], v[160:163], v[194:197], v[16:19]
	v_mfma_f32_16x16x32_bf16 v[16:19], v[170:173], v[178:181], v[28:31]
	v_mfma_f32_16x16x32_bf16 v[72:75], v[174:177], v[194:197], v[16:19]
	v_mfma_f32_16x16x32_bf16 v[16:19], v[60:63], v[198:201], v[68:71]
	v_mfma_f32_16x16x32_bf16 v[68:71], v[160:163], v[202:205], v[16:19]
	v_mfma_f32_16x16x32_bf16 v[16:19], v[170:173], v[198:201], v[64:67]
	v_mfma_f32_16x16x32_bf16 v[64:67], v[174:177], v[202:205], v[16:19]
	v_mfma_f32_16x16x32_bf16 v[16:19], v[60:63], v[206:209], v[32:35]
	v_mfma_f32_16x16x32_bf16 v[60:63], v[160:163], v[210:213], v[16:19]
	v_mfma_f32_16x16x32_bf16 v[16:19], v[170:173], v[206:209], v[36:39]
	v_mfma_f32_16x16x32_bf16 v[56:59], v[174:177], v[210:213], v[16:19]
	s_setprio 0
	s_add_i32 s46, s46, 2
	s_addk_i32 s8, 0x100
	s_addk_i32 s9, 0x100
	s_cmp_gt_u32 s46, 29
	s_cbranch_scc0 .Lrot_658
	s_barrier
	s_and_b64 vcc, exec, s[26:27]
	s_cbranch_vccz .LBB0_661
	s_barrier

; template <class Epi, class Sched, bool ALIGN_EPI = false, bool SP2 = false>
; __device__ __forceinline__ void gemm_phase(PG8_LAS unsigned char* lds, const Gemm g, const Sched& S, const Epi& E, const int wid  ) {
;     ...
;         const bool has_next = S.next(ui + 1, nxt); nxt.same = (has_next && nxt.pm == cur.pm) ? 1 : 0;
;         const unsigned nA = has_next ? (unsigned)g.asel(nxt.pn) * (unsigned)g.a_stride + (unsigned)nxt.pm * tstep : cA, nB = has_next ? (unsigned)nxt.pn * tstep : cB;
;     ...
; #pragma unroll
;         for (int a = 0; a < 2; ++a)
; #pragma unroll
;             for (int b = 0; b < 2; ++b)
; #pragma unroll
;                 for (int m = 0; m < 4; ++m)
; #pragma unroll
;                     for (int n = 0; n < 2; ++n) acc[a][b][m][n] = (f32x4){0.f, 0.f, 0.f, 0.f};
;         cur = nxt; cA = nA; cB = nB; ++ui;
.LBB0_803:
	s_mul_i32 s50, s49, 0x2c0000
	s_and_b64 s[0:1], s[4:5], exec
	s_mul_i32 s51, s48, 0x2c0000
	v_mov_b32_e32 v0, 0
	s_cselect_b32 s0, s50, s54
	s_cselect_b32 s1, s51, s55
	s_add_i32 s54, s54, 0x160080
	s_addk_i32 s55, 0x100
	s_mov_b32 s58, -2
	s_waitcnt lgkmcnt(0)
	v_mov_b32_e32 v1, v0
	v_mov_b32_e32 v2, v0
	v_mov_b32_e32 v3, v0
	v_mov_b32_e32 v4, v0
	v_mov_b32_e32 v5, v0
	v_mov_b32_e32 v6, v0
	v_mov_b32_e32 v7, v0
	v_mov_b32_e32 v16, v0
	v_mov_b32_e32 v17, v0
	v_mov_b32_e32 v18, v0
	v_mov_b32_e32 v19, v0
	v_mov_b32_e32 v20, v0
	v_mov_b32_e32 v21, v0
	v_mov_b32_e32 v22, v0
	v_mov_b32_e32 v23, v0
	v_mov_b32_e32 v32, v0
	v_mov_b32_e32 v33, v0
	v_mov_b32_e32 v34, v0
	v_mov_b32_e32 v35, v0
	v_mov_b32_e32 v36, v0
	v_mov_b32_e32 v37, v0
	v_mov_b32_e32 v38, v0
	v_mov_b32_e32 v39, v0
	v_mov_b32_e32 v48, v0
	v_mov_b32_e32 v49, v0
	v_mov_b32_e32 v50, v0
	v_mov_b32_e32 v51, v0
	v_mov_b32_e32 v52, v0
	v_mov_b32_e32 v53, v0
	v_mov_b32_e32 v54, v0
	v_mov_b32_e32 v55, v0
	v_mov_b32_e32 v8, v0
	v_mov_b32_e32 v9, v0
	v_mov_b32_e32 v10, v0
	v_mov_b32_e32 v11, v0
	v_mov_b32_e32 v12, v0
	v_mov_b32_e32 v13, v0
	v_mov_b32_e32 v14, v0
	v_mov_b32_e32 v15, v0
	v_mov_b32_e32 v24, v0
	v_mov_b32_e32 v25, v0
	v_mov_b32_e32 v26, v0
	v_mov_b32_e32 v27, v0
	v_mov_b32_e32 v28, v0
	v_mov_b32_e32 v29, v0
	v_mov_b32_e32 v30, v0
	v_mov_b32_e32 v31, v0
	v_mov_b32_e32 v40, v0
	v_mov_b32_e32 v41, v0
	v_mov_b32_e32 v42, v0
	v_mov_b32_e32 v43, v0
	v_mov_b32_e32 v44, v0
	v_mov_b32_e32 v45, v0
	v_mov_b32_e32 v46, v0
	v_mov_b32_e32 v47, v0
	v_mov_b32_e32 v56, v0
	v_mov_b32_e32 v57, v0
	v_mov_b32_e32 v58, v0
	v_mov_b32_e32 v59, v0
	v_mov_b32_e32 v60, v0
	v_mov_b32_e32 v61, v0
	v_mov_b32_e32 v62, v0
	v_mov_b32_e32 v63, v0
	v_mov_b32_e32 v64, v0
	v_mov_b32_e32 v65, v0
	v_mov_b32_e32 v66, v0
	v_mov_b32_e32 v67, v0
	v_mov_b32_e32 v68, v0
	v_mov_b32_e32 v69, v0
	v_mov_b32_e32 v70, v0
	v_mov_b32_e32 v71, v0
	v_mov_b32_e32 v80, v0
	v_mov_b32_e32 v81, v0
	v_mov_b32_e32 v82, v0
	v_mov_b32_e32 v83, v0
	v_mov_b32_e32 v84, v0
	v_mov_b32_e32 v85, v0
	v_mov_b32_e32 v86, v0
	v_mov_b32_e32 v87, v0
	v_mov_b32_e32 v96, v0
	v_mov_b32_e32 v97, v0
	v_mov_b32_e32 v98, v0
	v_mov_b32_e32 v99, v0
	v_mov_b32_e32 v100, v0
	v_mov_b32_e32 v101, v0
	v_mov_b32_e32 v102, v0
	v_mov_b32_e32 v103, v0
	v_mov_b32_e32 v112, v0
	v_mov_b32_e32 v113, v0
	v_mov_b32_e32 v114, v0
	v_mov_b32_e32 v115, v0
	v_mov_b32_e32 v116, v0
	v_mov_b32_e32 v117, v0
	v_mov_b32_e32 v118, v0
	v_mov_b32_e32 v119, v0
	v_mov_b32_e32 v72, v0
	v_mov_b32_e32 v73, v0
	v_mov_b32_e32 v74, v0
	v_mov_b32_e32 v75, v0
	v_mov_b32_e32 v76, v0
	v_mov_b32_e32 v77, v0
	v_mov_b32_e32 v78, v0
	v_mov_b32_e32 v79, v0
	v_mov_b32_e32 v88, v0
	v_mov_b32_e32 v89, v0
	v_mov_b32_e32 v90, v0
	v_mov_b32_e32 v91, v0
	v_mov_b32_e32 v92, v0
	v_mov_b32_e32 v93, v0
	v_mov_b32_e32 v94, v0
	v_mov_b32_e32 v95, v0
	v_mov_b32_e32 v104, v0
	v_mov_b32_e32 v105, v0
	v_mov_b32_e32 v106, v0
	v_mov_b32_e32 v107, v0
	v_mov_b32_e32 v108, v0
	v_mov_b32_e32 v109, v0
	v_mov_b32_e32 v110, v0
	v_mov_b32_e32 v111, v0
	v_mov_b32_e32 v120, v0
	v_mov_b32_e32 v121, v0
	v_mov_b32_e32 v122, v0
	v_mov_b32_e32 v123, v0
	v_mov_b32_e32 v124, v0
	v_mov_b32_e32 v125, v0
	v_mov_b32_e32 v126, v0
	v_mov_b32_e32 v127, v0
	s_branch .LBB0_804

; #define PG8_STAGE(bufoff, soff, voff) do { _Pragma("unroll") for (int _i = 0; _i < 2; ++_i) \
;         __builtin_amdgcn_raw_ptr_buffer_load_lds(rs_##voff, (PG8_LAS unsigned*)(lds + (bufoff) + ldsw + _i * 8192), 16, (int)(voff)[_i], (int)(soff), 0, 0); } while (0)
; #define PG8_LDA(dst, b, h) do { _Pragma("unroll") for (int m = 0; m < 4; ++m) _Pragma("unroll") for (int k = 0; k < 2; ++k) dst[m][k] = *(const PG8_LAS bf16x8*)(lds + PG8_SA(b, h) + aoff + m * 2048 + k * 1024); } while (0)
; #define PG8_LDB(dst, b, h) do { _Pragma("unroll") for (int n = 0; n < 2; ++n) _Pragma("unroll") for (int k = 0; k < 2; ++k) dst[n][k] = *(const PG8_LAS bf16x8*)(lds + PG8_SB(b, h) + boff + n * 2048 + k * 1024); } while (0)
; #define PG8_MMA(ai, bj, At, Bt) do { __builtin_amdgcn_s_setprio(1); _Pragma("unroll") for (int m = 0; m < 4; ++m) _Pragma("unroll") for (int n = 0; n < 2; ++n) _Pragma("unroll") for (int k = 0; k < 2; ++k) \
;         acc[ai][bj][m][n] = __builtin_amdgcn_mfma_f32_16x16x32_bf16(Bt[n][k], At[m][k], acc[ai][bj][m][n], 0, 0, 0); __builtin_amdgcn_s_setprio(0); } while (0)
; #define PG8_WAIT_V(n) asm volatile("s_waitcnt vmcnt(" #n ")" ::: "memory")
; #define PG8_BAR __builtin_amdgcn_s_barrier()
; template <class Epi, class Sched, bool ALIGN_EPI = false, bool SP2 = false>
; __device__ __forceinline__ void gemm_phase(PG8_LAS unsigned char* lds, const Gemm g, const Sched& S, const Epi& E, const int wid  ) {
;     ...
;         for (int t = 0; t < nt; t += 2) {
;             const bool last = (t == nt - 2);
;             const unsigned a1 = cA + (unsigned)(t + 1) * kstep;
;             const unsigned a2 = last ? nA : cA + (unsigned)(t + 2) * kstep, b2 = last ? nB : cB + (unsigned)(t + 2) * kstep;
;             const unsigned a3 = a2 + kstep, b3 = b2 + kstep;
;             if (last && has_next) S.a_ready(nxt);
;             if constexpr (SP2) {
;             PG8_LDB(B0, 0, 0); PG8_LDB(B1, 0, 1); PG8_SCHED; PG8_LDA(At, 0, 0); PG8_STAGE(PG8_SA(1, 1), a1 + hstep, voffA);
;             PG8_WAIT_V(8); PG8_WAIT_L(0); PG8_BAR; PG8_MMA(0, 0, At, B0); PG8_MMA(0, 1, At, B1); PG8_BAR; PG8_SCHED;
;             PG8_LDA(At, 0, 1); PG8_STAGE(PG8_SB(0, 0), b2, voffB); PG8_STAGE(PG8_SB(0, 1), b2 + hstep, voffB); PG8_STAGE(PG8_SA(0, 0), a2, voffA);
;             PG8_WAIT_V(8); PG8_WAIT_L(0); PG8_BAR; PG8_MMA(1, 0, At, B0); PG8_MMA(1, 1, At, B1); PG8_BAR; PG8_SCHED;
.LBB0_804:
	ds_read_b128 v[132:135], v140
	ds_read_b128 v[146:149], v140 offset:1024
	ds_read_b128 v[150:153], v140 offset:2048
	ds_read_b128 v[154:157], v140 offset:3072
	ds_read_b128 v[158:161], v141
	ds_read_b128 v[162:165], v141 offset:1024
	ds_read_b128 v[166:169], v141 offset:2048
	ds_read_b128 v[170:173], v141 offset:3072
	s_add_i32 s14, s54, 0xffea0080
	s_cmpk_eq_i32 s58, 0x54
	s_cselect_b32 s61, s0, s14
	s_cselect_b32 s60, s1, s55
	s_or_b32 s59, s61, 0x80
	s_mov_b32 m0, s45
	ds_read_b128 v[174:177], v142
	ds_read_b128 v[178:181], v142 offset:1024
	ds_read_b128 v[182:185], v142 offset:2048
	ds_read_b128 v[186:189], v142 offset:3072
	ds_read_b128 v[190:193], v142 offset:4096
	ds_read_b128 v[194:197], v142 offset:5120
	ds_read_b128 v[198:201], v142 offset:6144
	ds_read_b128 v[202:205], v142 offset:7168
	buffer_load_dwordx4 v136, s[8:11], s54 offen lds
	s_mov_b32 m0, s46
	s_nop 0
	buffer_load_dwordx4 v138, s[8:11], s54 offen lds
	s_waitcnt vmcnt(8)
	s_waitcnt lgkmcnt(0)
	s_barrier
	s_setprio 1
	s_waitcnt lgkmcnt(7)
	v_mfma_f32_16x16x32_bf16 v[124:127], v[132:135], v[174:177], v[124:127]
	v_mfma_f32_16x16x32_bf16 v[120:123], v[150:153], v[174:177], v[120:123]
	s_waitcnt lgkmcnt(5)
	v_mfma_f32_16x16x32_bf16 v[108:111], v[132:135], v[182:185], v[108:111]
	v_mfma_f32_16x16x32_bf16 v[104:107], v[150:153], v[182:185], v[104:107]
	s_waitcnt lgkmcnt(3)
	v_mfma_f32_16x16x32_bf16 v[92:95], v[132:135], v[190:193], v[92:95]
	v_mfma_f32_16x16x32_bf16 v[88:91], v[150:153], v[190:193], v[88:91]
	s_waitcnt lgkmcnt(1)
	v_mfma_f32_16x16x32_bf16 v[76:79], v[132:135], v[198:201], v[76:79]
	v_mfma_f32_16x16x32_bf16 v[72:75], v[150:153], v[198:201], v[72:75]
	v_mfma_f32_16x16x32_bf16 v[124:127], v[146:149], v[178:181], v[124:127]
	v_mfma_f32_16x16x32_bf16 v[120:123], v[154:157], v[178:181], v[120:123]
	v_mfma_f32_16x16x32_bf16 v[108:111], v[146:149], v[186:189], v[108:111]
	v_mfma_f32_16x16x32_bf16 v[104:107], v[154:157], v[186:189], v[104:107]
	v_mfma_f32_16x16x32_bf16 v[92:95], v[146:149], v[194:197], v[92:95]
	v_mfma_f32_16x16x32_bf16 v[88:91], v[154:157], v[194:197], v[88:91]
	s_waitcnt lgkmcnt(0)
	v_mfma_f32_16x16x32_bf16 v[76:79], v[146:149], v[202:205], v[76:79]
	v_mfma_f32_16x16x32_bf16 v[72:75], v[154:157], v[202:205], v[72:75]
	s_setprio 0
	s_setprio 1
	v_mfma_f32_16x16x32_bf16 v[116:119], v[158:161], v[174:177], v[116:119]
	v_mfma_f32_16x16x32_bf16 v[112:115], v[166:169], v[174:177], v[112:115]
	v_mfma_f32_16x16x32_bf16 v[100:103], v[158:161], v[182:185], v[100:103]
	v_mfma_f32_16x16x32_bf16 v[96:99], v[166:169], v[182:185], v[96:99]
	v_mfma_f32_16x16x32_bf16 v[84:87], v[158:161], v[190:193], v[84:87]
	v_mfma_f32_16x16x32_bf16 v[80:83], v[166:169], v[190:193], v[80:83]
	v_mfma_f32_16x16x32_bf16 v[68:71], v[158:161], v[198:201], v[68:71]
	v_mfma_f32_16x16x32_bf16 v[64:67], v[166:169], v[198:201], v[64:67]
	v_mfma_f32_16x16x32_bf16 v[116:119], v[162:165], v[178:181], v[116:119]
	v_mfma_f32_16x16x32_bf16 v[112:115], v[170:173], v[178:181], v[112:115]
	v_mfma_f32_16x16x32_bf16 v[100:103], v[162:165], v[186:189], v[100:103]
	v_mfma_f32_16x16x32_bf16 v[96:99], v[170:173], v[186:189], v[96:99]
	v_mfma_f32_16x16x32_bf16 v[84:87], v[162:165], v[194:197], v[84:87]
	v_mfma_f32_16x16x32_bf16 v[80:83], v[170:173], v[194:197], v[80:83]
	v_mfma_f32_16x16x32_bf16 v[68:71], v[162:165], v[202:205], v[68:71]
	v_mfma_f32_16x16x32_bf16 v[64:67], v[170:173], v[202:205], v[64:67]
	s_setprio 0
	s_barrier
	s_mov_b32 m0, s28
	s_mov_b32 s14, s10
	s_mov_b32 s15, s11
	ds_read_b128 v[174:177], v142 offset:16384
	ds_read_b128 v[178:181], v142 offset:17408
	ds_read_b128 v[182:185], v142 offset:18432
	ds_read_b128 v[186:189], v142 offset:19456
	ds_read_b128 v[190:193], v142 offset:20480
	ds_read_b128 v[194:197], v142 offset:21504
	ds_read_b128 v[198:201], v142 offset:22528
	ds_read_b128 v[202:205], v142 offset:23552
	buffer_load_dwordx4 v137, s[12:15], s60 offen lds
	s_mov_b32 m0, s29
	s_add_i32 s62, s60, 0x160000
	buffer_load_dwordx4 v139, s[12:15], s60 offen lds
	s_mov_b32 m0, s30
	s_nop 0
	buffer_load_dwordx4 v137, s[12:15], s62 offen lds
	s_mov_b32 m0, s31
	s_nop 0
	buffer_load_dwordx4 v139, s[12:15], s62 offen lds
	s_mov_b32 m0, s27
	s_nop 0
	buffer_load_dwordx4 v136, s[8:11], s61 offen lds
	s_mov_b32 m0, s33
	s_nop 0
	buffer_load_dwordx4 v138, s[8:11], s61 offen lds
	s_waitcnt vmcnt(8)
	s_waitcnt lgkmcnt(0)
	s_barrier
	s_setprio 1
	s_waitcnt lgkmcnt(7)
	v_mfma_f32_16x16x32_bf16 v[60:63], v[132:135], v[174:177], v[60:63]
	v_mfma_f32_16x16x32_bf16 v[56:59], v[150:153], v[174:177], v[56:59]
	s_waitcnt lgkmcnt(5)
	v_mfma_f32_16x16x32_bf16 v[44:47], v[132:135], v[182:185], v[44:47]
	v_mfma_f32_16x16x32_bf16 v[40:43], v[150:153], v[182:185], v[40:43]
	s_waitcnt lgkmcnt(3)
	v_mfma_f32_16x16x32_bf16 v[28:31], v[132:135], v[190:193], v[28:31]
	v_mfma_f32_16x16x32_bf16 v[24:27], v[150:153], v[190:193], v[24:27]
	s_waitcnt lgkmcnt(1)
	v_mfma_f32_16x16x32_bf16 v[12:15], v[132:135], v[198:201], v[12:15]
	v_mfma_f32_16x16x32_bf16 v[8:11], v[150:153], v[198:201], v[8:11]
	v_mfma_f32_16x16x32_bf16 v[60:63], v[146:149], v[178:181], v[60:63]
	v_mfma_f32_16x16x32_bf16 v[56:59], v[154:157], v[178:181], v[56:59]
	v_mfma_f32_16x16x32_bf16 v[44:47], v[146:149], v[186:189], v[44:47]
	v_mfma_f32_16x16x32_bf16 v[40:43], v[154:157], v[186:189], v[40:43]
	v_mfma_f32_16x16x32_bf16 v[28:31], v[146:149], v[194:197], v[28:31]
	v_mfma_f32_16x16x32_bf16 v[24:27], v[154:157], v[194:197], v[24:27]
	s_waitcnt lgkmcnt(0)
	v_mfma_f32_16x16x32_bf16 v[12:15], v[146:149], v[202:205], v[12:15]
	v_mfma_f32_16x16x32_bf16 v[8:11], v[154:157], v[202:205], v[8:11]
	s_setprio 0
	s_setprio 1
	v_mfma_f32_16x16x32_bf16 v[52:55], v[158:161], v[174:177], v[52:55]
	v_mfma_f32_16x16x32_bf16 v[48:51], v[166:169], v[174:177], v[48:51]
	v_mfma_f32_16x16x32_bf16 v[36:39], v[158:161], v[182:185], v[36:39]
	v_mfma_f32_16x16x32_bf16 v[32:35], v[166:169], v[182:185], v[32:35]
	v_mfma_f32_16x16x32_bf16 v[20:23], v[158:161], v[190:193], v[20:23]
	v_mfma_f32_16x16x32_bf16 v[16:19], v[166:169], v[190:193], v[16:19]
	v_mfma_f32_16x16x32_bf16 v[4:7], v[158:161], v[198:201], v[4:7]
	v_mfma_f32_16x16x32_bf16 v[0:3], v[166:169], v[198:201], v[0:3]
	v_mfma_f32_16x16x32_bf16 v[52:55], v[162:165], v[178:181], v[52:55]
	v_mfma_f32_16x16x32_bf16 v[48:51], v[170:173], v[178:181], v[48:51]
	v_mfma_f32_16x16x32_bf16 v[36:39], v[162:165], v[186:189], v[36:39]
	v_mfma_f32_16x16x32_bf16 v[32:35], v[170:173], v[186:189], v[32:35]
	v_mfma_f32_16x16x32_bf16 v[20:23], v[162:165], v[194:197], v[20:23]
	v_mfma_f32_16x16x32_bf16 v[16:19], v[170:173], v[194:197], v[16:19]
	v_mfma_f32_16x16x32_bf16 v[4:7], v[162:165], v[202:205], v[4:7]
	v_mfma_f32_16x16x32_bf16 v[0:3], v[170:173], v[202:205], v[0:3]
	s_setprio 0
	s_barrier
; #define PG8_STAGE(bufoff, soff, voff) do { _Pragma("unroll") for (int _i = 0; _i < 2; ++_i) \
;         __builtin_amdgcn_raw_ptr_buffer_load_lds(rs_##voff, (PG8_LAS unsigned*)(lds + (bufoff) + ldsw + _i * 8192), 16, (int)(voff)[_i], (int)(soff), 0, 0); } while (0)
; #define PG8_LDA(dst, b, h) do { _Pragma("unroll") for (int m = 0; m < 4; ++m) _Pragma("unroll") for (int k = 0; k < 2; ++k) dst[m][k] = *(const PG8_LAS bf16x8*)(lds + PG8_SA(b, h) + aoff + m * 2048 + k * 1024); } while (0)
; #define PG8_LDB(dst, b, h) do { _Pragma("unroll") for (int n = 0; n < 2; ++n) _Pragma("unroll") for (int k = 0; k < 2; ++k) dst[n][k] = *(const PG8_LAS bf16x8*)(lds + PG8_SB(b, h) + boff + n * 2048 + k * 1024); } while (0)
; #define PG8_MMA(ai, bj, At, Bt) do { __builtin_amdgcn_s_setprio(1); _Pragma("unroll") for (int m = 0; m < 4; ++m) _Pragma("unroll") for (int n = 0; n < 2; ++n) _Pragma("unroll") for (int k = 0; k < 2; ++k) \
;         acc[ai][bj][m][n] = __builtin_amdgcn_mfma_f32_16x16x32_bf16(Bt[n][k], At[m][k], acc[ai][bj][m][n], 0, 0, 0); __builtin_amdgcn_s_setprio(0); } while (0)
; #define PG8_WAIT_V(n) asm volatile("s_waitcnt vmcnt(" #n ")" ::: "memory")
; #define PG8_WAIT_L(n) asm volatile("s_waitcnt lgkmcnt(" #n ")" ::: "memory")
; #define PG8_BAR __builtin_amdgcn_s_barrier()
; #define PG8_SCHED __builtin_amdgcn_sched_barrier(0)
; template <class Epi, class Sched, bool ALIGN_EPI = false, bool SP2 = false>
; __device__ __forceinline__ void gemm_phase(PG8_LAS unsigned char* lds, const Gemm g, const Sched& S, const Epi& E, const int wid  ) {
;     ...
;             PG8_LDB(B0, 1, 0); PG8_LDB(B1, 1, 1); PG8_SCHED; PG8_LDA(At, 1, 0); PG8_STAGE(PG8_SA(0, 1), a2 + hstep, voffA);
;             PG8_WAIT_V(8); PG8_WAIT_L(0); PG8_BAR; PG8_MMA(0, 0, At, B0); PG8_MMA(0, 1, At, B1); PG8_BAR; PG8_SCHED;
;             PG8_LDA(At, 1, 1); PG8_STAGE(PG8_SB(1, 0), b3, voffB); PG8_STAGE(PG8_SB(1, 1), b3 + hstep, voffB); PG8_STAGE(PG8_SA(1, 0), a3, voffA);
;             PG8_WAIT_V(8); PG8_WAIT_L(0); PG8_BAR; PG8_MMA(1, 0, At, B0); PG8_MMA(1, 1, At, B1); PG8_BAR; PG8_SCHED;
;     ...
;         if constexpr (ALIGN_EPI) { if (wr == 0) PG8_BAR; }
	ds_read_b128 v[132:135], v143
	ds_read_b128 v[146:149], v143 offset:1024
	ds_read_b128 v[150:153], v143 offset:2048
	ds_read_b128 v[154:157], v143 offset:3072
	ds_read_b128 v[158:161], v144
	ds_read_b128 v[162:165], v144 offset:1024
	ds_read_b128 v[166:169], v144 offset:2048
	ds_read_b128 v[170:173], v144 offset:3072
	s_add_i32 s61, s61, 0x160000
	s_mov_b32 m0, s34
	ds_read_b128 v[174:177], v142 offset:32768
	ds_read_b128 v[178:181], v142 offset:33792
	ds_read_b128 v[182:185], v142 offset:34816
	ds_read_b128 v[186:189], v142 offset:35840
	ds_read_b128 v[190:193], v142 offset:36864
	ds_read_b128 v[194:197], v142 offset:37888
	ds_read_b128 v[198:201], v142 offset:38912
	ds_read_b128 v[202:205], v142 offset:39936
	buffer_load_dwordx4 v136, s[8:11], s61 offen lds
	s_mov_b32 m0, s35
	s_nop 0
	buffer_load_dwordx4 v138, s[8:11], s61 offen lds
	s_waitcnt vmcnt(8)
	s_waitcnt lgkmcnt(0)
	s_barrier
	s_setprio 1
	s_waitcnt lgkmcnt(7)
	v_mfma_f32_16x16x32_bf16 v[124:127], v[132:135], v[174:177], v[124:127]
	v_mfma_f32_16x16x32_bf16 v[120:123], v[150:153], v[174:177], v[120:123]
	s_waitcnt lgkmcnt(5)
	v_mfma_f32_16x16x32_bf16 v[108:111], v[132:135], v[182:185], v[108:111]
	v_mfma_f32_16x16x32_bf16 v[104:107], v[150:153], v[182:185], v[104:107]
	s_waitcnt lgkmcnt(3)
	v_mfma_f32_16x16x32_bf16 v[92:95], v[132:135], v[190:193], v[92:95]
	v_mfma_f32_16x16x32_bf16 v[88:91], v[150:153], v[190:193], v[88:91]
	s_waitcnt lgkmcnt(1)
	v_mfma_f32_16x16x32_bf16 v[76:79], v[132:135], v[198:201], v[76:79]
	v_mfma_f32_16x16x32_bf16 v[72:75], v[150:153], v[198:201], v[72:75]
	v_mfma_f32_16x16x32_bf16 v[124:127], v[146:149], v[178:181], v[124:127]
	v_mfma_f32_16x16x32_bf16 v[120:123], v[154:157], v[178:181], v[120:123]
	v_mfma_f32_16x16x32_bf16 v[108:111], v[146:149], v[186:189], v[108:111]
	v_mfma_f32_16x16x32_bf16 v[104:107], v[154:157], v[186:189], v[104:107]
	v_mfma_f32_16x16x32_bf16 v[92:95], v[146:149], v[194:197], v[92:95]
	v_mfma_f32_16x16x32_bf16 v[88:91], v[154:157], v[194:197], v[88:91]
	s_waitcnt lgkmcnt(0)
	v_mfma_f32_16x16x32_bf16 v[76:79], v[146:149], v[202:205], v[76:79]
	v_mfma_f32_16x16x32_bf16 v[72:75], v[154:157], v[202:205], v[72:75]
	s_setprio 0
	s_setprio 1
	v_mfma_f32_16x16x32_bf16 v[116:119], v[158:161], v[174:177], v[116:119]
	v_mfma_f32_16x16x32_bf16 v[112:115], v[166:169], v[174:177], v[112:115]
	v_mfma_f32_16x16x32_bf16 v[100:103], v[158:161], v[182:185], v[100:103]
	v_mfma_f32_16x16x32_bf16 v[96:99], v[166:169], v[182:185], v[96:99]
	v_mfma_f32_16x16x32_bf16 v[84:87], v[158:161], v[190:193], v[84:87]
	v_mfma_f32_16x16x32_bf16 v[80:83], v[166:169], v[190:193], v[80:83]
	v_mfma_f32_16x16x32_bf16 v[68:71], v[158:161], v[198:201], v[68:71]
	v_mfma_f32_16x16x32_bf16 v[64:67], v[166:169], v[198:201], v[64:67]
	v_mfma_f32_16x16x32_bf16 v[116:119], v[162:165], v[178:181], v[116:119]
	v_mfma_f32_16x16x32_bf16 v[112:115], v[170:173], v[178:181], v[112:115]
	v_mfma_f32_16x16x32_bf16 v[100:103], v[162:165], v[186:189], v[100:103]
	v_mfma_f32_16x16x32_bf16 v[96:99], v[170:173], v[186:189], v[96:99]
	v_mfma_f32_16x16x32_bf16 v[84:87], v[162:165], v[194:197], v[84:87]
	v_mfma_f32_16x16x32_bf16 v[80:83], v[170:173], v[194:197], v[80:83]
	v_mfma_f32_16x16x32_bf16 v[68:71], v[162:165], v[202:205], v[68:71]
	v_mfma_f32_16x16x32_bf16 v[64:67], v[170:173], v[202:205], v[64:67]
	s_setprio 0
	s_barrier
	s_mov_b32 m0, s36
	s_or_b32 s61, s60, 0x80
	ds_read_b128 v[174:177], v142 offset:49152
	ds_read_b128 v[178:181], v142 offset:50176
	ds_read_b128 v[182:185], v142 offset:51200
	ds_read_b128 v[186:189], v142 offset:52224
	ds_read_b128 v[190:193], v142 offset:53248
	ds_read_b128 v[194:197], v142 offset:54272
	ds_read_b128 v[198:201], v142 offset:55296
	ds_read_b128 v[202:205], v142 offset:56320
	buffer_load_dwordx4 v137, s[12:15], s61 offen lds
	s_mov_b32 m0, s37
	s_add_i32 s60, s60, 0x160080
	buffer_load_dwordx4 v139, s[12:15], s61 offen lds
	s_mov_b32 m0, s40
	s_nop 0
	buffer_load_dwordx4 v137, s[12:15], s60 offen lds
	s_mov_b32 m0, s41
	s_nop 0
	buffer_load_dwordx4 v139, s[12:15], s60 offen lds
	s_mov_b32 m0, s38
	s_nop 0
	buffer_load_dwordx4 v136, s[8:11], s59 offen lds
	s_mov_b32 m0, s39
	s_nop 0
	buffer_load_dwordx4 v138, s[8:11], s59 offen lds
	s_waitcnt vmcnt(8)
	s_waitcnt lgkmcnt(0)
	s_barrier
	s_setprio 1
	s_waitcnt lgkmcnt(7)
	v_mfma_f32_16x16x32_bf16 v[60:63], v[132:135], v[174:177], v[60:63]
	v_mfma_f32_16x16x32_bf16 v[56:59], v[150:153], v[174:177], v[56:59]
	s_waitcnt lgkmcnt(5)
	v_mfma_f32_16x16x32_bf16 v[44:47], v[132:135], v[182:185], v[44:47]
	v_mfma_f32_16x16x32_bf16 v[40:43], v[150:153], v[182:185], v[40:43]
	s_waitcnt lgkmcnt(3)
	v_mfma_f32_16x16x32_bf16 v[28:31], v[132:135], v[190:193], v[28:31]
	v_mfma_f32_16x16x32_bf16 v[24:27], v[150:153], v[190:193], v[24:27]
	s_waitcnt lgkmcnt(1)
	v_mfma_f32_16x16x32_bf16 v[12:15], v[132:135], v[198:201], v[12:15]
	v_mfma_f32_16x16x32_bf16 v[8:11], v[150:153], v[198:201], v[8:11]
	v_mfma_f32_16x16x32_bf16 v[60:63], v[146:149], v[178:181], v[60:63]
	v_mfma_f32_16x16x32_bf16 v[56:59], v[154:157], v[178:181], v[56:59]
	v_mfma_f32_16x16x32_bf16 v[44:47], v[146:149], v[186:189], v[44:47]
	v_mfma_f32_16x16x32_bf16 v[40:43], v[154:157], v[186:189], v[40:43]
	v_mfma_f32_16x16x32_bf16 v[28:31], v[146:149], v[194:197], v[28:31]
	v_mfma_f32_16x16x32_bf16 v[24:27], v[154:157], v[194:197], v[24:27]
	s_waitcnt lgkmcnt(0)
	v_mfma_f32_16x16x32_bf16 v[12:15], v[146:149], v[202:205], v[12:15]
	v_mfma_f32_16x16x32_bf16 v[8:11], v[154:157], v[202:205], v[8:11]
	s_setprio 0
	s_setprio 1
	v_mfma_f32_16x16x32_bf16 v[52:55], v[158:161], v[174:177], v[52:55]
	v_mfma_f32_16x16x32_bf16 v[48:51], v[166:169], v[174:177], v[48:51]
	v_mfma_f32_16x16x32_bf16 v[36:39], v[158:161], v[182:185], v[36:39]
	v_mfma_f32_16x16x32_bf16 v[32:35], v[166:169], v[182:185], v[32:35]
	v_mfma_f32_16x16x32_bf16 v[20:23], v[158:161], v[190:193], v[20:23]
	v_mfma_f32_16x16x32_bf16 v[16:19], v[166:169], v[190:193], v[16:19]
	v_mfma_f32_16x16x32_bf16 v[4:7], v[158:161], v[198:201], v[4:7]
	v_mfma_f32_16x16x32_bf16 v[0:3], v[166:169], v[198:201], v[0:3]
	v_mfma_f32_16x16x32_bf16 v[52:55], v[162:165], v[178:181], v[52:55]
	v_mfma_f32_16x16x32_bf16 v[48:51], v[170:173], v[178:181], v[48:51]
	v_mfma_f32_16x16x32_bf16 v[36:39], v[162:165], v[186:189], v[36:39]
	v_mfma_f32_16x16x32_bf16 v[32:35], v[170:173], v[186:189], v[32:35]
	v_mfma_f32_16x16x32_bf16 v[20:23], v[162:165], v[194:197], v[20:23]
	v_mfma_f32_16x16x32_bf16 v[16:19], v[170:173], v[194:197], v[16:19]
	v_mfma_f32_16x16x32_bf16 v[4:7], v[162:165], v[202:205], v[4:7]
	v_mfma_f32_16x16x32_bf16 v[0:3], v[170:173], v[202:205], v[0:3]
	s_setprio 0
	s_add_i32 s58, s58, 2
	s_addk_i32 s54, 0x100
	s_addk_i32 s55, 0x100
	s_cmpk_gt_u32 s58, 0x55
	s_cbranch_scc0 .Lrot_804
	s_barrier
	s_and_b64 vcc, exec, s[24:25]
	s_cbranch_vccz .LBB0_807
	s_barrier

; template <class Epi, class Sched, bool ALIGN_EPI = false, bool SP2 = false>
; __device__ __forceinline__ void gemm_phase(PG8_LAS unsigned char* lds, const Gemm g, const Sched& S, const Epi& E, const int wid  ) {
;     ...
;         const bool has_next = S.next(ui + 1, nxt); nxt.same = (has_next && nxt.pm == cur.pm) ? 1 : 0;
;         const unsigned nA = has_next ? (unsigned)g.asel(nxt.pn) * (unsigned)g.a_stride + (unsigned)nxt.pm * tstep : cA, nB = has_next ? (unsigned)nxt.pn * tstep : cB;
;     ...
; #pragma unroll
;         for (int a = 0; a < 2; ++a)
; #pragma unroll
;             for (int b = 0; b < 2; ++b)
; #pragma unroll
;                 for (int m = 0; m < 4; ++m)
; #pragma unroll
;                     for (int n = 0; n < 2; ++n) acc[a][b][m][n] = (f32x4){0.f, 0.f, 0.f, 0.f};
;         cur = nxt; cA = nA; cB = nB; ++ui;
.LBB0_902:
	s_lshl_b32 s70, s69, 20
	s_and_b64 s[14:15], s[4:5], exec
	s_cselect_b32 s33, s70, s41
	s_lshl_b32 s71, s68, 20
	s_and_b64 s[14:15], s[4:5], exec
	v_mov_b32_e32 v0, 0
	s_cselect_b32 s40, s71, s74
	s_add_i32 s41, s41, 0x80080
	s_addk_i32 s74, 0x100
	s_mov_b32 s75, -2
	s_waitcnt lgkmcnt(0)
	v_mov_b32_e32 v1, v0
	v_mov_b32_e32 v2, v0
	v_mov_b32_e32 v3, v0
	v_mov_b32_e32 v4, v0
	v_mov_b32_e32 v5, v0
	s_waitcnt lgkmcnt(6)
	v_mov_b32_e32 v6, v0
	v_mov_b32_e32 v7, v0
	s_waitcnt lgkmcnt(1)
	v_mov_b32_e32 v16, v0
	v_mov_b32_e32 v17, v0
	s_waitcnt lgkmcnt(0)
	v_mov_b32_e32 v18, v0
	v_mov_b32_e32 v19, v0
	v_mov_b32_e32 v20, v0
	v_mov_b32_e32 v21, v0
	v_mov_b32_e32 v22, v0
	v_mov_b32_e32 v23, v0
	v_mov_b32_e32 v32, v0
	v_mov_b32_e32 v33, v0
	v_mov_b32_e32 v34, v0
	v_mov_b32_e32 v35, v0
	v_mov_b32_e32 v36, v0
	v_mov_b32_e32 v37, v0
	v_mov_b32_e32 v38, v0
	v_mov_b32_e32 v39, v0
	v_mov_b32_e32 v48, v0
	v_mov_b32_e32 v49, v0
	v_mov_b32_e32 v50, v0
	v_mov_b32_e32 v51, v0
	v_mov_b32_e32 v52, v0
	v_mov_b32_e32 v53, v0
	v_mov_b32_e32 v54, v0
	v_mov_b32_e32 v55, v0
	v_mov_b32_e32 v8, v0
	v_mov_b32_e32 v9, v0
	v_mov_b32_e32 v10, v0
	v_mov_b32_e32 v11, v0
	v_mov_b32_e32 v12, v0
	v_mov_b32_e32 v13, v0
	v_mov_b32_e32 v14, v0
	v_mov_b32_e32 v15, v0
	v_mov_b32_e32 v24, v0
	v_mov_b32_e32 v25, v0
	v_mov_b32_e32 v26, v0
	v_mov_b32_e32 v27, v0
	v_mov_b32_e32 v28, v0
	v_mov_b32_e32 v29, v0
	v_mov_b32_e32 v30, v0
	v_mov_b32_e32 v31, v0
	v_mov_b32_e32 v40, v0
	v_mov_b32_e32 v41, v0
	v_mov_b32_e32 v42, v0
	v_mov_b32_e32 v43, v0
	v_mov_b32_e32 v44, v0
	v_mov_b32_e32 v45, v0
	v_mov_b32_e32 v46, v0
	v_mov_b32_e32 v47, v0
	v_mov_b32_e32 v56, v0
	v_mov_b32_e32 v57, v0
	v_mov_b32_e32 v58, v0
	v_mov_b32_e32 v59, v0
	v_mov_b32_e32 v60, v0
	v_mov_b32_e32 v61, v0
	v_mov_b32_e32 v62, v0
	v_mov_b32_e32 v63, v0
	v_mov_b32_e32 v64, v0
	v_mov_b32_e32 v65, v0
	v_mov_b32_e32 v66, v0
	v_mov_b32_e32 v67, v0
	v_mov_b32_e32 v68, v0
	v_mov_b32_e32 v69, v0
	v_mov_b32_e32 v70, v0
	v_mov_b32_e32 v71, v0
	v_mov_b32_e32 v80, v0
	v_mov_b32_e32 v81, v0
	v_mov_b32_e32 v82, v0
	v_mov_b32_e32 v83, v0
	v_mov_b32_e32 v84, v0
	v_mov_b32_e32 v85, v0
	v_mov_b32_e32 v86, v0
	v_mov_b32_e32 v87, v0
	v_mov_b32_e32 v96, v0
	v_mov_b32_e32 v97, v0
	v_mov_b32_e32 v98, v0
	v_mov_b32_e32 v99, v0
	v_mov_b32_e32 v100, v0
	v_mov_b32_e32 v101, v0
	v_mov_b32_e32 v102, v0
	v_mov_b32_e32 v103, v0
	v_mov_b32_e32 v112, v0
	v_mov_b32_e32 v113, v0
	v_mov_b32_e32 v114, v0
	v_mov_b32_e32 v115, v0
	v_mov_b32_e32 v116, v0
	v_mov_b32_e32 v117, v0
	v_mov_b32_e32 v118, v0
	v_mov_b32_e32 v119, v0
	v_mov_b32_e32 v72, v0
	v_mov_b32_e32 v73, v0
	v_mov_b32_e32 v74, v0
	v_mov_b32_e32 v75, v0
	v_mov_b32_e32 v76, v0
	v_mov_b32_e32 v77, v0
	v_mov_b32_e32 v78, v0
	v_mov_b32_e32 v79, v0
	v_mov_b32_e32 v88, v0
	v_mov_b32_e32 v89, v0
	v_mov_b32_e32 v90, v0
	v_mov_b32_e32 v91, v0
	v_mov_b32_e32 v92, v0
	v_mov_b32_e32 v93, v0
	v_mov_b32_e32 v94, v0
	v_mov_b32_e32 v95, v0
	v_mov_b32_e32 v104, v0
	v_mov_b32_e32 v105, v0
	v_mov_b32_e32 v106, v0
	v_mov_b32_e32 v107, v0
	v_mov_b32_e32 v108, v0
	v_mov_b32_e32 v109, v0
	v_mov_b32_e32 v110, v0
	v_mov_b32_e32 v111, v0
	v_mov_b32_e32 v120, v0
	v_mov_b32_e32 v121, v0
	v_mov_b32_e32 v122, v0
	v_mov_b32_e32 v123, v0
	v_mov_b32_e32 v124, v0
	v_mov_b32_e32 v125, v0
	v_mov_b32_e32 v126, v0
	v_mov_b32_e32 v127, v0
	s_branch .LBB0_903

; #define PG8_STAGE(bufoff, soff, voff) do { _Pragma("unroll") for (int _i = 0; _i < 2; ++_i) \
;         __builtin_amdgcn_raw_ptr_buffer_load_lds(rs_##voff, (PG8_LAS unsigned*)(lds + (bufoff) + ldsw + _i * 8192), 16, (int)(voff)[_i], (int)(soff), 0, 0); } while (0)
; #define PG8_LDA(dst, b, h) do { _Pragma("unroll") for (int m = 0; m < 4; ++m) _Pragma("unroll") for (int k = 0; k < 2; ++k) dst[m][k] = *(const PG8_LAS bf16x8*)(lds + PG8_SA(b, h) + aoff + m * 2048 + k * 1024); } while (0)
; #define PG8_LDB(dst, b, h) do { _Pragma("unroll") for (int n = 0; n < 2; ++n) _Pragma("unroll") for (int k = 0; k < 2; ++k) dst[n][k] = *(const PG8_LAS bf16x8*)(lds + PG8_SB(b, h) + boff + n * 2048 + k * 1024); } while (0)
; #define PG8_MMA(ai, bj, At, Bt) do { __builtin_amdgcn_s_setprio(1); _Pragma("unroll") for (int m = 0; m < 4; ++m) _Pragma("unroll") for (int n = 0; n < 2; ++n) _Pragma("unroll") for (int k = 0; k < 2; ++k) \
;         acc[ai][bj][m][n] = __builtin_amdgcn_mfma_f32_16x16x32_bf16(Bt[n][k], At[m][k], acc[ai][bj][m][n], 0, 0, 0); __builtin_amdgcn_s_setprio(0); } while (0)
; #define PG8_WAIT_V(n) asm volatile("s_waitcnt vmcnt(" #n ")" ::: "memory")
; #define PG8_BAR __builtin_amdgcn_s_barrier()
; template <class Epi, class Sched, bool ALIGN_EPI = false, bool SP2 = false>
; __device__ __forceinline__ void gemm_phase(PG8_LAS unsigned char* lds, const Gemm g, const Sched& S, const Epi& E, const int wid  ) {
;     ...
;         for (int t = 0; t < nt; t += 2) {
;             const bool last = (t == nt - 2);
;             const unsigned a1 = cA + (unsigned)(t + 1) * kstep;
;             const unsigned a2 = last ? nA : cA + (unsigned)(t + 2) * kstep, b2 = last ? nB : cB + (unsigned)(t + 2) * kstep;
;             const unsigned a3 = a2 + kstep, b3 = b2 + kstep;
;             if (last && has_next) S.a_ready(nxt);
;             if constexpr (SP2) {
;             PG8_LDB(B0, 0, 0); PG8_LDB(B1, 0, 1); PG8_SCHED; PG8_LDA(At, 0, 0); PG8_STAGE(PG8_SA(1, 1), a1 + hstep, voffA);
;             PG8_WAIT_V(8); PG8_WAIT_L(0); PG8_BAR; PG8_MMA(0, 0, At, B0); PG8_MMA(0, 1, At, B1); PG8_BAR; PG8_SCHED;
;             PG8_LDA(At, 0, 1); PG8_STAGE(PG8_SB(0, 0), b2, voffB); PG8_STAGE(PG8_SB(0, 1), b2 + hstep, voffB); PG8_STAGE(PG8_SA(0, 0), a2, voffA);
;             PG8_WAIT_V(8); PG8_WAIT_L(0); PG8_BAR; PG8_MMA(1, 0, At, B0); PG8_MMA(1, 1, At, B1); PG8_BAR; PG8_SCHED;
.LBB0_903:
	ds_read_b128 v[132:135], v152
	ds_read_b128 v[136:139], v152 offset:1024
	ds_read_b128 v[140:143], v152 offset:2048
	ds_read_b128 v[158:161], v152 offset:3072
	ds_read_b128 v[162:165], v153
	ds_read_b128 v[166:169], v153 offset:1024
	ds_read_b128 v[170:173], v153 offset:2048
	ds_read_b128 v[174:177], v153 offset:3072
	s_add_i32 s14, s41, 0xfff80080
	s_cmp_eq_u32 s75, 28
	s_cselect_b32 s78, s33, s14
	s_cselect_b32 s77, s40, s74
	s_or_b32 s76, s78, 0x80
	s_mov_b32 m0, s60
	ds_read_b128 v[178:181], v154
	ds_read_b128 v[182:185], v154 offset:1024
	ds_read_b128 v[186:189], v154 offset:2048
	ds_read_b128 v[190:193], v154 offset:3072
	ds_read_b128 v[194:197], v154 offset:4096
	ds_read_b128 v[198:201], v154 offset:5120
	ds_read_b128 v[202:205], v154 offset:6144
	ds_read_b128 v[206:209], v154 offset:7168
	buffer_load_dwordx4 v146, s[8:11], s41 offen lds
	s_mov_b32 m0, s61
	s_nop 0
	buffer_load_dwordx4 v148, s[8:11], s41 offen lds
	s_waitcnt vmcnt(8)
	s_waitcnt lgkmcnt(0)
	s_barrier
	s_setprio 1
	s_waitcnt lgkmcnt(7)
	v_mfma_f32_16x16x32_bf16 v[124:127], v[132:135], v[178:181], v[124:127]
	v_mfma_f32_16x16x32_bf16 v[120:123], v[140:143], v[178:181], v[120:123]
	s_waitcnt lgkmcnt(5)
	v_mfma_f32_16x16x32_bf16 v[108:111], v[132:135], v[186:189], v[108:111]
	v_mfma_f32_16x16x32_bf16 v[104:107], v[140:143], v[186:189], v[104:107]
	s_waitcnt lgkmcnt(3)
	v_mfma_f32_16x16x32_bf16 v[92:95], v[132:135], v[194:197], v[92:95]
	v_mfma_f32_16x16x32_bf16 v[88:91], v[140:143], v[194:197], v[88:91]
	s_waitcnt lgkmcnt(1)
	v_mfma_f32_16x16x32_bf16 v[76:79], v[132:135], v[202:205], v[76:79]
	v_mfma_f32_16x16x32_bf16 v[72:75], v[140:143], v[202:205], v[72:75]
	v_mfma_f32_16x16x32_bf16 v[124:127], v[136:139], v[182:185], v[124:127]
	v_mfma_f32_16x16x32_bf16 v[120:123], v[158:161], v[182:185], v[120:123]
	v_mfma_f32_16x16x32_bf16 v[108:111], v[136:139], v[190:193], v[108:111]
	v_mfma_f32_16x16x32_bf16 v[104:107], v[158:161], v[190:193], v[104:107]
	v_mfma_f32_16x16x32_bf16 v[92:95], v[136:139], v[198:201], v[92:95]
	v_mfma_f32_16x16x32_bf16 v[88:91], v[158:161], v[198:201], v[88:91]
	s_waitcnt lgkmcnt(0)
	v_mfma_f32_16x16x32_bf16 v[76:79], v[136:139], v[206:209], v[76:79]
	v_mfma_f32_16x16x32_bf16 v[72:75], v[158:161], v[206:209], v[72:75]
	s_setprio 0
	s_setprio 1
	v_mfma_f32_16x16x32_bf16 v[116:119], v[162:165], v[178:181], v[116:119]
	v_mfma_f32_16x16x32_bf16 v[112:115], v[170:173], v[178:181], v[112:115]
	v_mfma_f32_16x16x32_bf16 v[100:103], v[162:165], v[186:189], v[100:103]
	v_mfma_f32_16x16x32_bf16 v[96:99], v[170:173], v[186:189], v[96:99]
	v_mfma_f32_16x16x32_bf16 v[84:87], v[162:165], v[194:197], v[84:87]
	v_mfma_f32_16x16x32_bf16 v[80:83], v[170:173], v[194:197], v[80:83]
	v_mfma_f32_16x16x32_bf16 v[68:71], v[162:165], v[202:205], v[68:71]
	v_mfma_f32_16x16x32_bf16 v[64:67], v[170:173], v[202:205], v[64:67]
	v_mfma_f32_16x16x32_bf16 v[116:119], v[166:169], v[182:185], v[116:119]
	v_mfma_f32_16x16x32_bf16 v[112:115], v[174:177], v[182:185], v[112:115]
	v_mfma_f32_16x16x32_bf16 v[100:103], v[166:169], v[190:193], v[100:103]
	v_mfma_f32_16x16x32_bf16 v[96:99], v[174:177], v[190:193], v[96:99]
	v_mfma_f32_16x16x32_bf16 v[84:87], v[166:169], v[198:201], v[84:87]
	v_mfma_f32_16x16x32_bf16 v[80:83], v[174:177], v[198:201], v[80:83]
	v_mfma_f32_16x16x32_bf16 v[68:71], v[166:169], v[206:209], v[68:71]
	v_mfma_f32_16x16x32_bf16 v[64:67], v[174:177], v[206:209], v[64:67]
	s_setprio 0
	s_barrier
	s_mov_b32 m0, s35
	s_mov_b32 s14, s10
	s_mov_b32 s15, s11
	ds_read_b128 v[178:181], v154 offset:16384
	ds_read_b128 v[182:185], v154 offset:17408
	ds_read_b128 v[186:189], v154 offset:18432
	ds_read_b128 v[190:193], v154 offset:19456
	ds_read_b128 v[194:197], v154 offset:20480
	ds_read_b128 v[198:201], v154 offset:21504
	ds_read_b128 v[202:205], v154 offset:22528
	ds_read_b128 v[206:209], v154 offset:23552
	buffer_load_dwordx4 v147, s[12:15], s77 offen lds
	s_mov_b32 m0, s42
	s_add_i32 s79, s77, 0x80000
	buffer_load_dwordx4 v149, s[12:15], s77 offen lds
	s_mov_b32 m0, s43
	s_nop 0
	buffer_load_dwordx4 v147, s[12:15], s79 offen lds
	s_mov_b32 m0, s44
	s_nop 0
	buffer_load_dwordx4 v149, s[12:15], s79 offen lds
	s_mov_b32 m0, s34
	s_nop 0
	buffer_load_dwordx4 v146, s[8:11], s78 offen lds
	s_mov_b32 m0, s45
	s_nop 0
	buffer_load_dwordx4 v148, s[8:11], s78 offen lds
	s_waitcnt vmcnt(8)
	s_waitcnt lgkmcnt(0)
	s_barrier
	s_setprio 1
	s_waitcnt lgkmcnt(7)
	v_mfma_f32_16x16x32_bf16 v[60:63], v[132:135], v[178:181], v[60:63]
	v_mfma_f32_16x16x32_bf16 v[56:59], v[140:143], v[178:181], v[56:59]
	s_waitcnt lgkmcnt(5)
	v_mfma_f32_16x16x32_bf16 v[44:47], v[132:135], v[186:189], v[44:47]
	v_mfma_f32_16x16x32_bf16 v[40:43], v[140:143], v[186:189], v[40:43]
	s_waitcnt lgkmcnt(3)
	v_mfma_f32_16x16x32_bf16 v[28:31], v[132:135], v[194:197], v[28:31]
	v_mfma_f32_16x16x32_bf16 v[24:27], v[140:143], v[194:197], v[24:27]
	s_waitcnt lgkmcnt(1)
	v_mfma_f32_16x16x32_bf16 v[12:15], v[132:135], v[202:205], v[12:15]
	v_mfma_f32_16x16x32_bf16 v[8:11], v[140:143], v[202:205], v[8:11]
	v_mfma_f32_16x16x32_bf16 v[60:63], v[136:139], v[182:185], v[60:63]
	v_mfma_f32_16x16x32_bf16 v[56:59], v[158:161], v[182:185], v[56:59]
	v_mfma_f32_16x16x32_bf16 v[44:47], v[136:139], v[190:193], v[44:47]
	v_mfma_f32_16x16x32_bf16 v[40:43], v[158:161], v[190:193], v[40:43]
	v_mfma_f32_16x16x32_bf16 v[28:31], v[136:139], v[198:201], v[28:31]
	v_mfma_f32_16x16x32_bf16 v[24:27], v[158:161], v[198:201], v[24:27]
	s_waitcnt lgkmcnt(0)
	v_mfma_f32_16x16x32_bf16 v[12:15], v[136:139], v[206:209], v[12:15]
	v_mfma_f32_16x16x32_bf16 v[8:11], v[158:161], v[206:209], v[8:11]
	s_setprio 0
	s_setprio 1
	v_mfma_f32_16x16x32_bf16 v[52:55], v[162:165], v[178:181], v[52:55]
	v_mfma_f32_16x16x32_bf16 v[48:51], v[170:173], v[178:181], v[48:51]
	v_mfma_f32_16x16x32_bf16 v[36:39], v[162:165], v[186:189], v[36:39]
	v_mfma_f32_16x16x32_bf16 v[32:35], v[170:173], v[186:189], v[32:35]
	v_mfma_f32_16x16x32_bf16 v[20:23], v[162:165], v[194:197], v[20:23]
	v_mfma_f32_16x16x32_bf16 v[16:19], v[170:173], v[194:197], v[16:19]
	v_mfma_f32_16x16x32_bf16 v[4:7], v[162:165], v[202:205], v[4:7]
	v_mfma_f32_16x16x32_bf16 v[0:3], v[170:173], v[202:205], v[0:3]
	v_mfma_f32_16x16x32_bf16 v[52:55], v[166:169], v[182:185], v[52:55]
	v_mfma_f32_16x16x32_bf16 v[48:51], v[174:177], v[182:185], v[48:51]
	v_mfma_f32_16x16x32_bf16 v[36:39], v[166:169], v[190:193], v[36:39]
	v_mfma_f32_16x16x32_bf16 v[32:35], v[174:177], v[190:193], v[32:35]
	v_mfma_f32_16x16x32_bf16 v[20:23], v[166:169], v[198:201], v[20:23]
	v_mfma_f32_16x16x32_bf16 v[16:19], v[174:177], v[198:201], v[16:19]
	v_mfma_f32_16x16x32_bf16 v[4:7], v[166:169], v[206:209], v[4:7]
	v_mfma_f32_16x16x32_bf16 v[0:3], v[174:177], v[206:209], v[0:3]
	s_setprio 0
	s_barrier
; #define PG8_STAGE(bufoff, soff, voff) do { _Pragma("unroll") for (int _i = 0; _i < 2; ++_i) \
;         __builtin_amdgcn_raw_ptr_buffer_load_lds(rs_##voff, (PG8_LAS unsigned*)(lds + (bufoff) + ldsw + _i * 8192), 16, (int)(voff)[_i], (int)(soff), 0, 0); } while (0)
; #define PG8_LDA(dst, b, h) do { _Pragma("unroll") for (int m = 0; m < 4; ++m) _Pragma("unroll") for (int k = 0; k < 2; ++k) dst[m][k] = *(const PG8_LAS bf16x8*)(lds + PG8_SA(b, h) + aoff + m * 2048 + k * 1024); } while (0)
; #define PG8_LDB(dst, b, h) do { _Pragma("unroll") for (int n = 0; n < 2; ++n) _Pragma("unroll") for (int k = 0; k < 2; ++k) dst[n][k] = *(const PG8_LAS bf16x8*)(lds + PG8_SB(b, h) + boff + n * 2048 + k * 1024); } while (0)
; #define PG8_MMA(ai, bj, At, Bt) do { __builtin_amdgcn_s_setprio(1); _Pragma("unroll") for (int m = 0; m < 4; ++m) _Pragma("unroll") for (int n = 0; n < 2; ++n) _Pragma("unroll") for (int k = 0; k < 2; ++k) \
;         acc[ai][bj][m][n] = __builtin_amdgcn_mfma_f32_16x16x32_bf16(Bt[n][k], At[m][k], acc[ai][bj][m][n], 0, 0, 0); __builtin_amdgcn_s_setprio(0); } while (0)
; #define PG8_WAIT_V(n) asm volatile("s_waitcnt vmcnt(" #n ")" ::: "memory")
; #define PG8_WAIT_L(n) asm volatile("s_waitcnt lgkmcnt(" #n ")" ::: "memory")
; #define PG8_BAR __builtin_amdgcn_s_barrier()
; #define PG8_SCHED __builtin_amdgcn_sched_barrier(0)
; template <class Epi, class Sched, bool ALIGN_EPI = false, bool SP2 = false>
; __device__ __forceinline__ void gemm_phase(PG8_LAS unsigned char* lds, const Gemm g, const Sched& S, const Epi& E, const int wid  ) {
;     ...
;             PG8_LDB(B0, 1, 0); PG8_LDB(B1, 1, 1); PG8_SCHED; PG8_LDA(At, 1, 0); PG8_STAGE(PG8_SA(0, 1), a2 + hstep, voffA);
;             PG8_WAIT_V(8); PG8_WAIT_L(0); PG8_BAR; PG8_MMA(0, 0, At, B0); PG8_MMA(0, 1, At, B1); PG8_BAR; PG8_SCHED;
;             PG8_LDA(At, 1, 1); PG8_STAGE(PG8_SB(1, 0), b3, voffB); PG8_STAGE(PG8_SB(1, 1), b3 + hstep, voffB); PG8_STAGE(PG8_SA(1, 0), a3, voffA);
;             PG8_WAIT_V(8); PG8_WAIT_L(0); PG8_BAR; PG8_MMA(1, 0, At, B0); PG8_MMA(1, 1, At, B1); PG8_BAR; PG8_SCHED;
;     ...
;         if constexpr (ALIGN_EPI) { if (wr == 0) PG8_BAR; }
	ds_read_b128 v[132:135], v155
	ds_read_b128 v[136:139], v155 offset:1024
	ds_read_b128 v[140:143], v155 offset:2048
	ds_read_b128 v[158:161], v155 offset:3072
	ds_read_b128 v[162:165], v156
	ds_read_b128 v[166:169], v156 offset:1024
	ds_read_b128 v[170:173], v156 offset:2048
	ds_read_b128 v[174:177], v156 offset:3072
	s_add_i32 s78, s78, 0x80000
	s_mov_b32 m0, s46
	ds_read_b128 v[178:181], v154 offset:32768
	ds_read_b128 v[182:185], v154 offset:33792
	ds_read_b128 v[186:189], v154 offset:34816
	ds_read_b128 v[190:193], v154 offset:35840
	ds_read_b128 v[194:197], v154 offset:36864
	ds_read_b128 v[198:201], v154 offset:37888
	ds_read_b128 v[202:205], v154 offset:38912
	ds_read_b128 v[206:209], v154 offset:39936
	buffer_load_dwordx4 v146, s[8:11], s78 offen lds
	s_mov_b32 m0, s48
	s_nop 0
	buffer_load_dwordx4 v148, s[8:11], s78 offen lds
	s_waitcnt vmcnt(8)
	s_waitcnt lgkmcnt(0)
	s_barrier
	s_setprio 1
	s_waitcnt lgkmcnt(7)
	v_mfma_f32_16x16x32_bf16 v[124:127], v[132:135], v[178:181], v[124:127]
	v_mfma_f32_16x16x32_bf16 v[120:123], v[140:143], v[178:181], v[120:123]
	s_waitcnt lgkmcnt(5)
	v_mfma_f32_16x16x32_bf16 v[108:111], v[132:135], v[186:189], v[108:111]
	v_mfma_f32_16x16x32_bf16 v[104:107], v[140:143], v[186:189], v[104:107]
	s_waitcnt lgkmcnt(3)
	v_mfma_f32_16x16x32_bf16 v[92:95], v[132:135], v[194:197], v[92:95]
	v_mfma_f32_16x16x32_bf16 v[88:91], v[140:143], v[194:197], v[88:91]
	s_waitcnt lgkmcnt(1)
	v_mfma_f32_16x16x32_bf16 v[76:79], v[132:135], v[202:205], v[76:79]
	v_mfma_f32_16x16x32_bf16 v[72:75], v[140:143], v[202:205], v[72:75]
	v_mfma_f32_16x16x32_bf16 v[124:127], v[136:139], v[182:185], v[124:127]
	v_mfma_f32_16x16x32_bf16 v[120:123], v[158:161], v[182:185], v[120:123]
	v_mfma_f32_16x16x32_bf16 v[108:111], v[136:139], v[190:193], v[108:111]
	v_mfma_f32_16x16x32_bf16 v[104:107], v[158:161], v[190:193], v[104:107]
	v_mfma_f32_16x16x32_bf16 v[92:95], v[136:139], v[198:201], v[92:95]
	v_mfma_f32_16x16x32_bf16 v[88:91], v[158:161], v[198:201], v[88:91]
	s_waitcnt lgkmcnt(0)
	v_mfma_f32_16x16x32_bf16 v[76:79], v[136:139], v[206:209], v[76:79]
	v_mfma_f32_16x16x32_bf16 v[72:75], v[158:161], v[206:209], v[72:75]
	s_setprio 0
	s_setprio 1
	v_mfma_f32_16x16x32_bf16 v[116:119], v[162:165], v[178:181], v[116:119]
	v_mfma_f32_16x16x32_bf16 v[112:115], v[170:173], v[178:181], v[112:115]
	v_mfma_f32_16x16x32_bf16 v[100:103], v[162:165], v[186:189], v[100:103]
	v_mfma_f32_16x16x32_bf16 v[96:99], v[170:173], v[186:189], v[96:99]
	v_mfma_f32_16x16x32_bf16 v[84:87], v[162:165], v[194:197], v[84:87]
	v_mfma_f32_16x16x32_bf16 v[80:83], v[170:173], v[194:197], v[80:83]
	v_mfma_f32_16x16x32_bf16 v[68:71], v[162:165], v[202:205], v[68:71]
	v_mfma_f32_16x16x32_bf16 v[64:67], v[170:173], v[202:205], v[64:67]
	v_mfma_f32_16x16x32_bf16 v[116:119], v[166:169], v[182:185], v[116:119]
	v_mfma_f32_16x16x32_bf16 v[112:115], v[174:177], v[182:185], v[112:115]
	v_mfma_f32_16x16x32_bf16 v[100:103], v[166:169], v[190:193], v[100:103]
	v_mfma_f32_16x16x32_bf16 v[96:99], v[174:177], v[190:193], v[96:99]
	v_mfma_f32_16x16x32_bf16 v[84:87], v[166:169], v[198:201], v[84:87]
	v_mfma_f32_16x16x32_bf16 v[80:83], v[174:177], v[198:201], v[80:83]
	v_mfma_f32_16x16x32_bf16 v[68:71], v[166:169], v[206:209], v[68:71]
	v_mfma_f32_16x16x32_bf16 v[64:67], v[174:177], v[206:209], v[64:67]
	s_setprio 0
	s_barrier
	s_mov_b32 m0, s50
	s_or_b32 s78, s77, 0x80
	ds_read_b128 v[178:181], v154 offset:49152
	ds_read_b128 v[182:185], v154 offset:50176
	ds_read_b128 v[186:189], v154 offset:51200
	ds_read_b128 v[190:193], v154 offset:52224
	ds_read_b128 v[194:197], v154 offset:53248
	ds_read_b128 v[198:201], v154 offset:54272
	ds_read_b128 v[202:205], v154 offset:55296
	ds_read_b128 v[206:209], v154 offset:56320
	buffer_load_dwordx4 v147, s[12:15], s78 offen lds
	s_mov_b32 m0, s51
	s_add_i32 s77, s77, 0x80080
	buffer_load_dwordx4 v149, s[12:15], s78 offen lds
	s_mov_b32 m0, s55
	s_nop 0
	buffer_load_dwordx4 v147, s[12:15], s77 offen lds
	s_mov_b32 m0, s58
	s_nop 0
	buffer_load_dwordx4 v149, s[12:15], s77 offen lds
	s_mov_b32 m0, s53
	s_nop 0
	buffer_load_dwordx4 v146, s[8:11], s76 offen lds
	s_mov_b32 m0, s54
	s_nop 0
	buffer_load_dwordx4 v148, s[8:11], s76 offen lds
	s_waitcnt vmcnt(8)
	s_waitcnt lgkmcnt(0)
	s_barrier
	s_setprio 1
	s_waitcnt lgkmcnt(7)
	v_mfma_f32_16x16x32_bf16 v[60:63], v[132:135], v[178:181], v[60:63]
	v_mfma_f32_16x16x32_bf16 v[56:59], v[140:143], v[178:181], v[56:59]
	s_waitcnt lgkmcnt(5)
	v_mfma_f32_16x16x32_bf16 v[44:47], v[132:135], v[186:189], v[44:47]
	v_mfma_f32_16x16x32_bf16 v[40:43], v[140:143], v[186:189], v[40:43]
	s_waitcnt lgkmcnt(3)
	v_mfma_f32_16x16x32_bf16 v[28:31], v[132:135], v[194:197], v[28:31]
	v_mfma_f32_16x16x32_bf16 v[24:27], v[140:143], v[194:197], v[24:27]
	s_waitcnt lgkmcnt(1)
	v_mfma_f32_16x16x32_bf16 v[12:15], v[132:135], v[202:205], v[12:15]
	v_mfma_f32_16x16x32_bf16 v[8:11], v[140:143], v[202:205], v[8:11]
	v_mfma_f32_16x16x32_bf16 v[60:63], v[136:139], v[182:185], v[60:63]
	v_mfma_f32_16x16x32_bf16 v[56:59], v[158:161], v[182:185], v[56:59]
	v_mfma_f32_16x16x32_bf16 v[44:47], v[136:139], v[190:193], v[44:47]
	v_mfma_f32_16x16x32_bf16 v[40:43], v[158:161], v[190:193], v[40:43]
	v_mfma_f32_16x16x32_bf16 v[28:31], v[136:139], v[198:201], v[28:31]
	v_mfma_f32_16x16x32_bf16 v[24:27], v[158:161], v[198:201], v[24:27]
	s_waitcnt lgkmcnt(0)
	v_mfma_f32_16x16x32_bf16 v[12:15], v[136:139], v[206:209], v[12:15]
	v_mfma_f32_16x16x32_bf16 v[8:11], v[158:161], v[206:209], v[8:11]
	s_setprio 0
	s_setprio 1
	v_mfma_f32_16x16x32_bf16 v[52:55], v[162:165], v[178:181], v[52:55]
	v_mfma_f32_16x16x32_bf16 v[48:51], v[170:173], v[178:181], v[48:51]
	v_mfma_f32_16x16x32_bf16 v[36:39], v[162:165], v[186:189], v[36:39]
	v_mfma_f32_16x16x32_bf16 v[32:35], v[170:173], v[186:189], v[32:35]
	v_mfma_f32_16x16x32_bf16 v[20:23], v[162:165], v[194:197], v[20:23]
	v_mfma_f32_16x16x32_bf16 v[16:19], v[170:173], v[194:197], v[16:19]
	v_mfma_f32_16x16x32_bf16 v[4:7], v[162:165], v[202:205], v[4:7]
	v_mfma_f32_16x16x32_bf16 v[0:3], v[170:173], v[202:205], v[0:3]
	v_mfma_f32_16x16x32_bf16 v[52:55], v[166:169], v[182:185], v[52:55]
	v_mfma_f32_16x16x32_bf16 v[48:51], v[174:177], v[182:185], v[48:51]
	v_mfma_f32_16x16x32_bf16 v[36:39], v[166:169], v[190:193], v[36:39]
	v_mfma_f32_16x16x32_bf16 v[32:35], v[174:177], v[190:193], v[32:35]
	v_mfma_f32_16x16x32_bf16 v[20:23], v[166:169], v[198:201], v[20:23]
	v_mfma_f32_16x16x32_bf16 v[16:19], v[174:177], v[198:201], v[16:19]
	v_mfma_f32_16x16x32_bf16 v[4:7], v[166:169], v[206:209], v[4:7]
	v_mfma_f32_16x16x32_bf16 v[0:3], v[174:177], v[206:209], v[0:3]
	s_setprio 0
	s_add_i32 s75, s75, 2
	s_addk_i32 s41, 0x100
	s_addk_i32 s74, 0x100
	s_cmp_gt_u32 s75, 29
	s_cbranch_scc0 .Lrot_903
	s_barrier
	s_and_b64 vcc, exec, s[26:27]
	s_cbranch_vccz .LBB0_906
	s_barrier

; template <class Epi, class Sched, bool ALIGN_EPI = false, bool SP2 = false>
; __device__ __forceinline__ void gemm_phase(PG8_LAS unsigned char* lds, const Gemm g, const Sched& S, const Epi& E, const int wid  ) {
;     ...
;         const bool has_next = S.next(ui + 1, nxt); nxt.same = (has_next && nxt.pm == cur.pm) ? 1 : 0;
;         const unsigned nA = has_next ? (unsigned)g.asel(nxt.pn) * (unsigned)g.a_stride + (unsigned)nxt.pm * tstep : cA, nB = has_next ? (unsigned)nxt.pn * tstep : cB;
;     ...
; #pragma unroll
;         for (int a = 0; a < 2; ++a)
; #pragma unroll
;             for (int b = 0; b < 2; ++b)
; #pragma unroll
;                 for (int m = 0; m < 4; ++m)
; #pragma unroll
;                     for (int n = 0; n < 2; ++n) acc[a][b][m][n] = (f32x4){0.f, 0.f, 0.f, 0.f};
;         cur = nxt; cA = nA; cB = nB; ++ui;
.LBB0_1075:
	s_lshl_b32 s58, s51, 20
	s_and_b64 s[0:1], s[0:1], exec
	v_mov_b32_e32 v0, 0
	s_cselect_b32 s0, s58, s16
	s_add_i32 s1, s20, 0x80080
	s_addk_i32 s16, 0x100
	s_mov_b32 s20, -2
	v_mov_b32_e32 v1, v0
	v_mov_b32_e32 v2, v0
	v_mov_b32_e32 v3, v0
	v_mov_b32_e32 v4, v0
	v_mov_b32_e32 v5, v0
	v_mov_b32_e32 v6, v0
	v_mov_b32_e32 v7, v0
	v_mov_b32_e32 v16, v0
	v_mov_b32_e32 v17, v0
	v_mov_b32_e32 v18, v0
	v_mov_b32_e32 v19, v0
	v_mov_b32_e32 v20, v0
	v_mov_b32_e32 v21, v0
	v_mov_b32_e32 v22, v0
	v_mov_b32_e32 v23, v0
	v_mov_b32_e32 v32, v0
	v_mov_b32_e32 v33, v0
	v_mov_b32_e32 v34, v0
	v_mov_b32_e32 v35, v0
	v_mov_b32_e32 v36, v0
	v_mov_b32_e32 v37, v0
	v_mov_b32_e32 v38, v0
	v_mov_b32_e32 v39, v0
	v_mov_b32_e32 v48, v0
	v_mov_b32_e32 v49, v0
	v_mov_b32_e32 v50, v0
	v_mov_b32_e32 v51, v0
	v_mov_b32_e32 v52, v0
	v_mov_b32_e32 v53, v0
	v_mov_b32_e32 v54, v0
	v_mov_b32_e32 v55, v0
	v_mov_b32_e32 v8, v0
	v_mov_b32_e32 v9, v0
	v_mov_b32_e32 v10, v0
	v_mov_b32_e32 v11, v0
	v_mov_b32_e32 v12, v0
	v_mov_b32_e32 v13, v0
	v_mov_b32_e32 v14, v0
	v_mov_b32_e32 v15, v0
	v_mov_b32_e32 v24, v0
	v_mov_b32_e32 v25, v0
	v_mov_b32_e32 v26, v0
	v_mov_b32_e32 v27, v0
	v_mov_b32_e32 v28, v0
	v_mov_b32_e32 v29, v0
	v_mov_b32_e32 v30, v0
	v_mov_b32_e32 v31, v0
	v_mov_b32_e32 v40, v0
	v_mov_b32_e32 v41, v0
	v_mov_b32_e32 v42, v0
	v_mov_b32_e32 v43, v0
	v_mov_b32_e32 v44, v0
	v_mov_b32_e32 v45, v0
	v_mov_b32_e32 v46, v0
	v_mov_b32_e32 v47, v0
	v_mov_b32_e32 v56, v0
	v_mov_b32_e32 v57, v0
	v_mov_b32_e32 v58, v0
	v_mov_b32_e32 v59, v0
	v_mov_b32_e32 v60, v0
	v_mov_b32_e32 v61, v0
	v_mov_b32_e32 v62, v0
	v_mov_b32_e32 v63, v0
	v_mov_b32_e32 v64, v0
	v_mov_b32_e32 v65, v0
	v_mov_b32_e32 v66, v0
	v_mov_b32_e32 v67, v0
	v_mov_b32_e32 v68, v0
	v_mov_b32_e32 v69, v0
	v_mov_b32_e32 v70, v0
	v_mov_b32_e32 v71, v0
	v_mov_b32_e32 v80, v0
	v_mov_b32_e32 v81, v0
	v_mov_b32_e32 v82, v0
	v_mov_b32_e32 v83, v0
	v_mov_b32_e32 v84, v0
	v_mov_b32_e32 v85, v0
	v_mov_b32_e32 v86, v0
	v_mov_b32_e32 v87, v0
	v_mov_b32_e32 v96, v0
	v_mov_b32_e32 v97, v0
	v_mov_b32_e32 v98, v0
	v_mov_b32_e32 v99, v0
	v_mov_b32_e32 v100, v0
	v_mov_b32_e32 v101, v0
	v_mov_b32_e32 v102, v0
	v_mov_b32_e32 v103, v0
	v_mov_b32_e32 v112, v0
	v_mov_b32_e32 v113, v0
	v_mov_b32_e32 v114, v0
	v_mov_b32_e32 v115, v0
	v_mov_b32_e32 v116, v0
	v_mov_b32_e32 v117, v0
	v_mov_b32_e32 v118, v0
	v_mov_b32_e32 v119, v0
	v_mov_b32_e32 v72, v0
	v_mov_b32_e32 v73, v0
	v_mov_b32_e32 v74, v0
	v_mov_b32_e32 v75, v0
	v_mov_b32_e32 v76, v0
	v_mov_b32_e32 v77, v0
	v_mov_b32_e32 v78, v0
	v_mov_b32_e32 v79, v0
	v_mov_b32_e32 v88, v0
	v_mov_b32_e32 v89, v0
	v_mov_b32_e32 v90, v0
	v_mov_b32_e32 v91, v0
	v_mov_b32_e32 v92, v0
	v_mov_b32_e32 v93, v0
	v_mov_b32_e32 v94, v0
	v_mov_b32_e32 v95, v0
	v_mov_b32_e32 v104, v0
	v_mov_b32_e32 v105, v0
	v_mov_b32_e32 v106, v0
	v_mov_b32_e32 v107, v0
	v_mov_b32_e32 v108, v0
	v_mov_b32_e32 v109, v0
	v_mov_b32_e32 v110, v0
	v_mov_b32_e32 v111, v0
	v_mov_b32_e32 v120, v0
	v_mov_b32_e32 v121, v0
	v_mov_b32_e32 v122, v0
	v_mov_b32_e32 v123, v0
	v_mov_b32_e32 v124, v0
	v_mov_b32_e32 v125, v0
	v_mov_b32_e32 v126, v0
	v_mov_b32_e32 v127, v0
	s_branch .LBB0_1076

; #define PG8_STAGE(bufoff, soff, voff) do { _Pragma("unroll") for (int _i = 0; _i < 2; ++_i) \
;         __builtin_amdgcn_raw_ptr_buffer_load_lds(rs_##voff, (PG8_LAS unsigned*)(lds + (bufoff) + ldsw + _i * 8192), 16, (int)(voff)[_i], (int)(soff), 0, 0); } while (0)
; #define PG8_LDA(dst, b, h) do { _Pragma("unroll") for (int m = 0; m < 4; ++m) _Pragma("unroll") for (int k = 0; k < 2; ++k) dst[m][k] = *(const PG8_LAS bf16x8*)(lds + PG8_SA(b, h) + aoff + m * 2048 + k * 1024); } while (0)
; #define PG8_LDB(dst, b, h) do { _Pragma("unroll") for (int n = 0; n < 2; ++n) _Pragma("unroll") for (int k = 0; k < 2; ++k) dst[n][k] = *(const PG8_LAS bf16x8*)(lds + PG8_SB(b, h) + boff + n * 2048 + k * 1024); } while (0)
; #define PG8_MMA(ai, bj, At, Bt) do { __builtin_amdgcn_s_setprio(1); _Pragma("unroll") for (int m = 0; m < 4; ++m) _Pragma("unroll") for (int n = 0; n < 2; ++n) _Pragma("unroll") for (int k = 0; k < 2; ++k) \
;         acc[ai][bj][m][n] = __builtin_amdgcn_mfma_f32_16x16x32_bf16(Bt[n][k], At[m][k], acc[ai][bj][m][n], 0, 0, 0); __builtin_amdgcn_s_setprio(0); } while (0)
; #define PG8_WAIT_V(n) asm volatile("s_waitcnt vmcnt(" #n ")" ::: "memory")
; #define PG8_BAR __builtin_amdgcn_s_barrier()
; template <class Epi, class Sched, bool ALIGN_EPI = false, bool SP2 = false>
; __device__ __forceinline__ void gemm_phase(PG8_LAS unsigned char* lds, const Gemm g, const Sched& S, const Epi& E, const int wid  ) {
;     ...
;         for (int t = 0; t < nt; t += 2) {
;             const bool last = (t == nt - 2);
;             const unsigned a1 = cA + (unsigned)(t + 1) * kstep;
;             const unsigned a2 = last ? nA : cA + (unsigned)(t + 2) * kstep, b2 = last ? nB : cB + (unsigned)(t + 2) * kstep;
;             const unsigned a3 = a2 + kstep, b3 = b2 + kstep;
;             if (last && has_next) S.a_ready(nxt);
;             if constexpr (SP2) {
;             PG8_LDB(B0, 0, 0); PG8_LDB(B1, 0, 1); PG8_SCHED; PG8_LDA(At, 0, 0); PG8_STAGE(PG8_SA(1, 1), a1 + hstep, voffA);
;             PG8_WAIT_V(8); PG8_WAIT_L(0); PG8_BAR; PG8_MMA(0, 0, At, B0); PG8_MMA(0, 1, At, B1); PG8_BAR; PG8_SCHED;
;             PG8_LDA(At, 0, 1); PG8_STAGE(PG8_SB(0, 0), b2, voffB); PG8_STAGE(PG8_SB(0, 1), b2 + hstep, voffB); PG8_STAGE(PG8_SA(0, 0), a2, voffA);
;             PG8_WAIT_V(8); PG8_WAIT_L(0); PG8_BAR; PG8_MMA(1, 0, At, B0); PG8_MMA(1, 1, At, B1); PG8_BAR; PG8_SCHED;
.LBB0_1076:
	ds_read_b128 v[142:145], v136
	ds_read_b128 v[146:149], v136 offset:1024
	ds_read_b128 v[150:153], v136 offset:2048
	ds_read_b128 v[154:157], v136 offset:3072
	ds_read_b128 v[158:161], v137
	ds_read_b128 v[162:165], v137 offset:1024
	ds_read_b128 v[166:169], v137 offset:2048
	ds_read_b128 v[170:173], v137 offset:3072
	s_add_i32 s14, s1, 0xfff80080
	s_cmp_eq_u32 s20, 28
	s_cselect_b32 s54, s55, s14
	s_cselect_b32 s35, s0, s16
	s_add_i32 s21, s54, 0x80
	s_mov_b32 m0, s45
	ds_read_b128 v[174:177], v138
	ds_read_b128 v[178:181], v138 offset:1024
	ds_read_b128 v[182:185], v138 offset:2048
	ds_read_b128 v[186:189], v138 offset:3072
	ds_read_b128 v[190:193], v138 offset:4096
	ds_read_b128 v[194:197], v138 offset:5120
	ds_read_b128 v[198:201], v138 offset:6144
	ds_read_b128 v[202:205], v138 offset:7168
	buffer_load_dwordx4 v132, s[8:11], s1 offen lds
	s_mov_b32 m0, s46
	s_nop 0
	buffer_load_dwordx4 v134, s[8:11], s1 offen lds
	s_waitcnt vmcnt(8)
	s_waitcnt lgkmcnt(0)
	s_barrier
	s_setprio 1
	s_waitcnt lgkmcnt(7)
	v_mfma_f32_16x16x32_bf16 v[124:127], v[142:145], v[174:177], v[124:127]
	v_mfma_f32_16x16x32_bf16 v[120:123], v[150:153], v[174:177], v[120:123]
	s_waitcnt lgkmcnt(5)
	v_mfma_f32_16x16x32_bf16 v[108:111], v[142:145], v[182:185], v[108:111]
	v_mfma_f32_16x16x32_bf16 v[104:107], v[150:153], v[182:185], v[104:107]
	s_waitcnt lgkmcnt(3)
	v_mfma_f32_16x16x32_bf16 v[92:95], v[142:145], v[190:193], v[92:95]
	v_mfma_f32_16x16x32_bf16 v[88:91], v[150:153], v[190:193], v[88:91]
	s_waitcnt lgkmcnt(1)
	v_mfma_f32_16x16x32_bf16 v[76:79], v[142:145], v[198:201], v[76:79]
	v_mfma_f32_16x16x32_bf16 v[72:75], v[150:153], v[198:201], v[72:75]
	v_mfma_f32_16x16x32_bf16 v[124:127], v[146:149], v[178:181], v[124:127]
	v_mfma_f32_16x16x32_bf16 v[120:123], v[154:157], v[178:181], v[120:123]
	v_mfma_f32_16x16x32_bf16 v[108:111], v[146:149], v[186:189], v[108:111]
	v_mfma_f32_16x16x32_bf16 v[104:107], v[154:157], v[186:189], v[104:107]
	v_mfma_f32_16x16x32_bf16 v[92:95], v[146:149], v[194:197], v[92:95]
	v_mfma_f32_16x16x32_bf16 v[88:91], v[154:157], v[194:197], v[88:91]
	s_waitcnt lgkmcnt(0)
	v_mfma_f32_16x16x32_bf16 v[76:79], v[146:149], v[202:205], v[76:79]
	v_mfma_f32_16x16x32_bf16 v[72:75], v[154:157], v[202:205], v[72:75]
	s_setprio 0
	s_setprio 1
	v_mfma_f32_16x16x32_bf16 v[116:119], v[158:161], v[174:177], v[116:119]
	v_mfma_f32_16x16x32_bf16 v[112:115], v[166:169], v[174:177], v[112:115]
	v_mfma_f32_16x16x32_bf16 v[100:103], v[158:161], v[182:185], v[100:103]
	v_mfma_f32_16x16x32_bf16 v[96:99], v[166:169], v[182:185], v[96:99]
	v_mfma_f32_16x16x32_bf16 v[84:87], v[158:161], v[190:193], v[84:87]
	v_mfma_f32_16x16x32_bf16 v[80:83], v[166:169], v[190:193], v[80:83]
	v_mfma_f32_16x16x32_bf16 v[68:71], v[158:161], v[198:201], v[68:71]
	v_mfma_f32_16x16x32_bf16 v[64:67], v[166:169], v[198:201], v[64:67]
	v_mfma_f32_16x16x32_bf16 v[116:119], v[162:165], v[178:181], v[116:119]
	v_mfma_f32_16x16x32_bf16 v[112:115], v[170:173], v[178:181], v[112:115]
	v_mfma_f32_16x16x32_bf16 v[100:103], v[162:165], v[186:189], v[100:103]
	v_mfma_f32_16x16x32_bf16 v[96:99], v[170:173], v[186:189], v[96:99]
	v_mfma_f32_16x16x32_bf16 v[84:87], v[162:165], v[194:197], v[84:87]
	v_mfma_f32_16x16x32_bf16 v[80:83], v[170:173], v[194:197], v[80:83]
	v_mfma_f32_16x16x32_bf16 v[68:71], v[162:165], v[202:205], v[68:71]
	v_mfma_f32_16x16x32_bf16 v[64:67], v[170:173], v[202:205], v[64:67]
	s_setprio 0
	s_barrier
	s_mov_b32 m0, s22
	s_mov_b32 s14, s10
	s_mov_b32 s15, s11
	ds_read_b128 v[174:177], v138 offset:16384
	ds_read_b128 v[178:181], v138 offset:17408
	ds_read_b128 v[182:185], v138 offset:18432
	ds_read_b128 v[186:189], v138 offset:19456
	ds_read_b128 v[190:193], v138 offset:20480
	ds_read_b128 v[194:197], v138 offset:21504
	ds_read_b128 v[198:201], v138 offset:22528
	ds_read_b128 v[202:205], v138 offset:23552
	buffer_load_dwordx4 v133, s[12:15], s35 offen lds
	s_mov_b32 m0, s23
	s_add_i32 s59, s35, 0x80000
	buffer_load_dwordx4 v135, s[12:15], s35 offen lds
	s_mov_b32 m0, s24
	s_nop 0
	buffer_load_dwordx4 v133, s[12:15], s59 offen lds
	s_mov_b32 m0, s25
	s_nop 0
	buffer_load_dwordx4 v135, s[12:15], s59 offen lds
	s_mov_b32 m0, s3
	s_nop 0
	buffer_load_dwordx4 v132, s[8:11], s54 offen lds
	s_mov_b32 m0, s26
	s_nop 0
	buffer_load_dwordx4 v134, s[8:11], s54 offen lds
	s_waitcnt vmcnt(8)
	s_waitcnt lgkmcnt(0)
	s_barrier
	s_setprio 1
	s_waitcnt lgkmcnt(7)
	v_mfma_f32_16x16x32_bf16 v[60:63], v[142:145], v[174:177], v[60:63]
	v_mfma_f32_16x16x32_bf16 v[56:59], v[150:153], v[174:177], v[56:59]
	s_waitcnt lgkmcnt(5)
	v_mfma_f32_16x16x32_bf16 v[44:47], v[142:145], v[182:185], v[44:47]
	v_mfma_f32_16x16x32_bf16 v[40:43], v[150:153], v[182:185], v[40:43]
	s_waitcnt lgkmcnt(3)
	v_mfma_f32_16x16x32_bf16 v[28:31], v[142:145], v[190:193], v[28:31]
	v_mfma_f32_16x16x32_bf16 v[24:27], v[150:153], v[190:193], v[24:27]
	s_waitcnt lgkmcnt(1)
	v_mfma_f32_16x16x32_bf16 v[12:15], v[142:145], v[198:201], v[12:15]
	v_mfma_f32_16x16x32_bf16 v[8:11], v[150:153], v[198:201], v[8:11]
	v_mfma_f32_16x16x32_bf16 v[60:63], v[146:149], v[178:181], v[60:63]
	v_mfma_f32_16x16x32_bf16 v[56:59], v[154:157], v[178:181], v[56:59]
	v_mfma_f32_16x16x32_bf16 v[44:47], v[146:149], v[186:189], v[44:47]
	v_mfma_f32_16x16x32_bf16 v[40:43], v[154:157], v[186:189], v[40:43]
	v_mfma_f32_16x16x32_bf16 v[28:31], v[146:149], v[194:197], v[28:31]
	v_mfma_f32_16x16x32_bf16 v[24:27], v[154:157], v[194:197], v[24:27]
	s_waitcnt lgkmcnt(0)
	v_mfma_f32_16x16x32_bf16 v[12:15], v[146:149], v[202:205], v[12:15]
	v_mfma_f32_16x16x32_bf16 v[8:11], v[154:157], v[202:205], v[8:11]
	s_setprio 0
	s_setprio 1
	v_mfma_f32_16x16x32_bf16 v[52:55], v[158:161], v[174:177], v[52:55]
	v_mfma_f32_16x16x32_bf16 v[48:51], v[166:169], v[174:177], v[48:51]
	v_mfma_f32_16x16x32_bf16 v[36:39], v[158:161], v[182:185], v[36:39]
	v_mfma_f32_16x16x32_bf16 v[32:35], v[166:169], v[182:185], v[32:35]
	v_mfma_f32_16x16x32_bf16 v[20:23], v[158:161], v[190:193], v[20:23]
	v_mfma_f32_16x16x32_bf16 v[16:19], v[166:169], v[190:193], v[16:19]
	v_mfma_f32_16x16x32_bf16 v[4:7], v[158:161], v[198:201], v[4:7]
	v_mfma_f32_16x16x32_bf16 v[0:3], v[166:169], v[198:201], v[0:3]
	v_mfma_f32_16x16x32_bf16 v[52:55], v[162:165], v[178:181], v[52:55]
	v_mfma_f32_16x16x32_bf16 v[48:51], v[170:173], v[178:181], v[48:51]
	v_mfma_f32_16x16x32_bf16 v[36:39], v[162:165], v[186:189], v[36:39]
	v_mfma_f32_16x16x32_bf16 v[32:35], v[170:173], v[186:189], v[32:35]
	v_mfma_f32_16x16x32_bf16 v[20:23], v[162:165], v[194:197], v[20:23]
	v_mfma_f32_16x16x32_bf16 v[16:19], v[170:173], v[194:197], v[16:19]
	v_mfma_f32_16x16x32_bf16 v[4:7], v[162:165], v[202:205], v[4:7]
	v_mfma_f32_16x16x32_bf16 v[0:3], v[170:173], v[202:205], v[0:3]
	s_setprio 0
	s_barrier
; #define PG8_STAGE(bufoff, soff, voff) do { _Pragma("unroll") for (int _i = 0; _i < 2; ++_i) \
;         __builtin_amdgcn_raw_ptr_buffer_load_lds(rs_##voff, (PG8_LAS unsigned*)(lds + (bufoff) + ldsw + _i * 8192), 16, (int)(voff)[_i], (int)(soff), 0, 0); } while (0)
; #define PG8_LDA(dst, b, h) do { _Pragma("unroll") for (int m = 0; m < 4; ++m) _Pragma("unroll") for (int k = 0; k < 2; ++k) dst[m][k] = *(const PG8_LAS bf16x8*)(lds + PG8_SA(b, h) + aoff + m * 2048 + k * 1024); } while (0)
; #define PG8_LDB(dst, b, h) do { _Pragma("unroll") for (int n = 0; n < 2; ++n) _Pragma("unroll") for (int k = 0; k < 2; ++k) dst[n][k] = *(const PG8_LAS bf16x8*)(lds + PG8_SB(b, h) + boff + n * 2048 + k * 1024); } while (0)
; #define PG8_MMA(ai, bj, At, Bt) do { __builtin_amdgcn_s_setprio(1); _Pragma("unroll") for (int m = 0; m < 4; ++m) _Pragma("unroll") for (int n = 0; n < 2; ++n) _Pragma("unroll") for (int k = 0; k < 2; ++k) \
;         acc[ai][bj][m][n] = __builtin_amdgcn_mfma_f32_16x16x32_bf16(Bt[n][k], At[m][k], acc[ai][bj][m][n], 0, 0, 0); __builtin_amdgcn_s_setprio(0); } while (0)
; #define PG8_WAIT_V(n) asm volatile("s_waitcnt vmcnt(" #n ")" ::: "memory")
; #define PG8_WAIT_L(n) asm volatile("s_waitcnt lgkmcnt(" #n ")" ::: "memory")
; #define PG8_BAR __builtin_amdgcn_s_barrier()
; #define PG8_SCHED __builtin_amdgcn_sched_barrier(0)
; template <class Epi, class Sched, bool ALIGN_EPI = false, bool SP2 = false>
; __device__ __forceinline__ void gemm_phase(PG8_LAS unsigned char* lds, const Gemm g, const Sched& S, const Epi& E, const int wid  ) {
;     ...
;             PG8_LDB(B0, 1, 0); PG8_LDB(B1, 1, 1); PG8_SCHED; PG8_LDA(At, 1, 0); PG8_STAGE(PG8_SA(0, 1), a2 + hstep, voffA);
;             PG8_WAIT_V(8); PG8_WAIT_L(0); PG8_BAR; PG8_MMA(0, 0, At, B0); PG8_MMA(0, 1, At, B1); PG8_BAR; PG8_SCHED;
;             PG8_LDA(At, 1, 1); PG8_STAGE(PG8_SB(1, 0), b3, voffB); PG8_STAGE(PG8_SB(1, 1), b3 + hstep, voffB); PG8_STAGE(PG8_SA(1, 0), a3, voffA);
;             PG8_WAIT_V(8); PG8_WAIT_L(0); PG8_BAR; PG8_MMA(1, 0, At, B0); PG8_MMA(1, 1, At, B1); PG8_BAR; PG8_SCHED;
;     ...
;         if constexpr (ALIGN_EPI) { if (wr == 0) PG8_BAR; }
	ds_read_b128 v[142:145], v139
	ds_read_b128 v[146:149], v139 offset:1024
	ds_read_b128 v[150:153], v139 offset:2048
	ds_read_b128 v[154:157], v139 offset:3072
	ds_read_b128 v[158:161], v140
	ds_read_b128 v[162:165], v140 offset:1024
	ds_read_b128 v[166:169], v140 offset:2048
	ds_read_b128 v[170:173], v140 offset:3072
	s_add_i32 s54, s54, 0x80000
	s_mov_b32 m0, s27
	ds_read_b128 v[174:177], v138 offset:32768
	ds_read_b128 v[178:181], v138 offset:33792
	ds_read_b128 v[182:185], v138 offset:34816
	ds_read_b128 v[186:189], v138 offset:35840
	ds_read_b128 v[190:193], v138 offset:36864
	ds_read_b128 v[194:197], v138 offset:37888
	ds_read_b128 v[198:201], v138 offset:38912
	ds_read_b128 v[202:205], v138 offset:39936
	buffer_load_dwordx4 v132, s[8:11], s54 offen lds
	s_mov_b32 m0, s28
	s_nop 0
	buffer_load_dwordx4 v134, s[8:11], s54 offen lds
	s_waitcnt vmcnt(8)
	s_waitcnt lgkmcnt(0)
	s_barrier
	s_setprio 1
	s_waitcnt lgkmcnt(7)
	v_mfma_f32_16x16x32_bf16 v[124:127], v[142:145], v[174:177], v[124:127]
	v_mfma_f32_16x16x32_bf16 v[120:123], v[150:153], v[174:177], v[120:123]
	s_waitcnt lgkmcnt(5)
	v_mfma_f32_16x16x32_bf16 v[108:111], v[142:145], v[182:185], v[108:111]
	v_mfma_f32_16x16x32_bf16 v[104:107], v[150:153], v[182:185], v[104:107]
	s_waitcnt lgkmcnt(3)
	v_mfma_f32_16x16x32_bf16 v[92:95], v[142:145], v[190:193], v[92:95]
	v_mfma_f32_16x16x32_bf16 v[88:91], v[150:153], v[190:193], v[88:91]
	s_waitcnt lgkmcnt(1)
	v_mfma_f32_16x16x32_bf16 v[76:79], v[142:145], v[198:201], v[76:79]
	v_mfma_f32_16x16x32_bf16 v[72:75], v[150:153], v[198:201], v[72:75]
	v_mfma_f32_16x16x32_bf16 v[124:127], v[146:149], v[178:181], v[124:127]
	v_mfma_f32_16x16x32_bf16 v[120:123], v[154:157], v[178:181], v[120:123]
	v_mfma_f32_16x16x32_bf16 v[108:111], v[146:149], v[186:189], v[108:111]
	v_mfma_f32_16x16x32_bf16 v[104:107], v[154:157], v[186:189], v[104:107]
	v_mfma_f32_16x16x32_bf16 v[92:95], v[146:149], v[194:197], v[92:95]
	v_mfma_f32_16x16x32_bf16 v[88:91], v[154:157], v[194:197], v[88:91]
	s_waitcnt lgkmcnt(0)
	v_mfma_f32_16x16x32_bf16 v[76:79], v[146:149], v[202:205], v[76:79]
	v_mfma_f32_16x16x32_bf16 v[72:75], v[154:157], v[202:205], v[72:75]
	s_setprio 0
	s_setprio 1
	v_mfma_f32_16x16x32_bf16 v[116:119], v[158:161], v[174:177], v[116:119]
	v_mfma_f32_16x16x32_bf16 v[112:115], v[166:169], v[174:177], v[112:115]
	v_mfma_f32_16x16x32_bf16 v[100:103], v[158:161], v[182:185], v[100:103]
	v_mfma_f32_16x16x32_bf16 v[96:99], v[166:169], v[182:185], v[96:99]
	v_mfma_f32_16x16x32_bf16 v[84:87], v[158:161], v[190:193], v[84:87]
	v_mfma_f32_16x16x32_bf16 v[80:83], v[166:169], v[190:193], v[80:83]
	v_mfma_f32_16x16x32_bf16 v[68:71], v[158:161], v[198:201], v[68:71]
	v_mfma_f32_16x16x32_bf16 v[64:67], v[166:169], v[198:201], v[64:67]
	v_mfma_f32_16x16x32_bf16 v[116:119], v[162:165], v[178:181], v[116:119]
	v_mfma_f32_16x16x32_bf16 v[112:115], v[170:173], v[178:181], v[112:115]
	v_mfma_f32_16x16x32_bf16 v[100:103], v[162:165], v[186:189], v[100:103]
	v_mfma_f32_16x16x32_bf16 v[96:99], v[170:173], v[186:189], v[96:99]
	v_mfma_f32_16x16x32_bf16 v[84:87], v[162:165], v[194:197], v[84:87]
	v_mfma_f32_16x16x32_bf16 v[80:83], v[170:173], v[194:197], v[80:83]
	v_mfma_f32_16x16x32_bf16 v[68:71], v[162:165], v[202:205], v[68:71]
	v_mfma_f32_16x16x32_bf16 v[64:67], v[170:173], v[202:205], v[64:67]
	s_setprio 0
	s_barrier
	s_mov_b32 m0, s37
	s_or_b32 s54, s35, 0x80
	ds_read_b128 v[174:177], v138 offset:49152
	ds_read_b128 v[178:181], v138 offset:50176
	ds_read_b128 v[182:185], v138 offset:51200
	ds_read_b128 v[186:189], v138 offset:52224
	ds_read_b128 v[190:193], v138 offset:53248
	ds_read_b128 v[194:197], v138 offset:54272
	ds_read_b128 v[198:201], v138 offset:55296
	ds_read_b128 v[202:205], v138 offset:56320
	buffer_load_dwordx4 v133, s[12:15], s54 offen lds
	s_mov_b32 m0, s38
	s_add_i32 s35, s35, 0x80080
	buffer_load_dwordx4 v135, s[12:15], s54 offen lds
	s_mov_b32 m0, s41
	s_nop 0
	buffer_load_dwordx4 v133, s[12:15], s35 offen lds
	s_mov_b32 m0, s42
	s_nop 0
	buffer_load_dwordx4 v135, s[12:15], s35 offen lds
	s_mov_b32 m0, s39
	s_nop 0
	buffer_load_dwordx4 v132, s[8:11], s21 offen lds
	s_mov_b32 m0, s40
	s_nop 0
	buffer_load_dwordx4 v134, s[8:11], s21 offen lds
	s_waitcnt vmcnt(8)
	s_waitcnt lgkmcnt(0)
	s_barrier
	s_setprio 1
	s_waitcnt lgkmcnt(7)
	v_mfma_f32_16x16x32_bf16 v[60:63], v[142:145], v[174:177], v[60:63]
	v_mfma_f32_16x16x32_bf16 v[56:59], v[150:153], v[174:177], v[56:59]
	s_waitcnt lgkmcnt(5)
	v_mfma_f32_16x16x32_bf16 v[44:47], v[142:145], v[182:185], v[44:47]
	v_mfma_f32_16x16x32_bf16 v[40:43], v[150:153], v[182:185], v[40:43]
	s_waitcnt lgkmcnt(3)
	v_mfma_f32_16x16x32_bf16 v[28:31], v[142:145], v[190:193], v[28:31]
	v_mfma_f32_16x16x32_bf16 v[24:27], v[150:153], v[190:193], v[24:27]
	s_waitcnt lgkmcnt(1)
	v_mfma_f32_16x16x32_bf16 v[12:15], v[142:145], v[198:201], v[12:15]
	v_mfma_f32_16x16x32_bf16 v[8:11], v[150:153], v[198:201], v[8:11]
	v_mfma_f32_16x16x32_bf16 v[60:63], v[146:149], v[178:181], v[60:63]
	v_mfma_f32_16x16x32_bf16 v[56:59], v[154:157], v[178:181], v[56:59]
	v_mfma_f32_16x16x32_bf16 v[44:47], v[146:149], v[186:189], v[44:47]
	v_mfma_f32_16x16x32_bf16 v[40:43], v[154:157], v[186:189], v[40:43]
	v_mfma_f32_16x16x32_bf16 v[28:31], v[146:149], v[194:197], v[28:31]
	v_mfma_f32_16x16x32_bf16 v[24:27], v[154:157], v[194:197], v[24:27]
	s_waitcnt lgkmcnt(0)
	v_mfma_f32_16x16x32_bf16 v[12:15], v[146:149], v[202:205], v[12:15]
	v_mfma_f32_16x16x32_bf16 v[8:11], v[154:157], v[202:205], v[8:11]
	s_setprio 0
	s_setprio 1
	v_mfma_f32_16x16x32_bf16 v[52:55], v[158:161], v[174:177], v[52:55]
	v_mfma_f32_16x16x32_bf16 v[48:51], v[166:169], v[174:177], v[48:51]
	v_mfma_f32_16x16x32_bf16 v[36:39], v[158:161], v[182:185], v[36:39]
	v_mfma_f32_16x16x32_bf16 v[32:35], v[166:169], v[182:185], v[32:35]
	v_mfma_f32_16x16x32_bf16 v[20:23], v[158:161], v[190:193], v[20:23]
	v_mfma_f32_16x16x32_bf16 v[16:19], v[166:169], v[190:193], v[16:19]
	v_mfma_f32_16x16x32_bf16 v[4:7], v[158:161], v[198:201], v[4:7]
	v_mfma_f32_16x16x32_bf16 v[0:3], v[166:169], v[198:201], v[0:3]
	v_mfma_f32_16x16x32_bf16 v[52:55], v[162:165], v[178:181], v[52:55]
	v_mfma_f32_16x16x32_bf16 v[48:51], v[170:173], v[178:181], v[48:51]
	v_mfma_f32_16x16x32_bf16 v[36:39], v[162:165], v[186:189], v[36:39]
	v_mfma_f32_16x16x32_bf16 v[32:35], v[170:173], v[186:189], v[32:35]
	v_mfma_f32_16x16x32_bf16 v[20:23], v[162:165], v[194:197], v[20:23]
	v_mfma_f32_16x16x32_bf16 v[16:19], v[170:173], v[194:197], v[16:19]
	v_mfma_f32_16x16x32_bf16 v[4:7], v[162:165], v[202:205], v[4:7]
	v_mfma_f32_16x16x32_bf16 v[0:3], v[170:173], v[202:205], v[0:3]
	s_setprio 0
	s_add_i32 s20, s20, 2
	s_addk_i32 s1, 0x100
	s_addk_i32 s16, 0x100
	s_cmp_gt_u32 s20, 29
	s_cbranch_scc0 .Lrot_1076
	s_barrier
	s_and_b64 vcc, exec, s[18:19]
	s_cbranch_vccz .LBB0_1079
	s_barrier

; template <class Epi, class Sched, bool ALIGN_EPI = false, bool SP2 = false>
; __device__ __forceinline__ void gemm_phase(PG8_LAS unsigned char* lds, const Gemm g, const Sched& S, const Epi& E, const int wid  ) {
;     ...
;         const bool has_next = S.next(ui + 1, nxt); nxt.same = (has_next && nxt.pm == cur.pm) ? 1 : 0;
;         const unsigned nA = has_next ? (unsigned)g.asel(nxt.pn) * (unsigned)g.a_stride + (unsigned)nxt.pm * tstep : cA, nB = has_next ? (unsigned)nxt.pn * tstep : cB;
;     ...
; #pragma unroll
;         for (int a = 0; a < 2; ++a)
; #pragma unroll
;             for (int b = 0; b < 2; ++b)
; #pragma unroll
;                 for (int m = 0; m < 4; ++m)
; #pragma unroll
;                     for (int n = 0; n < 2; ++n) acc[a][b][m][n] = (f32x4){0.f, 0.f, 0.f, 0.f};
;         cur = nxt; cA = nA; cB = nB; ++ui;
.LBB0_1942:
	s_lshl_b32 s50, s49, 20
	s_and_b64 s[0:1], s[4:5], exec
	s_cselect_b32 s0, s50, s54
	s_lshl_b32 s51, s48, 20
	s_and_b64 s[14:15], s[4:5], exec
	v_mov_b32_e32 v0, 0
	s_cselect_b32 s1, s51, s55
	s_add_i32 s54, s54, 0x80080
	s_addk_i32 s55, 0x100
	s_mov_b32 s58, -2
	s_waitcnt lgkmcnt(0)
	v_mov_b32_e32 v1, v0
	v_mov_b32_e32 v2, v0
	v_mov_b32_e32 v3, v0
	v_mov_b32_e32 v4, v0
	v_mov_b32_e32 v5, v0
	v_mov_b32_e32 v6, v0
	v_mov_b32_e32 v7, v0
	v_mov_b32_e32 v16, v0
	v_mov_b32_e32 v17, v0
	v_mov_b32_e32 v18, v0
	v_mov_b32_e32 v19, v0
	s_waitcnt vmcnt(21)
	v_mov_b32_e32 v20, v0
	v_mov_b32_e32 v21, v0
	v_mov_b32_e32 v22, v0
	v_mov_b32_e32 v23, v0
	v_mov_b32_e32 v32, v0
	v_mov_b32_e32 v33, v0
	v_mov_b32_e32 v34, v0
	v_mov_b32_e32 v35, v0
	v_mov_b32_e32 v36, v0
	v_mov_b32_e32 v37, v0
	v_mov_b32_e32 v38, v0
	v_mov_b32_e32 v39, v0
	v_mov_b32_e32 v48, v0
	v_mov_b32_e32 v49, v0
	s_waitcnt vmcnt(16)
	v_mov_b32_e32 v50, v0
	v_mov_b32_e32 v51, v0
	v_mov_b32_e32 v52, v0
	v_mov_b32_e32 v53, v0
	v_mov_b32_e32 v54, v0
	v_mov_b32_e32 v55, v0
	v_mov_b32_e32 v8, v0
	v_mov_b32_e32 v9, v0
	v_mov_b32_e32 v10, v0
	v_mov_b32_e32 v11, v0
	v_mov_b32_e32 v12, v0
	v_mov_b32_e32 v13, v0
	v_mov_b32_e32 v14, v0
	v_mov_b32_e32 v15, v0
	v_mov_b32_e32 v24, v0
	v_mov_b32_e32 v25, v0
	v_mov_b32_e32 v26, v0
	v_mov_b32_e32 v27, v0
	v_mov_b32_e32 v28, v0
	v_mov_b32_e32 v29, v0
	v_mov_b32_e32 v30, v0
	v_mov_b32_e32 v31, v0
	v_mov_b32_e32 v40, v0
	v_mov_b32_e32 v41, v0
	v_mov_b32_e32 v42, v0
	v_mov_b32_e32 v43, v0
	v_mov_b32_e32 v44, v0
	v_mov_b32_e32 v45, v0
	v_mov_b32_e32 v46, v0
	v_mov_b32_e32 v47, v0
	v_mov_b32_e32 v56, v0
	v_mov_b32_e32 v57, v0
	v_mov_b32_e32 v58, v0
	v_mov_b32_e32 v59, v0
	v_mov_b32_e32 v60, v0
	v_mov_b32_e32 v61, v0
	v_mov_b32_e32 v62, v0
	v_mov_b32_e32 v63, v0
	v_mov_b32_e32 v64, v0
	v_mov_b32_e32 v65, v0
	s_waitcnt vmcnt(15)
	v_mov_b32_e32 v66, v0
	v_mov_b32_e32 v67, v0
	v_mov_b32_e32 v68, v0
	v_mov_b32_e32 v69, v0
	v_mov_b32_e32 v70, v0
	v_mov_b32_e32 v71, v0
	v_mov_b32_e32 v80, v0
	v_mov_b32_e32 v81, v0
	v_mov_b32_e32 v82, v0
	v_mov_b32_e32 v83, v0
	v_mov_b32_e32 v84, v0
	v_mov_b32_e32 v85, v0
	v_mov_b32_e32 v86, v0
	v_mov_b32_e32 v87, v0
	v_mov_b32_e32 v96, v0
	v_mov_b32_e32 v97, v0
	v_mov_b32_e32 v98, v0
	v_mov_b32_e32 v99, v0
	v_mov_b32_e32 v100, v0
	v_mov_b32_e32 v101, v0
	v_mov_b32_e32 v102, v0
	v_mov_b32_e32 v103, v0
	v_mov_b32_e32 v112, v0
	v_mov_b32_e32 v113, v0
	v_mov_b32_e32 v114, v0
	v_mov_b32_e32 v115, v0
	v_mov_b32_e32 v116, v0
	v_mov_b32_e32 v117, v0
	v_mov_b32_e32 v118, v0
	v_mov_b32_e32 v119, v0
	v_mov_b32_e32 v72, v0
	v_mov_b32_e32 v73, v0
	v_mov_b32_e32 v74, v0
	v_mov_b32_e32 v75, v0
	v_mov_b32_e32 v76, v0
	v_mov_b32_e32 v77, v0
	v_mov_b32_e32 v78, v0
	v_mov_b32_e32 v79, v0
	v_mov_b32_e32 v88, v0
	v_mov_b32_e32 v89, v0
	v_mov_b32_e32 v90, v0
	v_mov_b32_e32 v91, v0
	v_mov_b32_e32 v92, v0
	v_mov_b32_e32 v93, v0
	v_mov_b32_e32 v94, v0
	v_mov_b32_e32 v95, v0
	v_mov_b32_e32 v104, v0
	v_mov_b32_e32 v105, v0
	v_mov_b32_e32 v106, v0
	v_mov_b32_e32 v107, v0
	v_mov_b32_e32 v108, v0
	v_mov_b32_e32 v109, v0
	v_mov_b32_e32 v110, v0
	v_mov_b32_e32 v111, v0
	v_mov_b32_e32 v120, v0
	v_mov_b32_e32 v121, v0
	v_mov_b32_e32 v122, v0
	v_mov_b32_e32 v123, v0
	v_mov_b32_e32 v124, v0
	v_mov_b32_e32 v125, v0
	v_mov_b32_e32 v126, v0
	v_mov_b32_e32 v127, v0
	s_branch .LBB0_1943

; template <class Epi, class Sched, bool ALIGN_EPI = false, bool SP2 = false>
; __device__ __forceinline__ void gemm_phase(PG8_LAS unsigned char* lds, const Gemm g, const Sched& S, const Epi& E, const int wid  ) {
;     ...
;         const bool has_next = S.next(ui + 1, nxt); nxt.same = (has_next && nxt.pm == cur.pm) ? 1 : 0;
;         const unsigned nA = has_next ? (unsigned)g.asel(nxt.pn) * (unsigned)g.a_stride + (unsigned)nxt.pm * tstep : cA, nB = has_next ? (unsigned)nxt.pn * tstep : cB;
;     ...
; #pragma unroll
;         for (int a = 0; a < 2; ++a)
; #pragma unroll
;             for (int b = 0; b < 2; ++b)
; #pragma unroll
;                 for (int m = 0; m < 4; ++m)
; #pragma unroll
;                     for (int n = 0; n < 2; ++n) acc[a][b][m][n] = (f32x4){0.f, 0.f, 0.f, 0.f};
;         cur = nxt; cA = nA; cB = nB; ++ui;
.LBB0_2036:
	s_lshl_b32 s90, s89, 20
	s_and_b64 s[6:7], s[4:5], exec
	s_cselect_b32 s6, s90, s48
	s_lshl_b32 s91, s88, 20
	s_and_b64 s[18:19], s[4:5], exec
	v_mov_b32_e32 v56, 0
	s_cselect_b32 s7, s91, s9
	s_add_i32 s8, s48, 0x80080
	s_addk_i32 s9, 0x100
	s_mov_b32 s48, -2
	v_mov_b32_e32 v57, v56
	v_mov_b32_e32 v58, v56
	v_mov_b32_e32 v59, v56
	v_mov_b32_e32 v60, v56
	v_mov_b32_e32 v61, v56
	v_mov_b32_e32 v62, v56
	v_mov_b32_e32 v63, v56
	v_mov_b32_e32 v64, v56
	v_mov_b32_e32 v65, v56
	v_mov_b32_e32 v66, v56
	v_mov_b32_e32 v67, v56
	v_mov_b32_e32 v68, v56
	v_mov_b32_e32 v69, v56
	v_mov_b32_e32 v70, v56
	v_mov_b32_e32 v71, v56
	v_mov_b32_e32 v72, v56
	v_mov_b32_e32 v73, v56
	v_mov_b32_e32 v74, v56
	v_mov_b32_e32 v75, v56
	v_mov_b32_e32 v80, v56
	v_mov_b32_e32 v81, v56
	v_mov_b32_e32 v82, v56
	v_mov_b32_e32 v83, v56
	v_mov_b32_e32 v0, v56
	v_mov_b32_e32 v1, v56
	s_waitcnt lgkmcnt(7)
	v_mov_b32_e32 v2, v56
	v_mov_b32_e32 v3, v56
	s_waitcnt lgkmcnt(6)
	v_mov_b32_e32 v4, v56
	v_mov_b32_e32 v5, v56
	s_waitcnt lgkmcnt(5)
	v_mov_b32_e32 v6, v56
	v_mov_b32_e32 v7, v56
	v_mov_b32_e32 v48, v56
	v_mov_b32_e32 v49, v56
	v_mov_b32_e32 v50, v56
	v_mov_b32_e32 v51, v56
	v_mov_b32_e32 v92, v56
	v_mov_b32_e32 v93, v56
	v_mov_b32_e32 v94, v56
	v_mov_b32_e32 v95, v56
	v_mov_b32_e32 v76, v56
	v_mov_b32_e32 v77, v56
	v_mov_b32_e32 v78, v56
	v_mov_b32_e32 v79, v56
	v_mov_b32_e32 v84, v56
	v_mov_b32_e32 v85, v56
	v_mov_b32_e32 v86, v56
	v_mov_b32_e32 v87, v56
	v_mov_b32_e32 v88, v56
	v_mov_b32_e32 v89, v56
	v_mov_b32_e32 v90, v56
	v_mov_b32_e32 v91, v56
	v_mov_b32_e32 v96, v56
	v_mov_b32_e32 v97, v56
	v_mov_b32_e32 v98, v56
	v_mov_b32_e32 v99, v56
	v_mov_b32_e32 v100, v56
	v_mov_b32_e32 v101, v56
	v_mov_b32_e32 v102, v56
	v_mov_b32_e32 v103, v56
	v_mov_b32_e32 v104, v56
	v_mov_b32_e32 v105, v56
	v_mov_b32_e32 v106, v56
	v_mov_b32_e32 v107, v56
	v_mov_b32_e32 v108, v56
	v_mov_b32_e32 v109, v56
	v_mov_b32_e32 v110, v56
	v_mov_b32_e32 v111, v56
	v_mov_b32_e32 v112, v56
	v_mov_b32_e32 v113, v56
	v_mov_b32_e32 v114, v56
	v_mov_b32_e32 v115, v56
	v_mov_b32_e32 v116, v56
	v_mov_b32_e32 v117, v56
	v_mov_b32_e32 v118, v56
	v_mov_b32_e32 v119, v56
	v_mov_b32_e32 v124, v56
	v_mov_b32_e32 v125, v56
	v_mov_b32_e32 v126, v56
	v_mov_b32_e32 v127, v56
	v_mov_b32_e32 v128, v56
	v_mov_b32_e32 v129, v56
	v_mov_b32_e32 v130, v56
	v_mov_b32_e32 v131, v56
	v_mov_b32_e32 v136, v56
	v_mov_b32_e32 v137, v56
	v_mov_b32_e32 v138, v56
	v_mov_b32_e32 v139, v56
	s_waitcnt lgkmcnt(4)
	v_mov_b32_e32 v8, v56
	v_mov_b32_e32 v9, v56
	s_waitcnt lgkmcnt(3)
	v_mov_b32_e32 v10, v56
	v_mov_b32_e32 v11, v56
	s_waitcnt lgkmcnt(2)
	v_mov_b32_e32 v12, v56
	v_mov_b32_e32 v13, v56
	s_waitcnt lgkmcnt(1)
	v_mov_b32_e32 v14, v56
	v_mov_b32_e32 v15, v56
	v_mov_b32_e32 v120, v56
	v_mov_b32_e32 v121, v56
	v_mov_b32_e32 v122, v56
	v_mov_b32_e32 v123, v56
	v_mov_b32_e32 v156, v56
	v_mov_b32_e32 v157, v56
	v_mov_b32_e32 v158, v56
	v_mov_b32_e32 v159, v56
	v_mov_b32_e32 v132, v56
	v_mov_b32_e32 v133, v56
	v_mov_b32_e32 v134, v56
	v_mov_b32_e32 v135, v56
	v_mov_b32_e32 v140, v56
	v_mov_b32_e32 v141, v56
	v_mov_b32_e32 v142, v56
	v_mov_b32_e32 v143, v56
	v_mov_b32_e32 v144, v56
	v_mov_b32_e32 v145, v56
	v_mov_b32_e32 v146, v56
	v_mov_b32_e32 v147, v56
	v_mov_b32_e32 v148, v56
	v_mov_b32_e32 v149, v56
	v_mov_b32_e32 v150, v56
	v_mov_b32_e32 v151, v56
	v_mov_b32_e32 v52, v56
	v_mov_b32_e32 v53, v56
	v_mov_b32_e32 v54, v56
	v_mov_b32_e32 v55, v56
	v_mov_b32_e32 v152, v56
	v_mov_b32_e32 v153, v56
	v_mov_b32_e32 v154, v56
	v_mov_b32_e32 v155, v56
	s_branch .LBB0_2037

; #define PG8_STAGE(bufoff, soff, voff) do { _Pragma("unroll") for (int _i = 0; _i < 2; ++_i) \
;         __builtin_amdgcn_raw_ptr_buffer_load_lds(rs_##voff, (PG8_LAS unsigned*)(lds + (bufoff) + ldsw + _i * 8192), 16, (int)(voff)[_i], (int)(soff), 0, 0); } while (0)
; #define PG8_LDA(dst, b, h) do { _Pragma("unroll") for (int m = 0; m < 4; ++m) _Pragma("unroll") for (int k = 0; k < 2; ++k) dst[m][k] = *(const PG8_LAS bf16x8*)(lds + PG8_SA(b, h) + aoff + m * 2048 + k * 1024); } while (0)
; #define PG8_LDB(dst, b, h) do { _Pragma("unroll") for (int n = 0; n < 2; ++n) _Pragma("unroll") for (int k = 0; k < 2; ++k) dst[n][k] = *(const PG8_LAS bf16x8*)(lds + PG8_SB(b, h) + boff + n * 2048 + k * 1024); } while (0)
; #define PG8_MMA(ai, bj, At, Bt) do { __builtin_amdgcn_s_setprio(1); _Pragma("unroll") for (int m = 0; m < 4; ++m) _Pragma("unroll") for (int n = 0; n < 2; ++n) _Pragma("unroll") for (int k = 0; k < 2; ++k) \
;         acc[ai][bj][m][n] = __builtin_amdgcn_mfma_f32_16x16x32_bf16(Bt[n][k], At[m][k], acc[ai][bj][m][n], 0, 0, 0); __builtin_amdgcn_s_setprio(0); } while (0)
; #define PG8_WAIT_V(n) asm volatile("s_waitcnt vmcnt(" #n ")" ::: "memory")
; #define PG8_BAR __builtin_amdgcn_s_barrier()
; template <class Epi, class Sched, bool ALIGN_EPI = false, bool SP2 = false>
; __device__ __forceinline__ void gemm_phase(PG8_LAS unsigned char* lds, const Gemm g, const Sched& S, const Epi& E, const int wid  ) {
;     ...
;         for (int t = 0; t < nt; t += 2) {
;             const bool last = (t == nt - 2);
;             const unsigned a1 = cA + (unsigned)(t + 1) * kstep;
;             const unsigned a2 = last ? nA : cA + (unsigned)(t + 2) * kstep, b2 = last ? nB : cB + (unsigned)(t + 2) * kstep;
;             const unsigned a3 = a2 + kstep, b3 = b2 + kstep;
;             if (last && has_next) S.a_ready(nxt);
;             if constexpr (SP2) {
;             PG8_LDB(B0, 0, 0); PG8_LDB(B1, 0, 1); PG8_SCHED; PG8_LDA(At, 0, 0); PG8_STAGE(PG8_SA(1, 1), a1 + hstep, voffA);
;             PG8_WAIT_V(8); PG8_WAIT_L(0); PG8_BAR; PG8_MMA(0, 0, At, B0); PG8_MMA(0, 1, At, B1); PG8_BAR; PG8_SCHED;
;             PG8_LDA(At, 0, 1); PG8_STAGE(PG8_SB(0, 0), b2, voffB); PG8_STAGE(PG8_SB(0, 1), b2 + hstep, voffB); PG8_STAGE(PG8_SA(0, 0), a2, voffA);
;             PG8_WAIT_V(8); PG8_WAIT_L(0); PG8_BAR; PG8_MMA(1, 0, At, B0); PG8_MMA(1, 1, At, B1); PG8_BAR; PG8_SCHED;
.LBB0_2037:
	s_waitcnt lgkmcnt(0)
	ds_read_b128 v[16:19], v188
	ds_read_b128 v[20:23], v188 offset:1024
	ds_read_b128 v[24:27], v188 offset:2048
	ds_read_b128 v[28:31], v188 offset:3072
	ds_read_b128 v[32:35], v189
	ds_read_b128 v[36:39], v189 offset:1024
	ds_read_b128 v[40:43], v189 offset:2048
	ds_read_b128 v[44:47], v189 offset:3072
	s_add_i32 s18, s8, 0xfff80080
	s_cmp_eq_u32 s48, 28
	s_cselect_b32 s93, s6, s18
	s_cselect_b32 s92, s7, s9
	s_or_b32 s49, s93, 0x80
	s_mov_b32 m0, s74
	ds_read_b128 v[160:163], v190
	ds_read_b128 v[170:173], v190 offset:1024
	ds_read_b128 v[174:177], v190 offset:2048
	ds_read_b128 v[178:181], v190 offset:3072
	ds_read_b128 v[194:197], v190 offset:4096
	ds_read_b128 v[198:201], v190 offset:5120
	ds_read_b128 v[202:205], v190 offset:6144
	ds_read_b128 v[206:209], v190 offset:7168
	buffer_load_dwordx4 v182, s[12:15], s8 offen lds
	s_mov_b32 m0, s76
	s_nop 0
	buffer_load_dwordx4 v184, s[12:15], s8 offen lds
	s_waitcnt vmcnt(8)
	s_waitcnt lgkmcnt(0)
	s_barrier
	s_setprio 1
	s_waitcnt lgkmcnt(7)
	v_mfma_f32_16x16x32_bf16 v[152:155], v[16:19], v[160:163], v[152:155]
	v_mfma_f32_16x16x32_bf16 v[52:55], v[24:27], v[160:163], v[52:55]
	s_waitcnt lgkmcnt(5)
	v_mfma_f32_16x16x32_bf16 v[148:151], v[16:19], v[174:177], v[148:151]
	v_mfma_f32_16x16x32_bf16 v[144:147], v[24:27], v[174:177], v[144:147]
	s_waitcnt lgkmcnt(3)
	v_mfma_f32_16x16x32_bf16 v[140:143], v[16:19], v[194:197], v[140:143]
	v_mfma_f32_16x16x32_bf16 v[132:135], v[24:27], v[194:197], v[132:135]
	s_waitcnt lgkmcnt(1)
	v_mfma_f32_16x16x32_bf16 v[156:159], v[16:19], v[202:205], v[156:159]
	v_mfma_f32_16x16x32_bf16 v[120:123], v[24:27], v[202:205], v[120:123]
	v_mfma_f32_16x16x32_bf16 v[152:155], v[20:23], v[170:173], v[152:155]
	v_mfma_f32_16x16x32_bf16 v[52:55], v[28:31], v[170:173], v[52:55]
	v_mfma_f32_16x16x32_bf16 v[148:151], v[20:23], v[178:181], v[148:151]
	v_mfma_f32_16x16x32_bf16 v[144:147], v[28:31], v[178:181], v[144:147]
	v_mfma_f32_16x16x32_bf16 v[140:143], v[20:23], v[198:201], v[140:143]
	v_mfma_f32_16x16x32_bf16 v[132:135], v[28:31], v[198:201], v[132:135]
	s_waitcnt lgkmcnt(0)
	v_mfma_f32_16x16x32_bf16 v[156:159], v[20:23], v[206:209], v[156:159]
	v_mfma_f32_16x16x32_bf16 v[120:123], v[28:31], v[206:209], v[120:123]
	s_setprio 0
	s_setprio 1
	v_mfma_f32_16x16x32_bf16 v[12:15], v[32:35], v[160:163], v[12:15]
	v_mfma_f32_16x16x32_bf16 v[8:11], v[40:43], v[160:163], v[8:11]
	v_mfma_f32_16x16x32_bf16 v[136:139], v[32:35], v[174:177], v[136:139]
	v_mfma_f32_16x16x32_bf16 v[128:131], v[40:43], v[174:177], v[128:131]
	v_mfma_f32_16x16x32_bf16 v[124:127], v[32:35], v[194:197], v[124:127]
	v_mfma_f32_16x16x32_bf16 v[116:119], v[40:43], v[194:197], v[116:119]
	v_mfma_f32_16x16x32_bf16 v[112:115], v[32:35], v[202:205], v[112:115]
	v_mfma_f32_16x16x32_bf16 v[108:111], v[40:43], v[202:205], v[108:111]
	v_mfma_f32_16x16x32_bf16 v[12:15], v[36:39], v[170:173], v[12:15]
	v_mfma_f32_16x16x32_bf16 v[8:11], v[44:47], v[170:173], v[8:11]
	v_mfma_f32_16x16x32_bf16 v[136:139], v[36:39], v[178:181], v[136:139]
	v_mfma_f32_16x16x32_bf16 v[128:131], v[44:47], v[178:181], v[128:131]
	v_mfma_f32_16x16x32_bf16 v[124:127], v[36:39], v[198:201], v[124:127]
	v_mfma_f32_16x16x32_bf16 v[116:119], v[44:47], v[198:201], v[116:119]
	v_mfma_f32_16x16x32_bf16 v[112:115], v[36:39], v[206:209], v[112:115]
	v_mfma_f32_16x16x32_bf16 v[108:111], v[44:47], v[206:209], v[108:111]
	s_setprio 0
	s_barrier
	s_mov_b32 m0, s34
	s_mov_b32 s18, s14
	s_mov_b32 s19, s15
	ds_read_b128 v[160:163], v190 offset:16384
	ds_read_b128 v[170:173], v190 offset:17408
	ds_read_b128 v[174:177], v190 offset:18432
	ds_read_b128 v[178:181], v190 offset:19456
	ds_read_b128 v[194:197], v190 offset:20480
	ds_read_b128 v[198:201], v190 offset:21504
	ds_read_b128 v[202:205], v190 offset:22528
	ds_read_b128 v[206:209], v190 offset:23552
	buffer_load_dwordx4 v183, s[16:19], s92 offen lds
	s_mov_b32 m0, s35
	s_add_i32 s94, s92, 0x80000
	buffer_load_dwordx4 v185, s[16:19], s92 offen lds
	s_mov_b32 m0, s50
	s_nop 0
	buffer_load_dwordx4 v183, s[16:19], s94 offen lds
	s_mov_b32 m0, s51
	s_nop 0
	buffer_load_dwordx4 v185, s[16:19], s94 offen lds
	s_mov_b32 m0, s33
	s_nop 0
	buffer_load_dwordx4 v182, s[12:15], s93 offen lds
	s_mov_b32 m0, s53
	s_nop 0
	buffer_load_dwordx4 v184, s[12:15], s93 offen lds
	s_waitcnt vmcnt(8)
	s_waitcnt lgkmcnt(0)
	s_barrier
	s_setprio 1
	s_waitcnt lgkmcnt(7)
	v_mfma_f32_16x16x32_bf16 v[104:107], v[16:19], v[160:163], v[104:107]
	v_mfma_f32_16x16x32_bf16 v[100:103], v[24:27], v[160:163], v[100:103]
	s_waitcnt lgkmcnt(5)
	v_mfma_f32_16x16x32_bf16 v[96:99], v[16:19], v[174:177], v[96:99]
	v_mfma_f32_16x16x32_bf16 v[88:91], v[24:27], v[174:177], v[88:91]
	s_waitcnt lgkmcnt(3)
	v_mfma_f32_16x16x32_bf16 v[84:87], v[16:19], v[194:197], v[84:87]
	v_mfma_f32_16x16x32_bf16 v[76:79], v[24:27], v[194:197], v[76:79]
	s_waitcnt lgkmcnt(1)
	v_mfma_f32_16x16x32_bf16 v[16:19], v[16:19], v[202:205], v[92:95]
	v_mfma_f32_16x16x32_bf16 v[104:107], v[20:23], v[170:173], v[104:107]
	v_mfma_f32_16x16x32_bf16 v[100:103], v[28:31], v[170:173], v[100:103]
	v_mfma_f32_16x16x32_bf16 v[96:99], v[20:23], v[178:181], v[96:99]
	v_mfma_f32_16x16x32_bf16 v[88:91], v[28:31], v[178:181], v[88:91]
	v_mfma_f32_16x16x32_bf16 v[84:87], v[20:23], v[198:201], v[84:87]
	v_mfma_f32_16x16x32_bf16 v[76:79], v[28:31], v[198:201], v[76:79]
	s_waitcnt lgkmcnt(0)
	v_mfma_f32_16x16x32_bf16 v[16:19], v[20:23], v[206:209], v[16:19]
	v_mfma_f32_16x16x32_bf16 v[20:23], v[24:27], v[202:205], v[48:51]
	v_mfma_f32_16x16x32_bf16 v[20:23], v[28:31], v[206:209], v[20:23]
	s_setprio 0
	s_setprio 1
	v_mfma_f32_16x16x32_bf16 v[48:51], v[32:35], v[194:197], v[68:71]
	v_mfma_f32_16x16x32_bf16 v[4:7], v[32:35], v[160:163], v[4:7]
	v_mfma_f32_16x16x32_bf16 v[0:3], v[40:43], v[160:163], v[0:3]
	v_mfma_f32_16x16x32_bf16 v[24:27], v[32:35], v[174:177], v[80:83]
	v_mfma_f32_16x16x32_bf16 v[68:71], v[36:39], v[198:201], v[48:51]
	v_mfma_f32_16x16x32_bf16 v[48:51], v[40:43], v[194:197], v[64:67]
	v_mfma_f32_16x16x32_bf16 v[32:35], v[32:35], v[202:205], v[60:63]
	v_mfma_f32_16x16x32_bf16 v[4:7], v[36:39], v[170:173], v[4:7]
	v_mfma_f32_16x16x32_bf16 v[0:3], v[44:47], v[170:173], v[0:3]
	v_mfma_f32_16x16x32_bf16 v[24:27], v[36:39], v[178:181], v[24:27]
	v_mfma_f32_16x16x32_bf16 v[28:31], v[40:43], v[174:177], v[72:75]
	v_mfma_f32_16x16x32_bf16 v[64:67], v[44:47], v[198:201], v[48:51]
	v_mfma_f32_16x16x32_bf16 v[32:35], v[36:39], v[206:209], v[32:35]
	v_mfma_f32_16x16x32_bf16 v[36:39], v[40:43], v[202:205], v[56:59]
	v_mfma_f32_16x16x32_bf16 v[28:31], v[44:47], v[178:181], v[28:31]
	v_mfma_f32_16x16x32_bf16 v[36:39], v[44:47], v[206:209], v[36:39]
	s_setprio 0
	s_barrier
; #define PG8_STAGE(bufoff, soff, voff) do { _Pragma("unroll") for (int _i = 0; _i < 2; ++_i) \
;         __builtin_amdgcn_raw_ptr_buffer_load_lds(rs_##voff, (PG8_LAS unsigned*)(lds + (bufoff) + ldsw + _i * 8192), 16, (int)(voff)[_i], (int)(soff), 0, 0); } while (0)
; #define PG8_LDA(dst, b, h) do { _Pragma("unroll") for (int m = 0; m < 4; ++m) _Pragma("unroll") for (int k = 0; k < 2; ++k) dst[m][k] = *(const PG8_LAS bf16x8*)(lds + PG8_SA(b, h) + aoff + m * 2048 + k * 1024); } while (0)
; #define PG8_LDB(dst, b, h) do { _Pragma("unroll") for (int n = 0; n < 2; ++n) _Pragma("unroll") for (int k = 0; k < 2; ++k) dst[n][k] = *(const PG8_LAS bf16x8*)(lds + PG8_SB(b, h) + boff + n * 2048 + k * 1024); } while (0)
; #define PG8_MMA(ai, bj, At, Bt) do { __builtin_amdgcn_s_setprio(1); _Pragma("unroll") for (int m = 0; m < 4; ++m) _Pragma("unroll") for (int n = 0; n < 2; ++n) _Pragma("unroll") for (int k = 0; k < 2; ++k) \
;         acc[ai][bj][m][n] = __builtin_amdgcn_mfma_f32_16x16x32_bf16(Bt[n][k], At[m][k], acc[ai][bj][m][n], 0, 0, 0); __builtin_amdgcn_s_setprio(0); } while (0)
; #define PG8_WAIT_V(n) asm volatile("s_waitcnt vmcnt(" #n ")" ::: "memory")
; #define PG8_WAIT_L(n) asm volatile("s_waitcnt lgkmcnt(" #n ")" ::: "memory")
; #define PG8_BAR __builtin_amdgcn_s_barrier()
; #define PG8_SCHED __builtin_amdgcn_sched_barrier(0)
; template <class Epi, class Sched, bool ALIGN_EPI = false, bool SP2 = false>
; __device__ __forceinline__ void gemm_phase(PG8_LAS unsigned char* lds, const Gemm g, const Sched& S, const Epi& E, const int wid  ) {
;     ...
;             PG8_LDB(B0, 1, 0); PG8_LDB(B1, 1, 1); PG8_SCHED; PG8_LDA(At, 1, 0); PG8_STAGE(PG8_SA(0, 1), a2 + hstep, voffA);
;             PG8_WAIT_V(8); PG8_WAIT_L(0); PG8_BAR; PG8_MMA(0, 0, At, B0); PG8_MMA(0, 1, At, B1); PG8_BAR; PG8_SCHED;
;             PG8_LDA(At, 1, 1); PG8_STAGE(PG8_SB(1, 0), b3, voffB); PG8_STAGE(PG8_SB(1, 1), b3 + hstep, voffB); PG8_STAGE(PG8_SA(1, 0), a3, voffA);
;             PG8_WAIT_V(8); PG8_WAIT_L(0); PG8_BAR; PG8_MMA(1, 0, At, B0); PG8_MMA(1, 1, At, B1); PG8_BAR; PG8_SCHED;
;     ...
;         if constexpr (ALIGN_EPI) { if (wr == 0) PG8_BAR; }
	ds_read_b128 v[40:43], v191
	ds_read_b128 v[44:47], v191 offset:1024
	ds_read_b128 v[48:51], v191 offset:2048
	ds_read_b128 v[56:59], v191 offset:3072
	ds_read_b128 v[60:63], v192
	ds_read_b128 v[160:163], v192 offset:1024
	ds_read_b128 v[170:173], v192 offset:2048
	ds_read_b128 v[174:177], v192 offset:3072
	s_add_i32 s93, s93, 0x80000
	s_mov_b32 m0, s54
	ds_read_b128 v[72:75], v190 offset:32768
	ds_read_b128 v[80:83], v190 offset:33792
	ds_read_b128 v[92:95], v190 offset:34816
	ds_read_b128 v[178:181], v190 offset:35840
	ds_read_b128 v[194:197], v190 offset:36864
	ds_read_b128 v[198:201], v190 offset:37888
	ds_read_b128 v[202:205], v190 offset:38912
	ds_read_b128 v[206:209], v190 offset:39936
	buffer_load_dwordx4 v182, s[12:15], s93 offen lds
	s_mov_b32 m0, s58
	s_nop 0
	buffer_load_dwordx4 v184, s[12:15], s93 offen lds
	s_waitcnt vmcnt(8)
	s_waitcnt lgkmcnt(0)
	s_barrier
	s_setprio 1
	s_waitcnt lgkmcnt(7)
	v_mfma_f32_16x16x32_bf16 v[152:155], v[40:43], v[72:75], v[152:155]
	v_mfma_f32_16x16x32_bf16 v[52:55], v[48:51], v[72:75], v[52:55]
	s_waitcnt lgkmcnt(5)
	v_mfma_f32_16x16x32_bf16 v[148:151], v[40:43], v[92:95], v[148:151]
	v_mfma_f32_16x16x32_bf16 v[144:147], v[48:51], v[92:95], v[144:147]
	s_waitcnt lgkmcnt(3)
	v_mfma_f32_16x16x32_bf16 v[140:143], v[40:43], v[194:197], v[140:143]
	v_mfma_f32_16x16x32_bf16 v[132:135], v[48:51], v[194:197], v[132:135]
	s_waitcnt lgkmcnt(1)
	v_mfma_f32_16x16x32_bf16 v[156:159], v[40:43], v[202:205], v[156:159]
	v_mfma_f32_16x16x32_bf16 v[120:123], v[48:51], v[202:205], v[120:123]
	v_mfma_f32_16x16x32_bf16 v[152:155], v[44:47], v[80:83], v[152:155]
	v_mfma_f32_16x16x32_bf16 v[52:55], v[56:59], v[80:83], v[52:55]
	v_mfma_f32_16x16x32_bf16 v[148:151], v[44:47], v[178:181], v[148:151]
	v_mfma_f32_16x16x32_bf16 v[144:147], v[56:59], v[178:181], v[144:147]
	v_mfma_f32_16x16x32_bf16 v[140:143], v[44:47], v[198:201], v[140:143]
	v_mfma_f32_16x16x32_bf16 v[132:135], v[56:59], v[198:201], v[132:135]
	s_waitcnt lgkmcnt(0)
	v_mfma_f32_16x16x32_bf16 v[156:159], v[44:47], v[206:209], v[156:159]
	v_mfma_f32_16x16x32_bf16 v[120:123], v[56:59], v[206:209], v[120:123]
	s_setprio 0
	s_setprio 1
	v_mfma_f32_16x16x32_bf16 v[12:15], v[60:63], v[72:75], v[12:15]
	v_mfma_f32_16x16x32_bf16 v[8:11], v[170:173], v[72:75], v[8:11]
	v_mfma_f32_16x16x32_bf16 v[72:75], v[60:63], v[92:95], v[136:139]
	v_mfma_f32_16x16x32_bf16 v[136:139], v[160:163], v[178:181], v[72:75]
	v_mfma_f32_16x16x32_bf16 v[72:75], v[170:173], v[92:95], v[128:131]
	v_mfma_f32_16x16x32_bf16 v[128:131], v[174:177], v[178:181], v[72:75]
	v_mfma_f32_16x16x32_bf16 v[72:75], v[60:63], v[194:197], v[124:127]
	v_mfma_f32_16x16x32_bf16 v[124:127], v[160:163], v[198:201], v[72:75]
	v_mfma_f32_16x16x32_bf16 v[72:75], v[170:173], v[194:197], v[116:119]
	v_mfma_f32_16x16x32_bf16 v[116:119], v[174:177], v[198:201], v[72:75]
	v_mfma_f32_16x16x32_bf16 v[72:75], v[60:63], v[202:205], v[112:115]
	v_mfma_f32_16x16x32_bf16 v[112:115], v[160:163], v[206:209], v[72:75]
	v_mfma_f32_16x16x32_bf16 v[72:75], v[170:173], v[202:205], v[108:111]
	v_mfma_f32_16x16x32_bf16 v[12:15], v[160:163], v[80:83], v[12:15]
	v_mfma_f32_16x16x32_bf16 v[8:11], v[174:177], v[80:83], v[8:11]
	v_mfma_f32_16x16x32_bf16 v[108:111], v[174:177], v[206:209], v[72:75]
	s_setprio 0
	s_barrier
	s_mov_b32 m0, s63
	s_or_b32 s93, s92, 0x80
	s_nop 0
	ds_read_b128 v[72:75], v190 offset:49152
	ds_read_b128 v[80:83], v190 offset:50176
	ds_read_b128 v[178:181], v190 offset:51200
	ds_read_b128 v[194:197], v190 offset:52224
	ds_read_b128 v[198:201], v190 offset:53248
	ds_read_b128 v[202:205], v190 offset:54272
	ds_read_b128 v[206:209], v190 offset:55296
	ds_read_b128 v[210:213], v190 offset:56320
	buffer_load_dwordx4 v183, s[16:19], s93 offen lds
	s_mov_b32 m0, s65
	s_add_i32 s92, s92, 0x80080
	buffer_load_dwordx4 v185, s[16:19], s93 offen lds
	s_mov_b32 m0, s68
	s_nop 0
	buffer_load_dwordx4 v183, s[16:19], s92 offen lds
	s_mov_b32 m0, s69
	s_nop 0
	buffer_load_dwordx4 v185, s[16:19], s92 offen lds
	s_mov_b32 m0, s66
	s_nop 0
	buffer_load_dwordx4 v182, s[12:15], s49 offen lds
	s_mov_b32 m0, s67
	s_nop 0
	buffer_load_dwordx4 v184, s[12:15], s49 offen lds
	s_waitcnt vmcnt(8)
	s_waitcnt lgkmcnt(0)
	s_barrier
	s_setprio 1
	s_waitcnt lgkmcnt(7)
	v_mfma_f32_16x16x32_bf16 v[92:95], v[40:43], v[72:75], v[104:107]
	s_waitcnt lgkmcnt(6)
	v_mfma_f32_16x16x32_bf16 v[104:107], v[44:47], v[80:83], v[92:95]
	v_mfma_f32_16x16x32_bf16 v[92:95], v[48:51], v[72:75], v[100:103]
	v_mfma_f32_16x16x32_bf16 v[100:103], v[56:59], v[80:83], v[92:95]
	s_waitcnt lgkmcnt(5)
	v_mfma_f32_16x16x32_bf16 v[92:95], v[40:43], v[178:181], v[96:99]
	s_waitcnt lgkmcnt(1)
	v_mfma_f32_16x16x32_bf16 v[16:19], v[40:43], v[206:209], v[16:19]
	v_mfma_f32_16x16x32_bf16 v[96:99], v[44:47], v[194:197], v[92:95]
	v_mfma_f32_16x16x32_bf16 v[88:91], v[48:51], v[178:181], v[88:91]
	v_mfma_f32_16x16x32_bf16 v[84:87], v[40:43], v[198:201], v[84:87]
	v_mfma_f32_16x16x32_bf16 v[76:79], v[48:51], v[198:201], v[76:79]
	s_waitcnt lgkmcnt(0)
	v_mfma_f32_16x16x32_bf16 v[92:95], v[44:47], v[210:213], v[16:19]
	v_mfma_f32_16x16x32_bf16 v[16:19], v[48:51], v[206:209], v[20:23]
	v_mfma_f32_16x16x32_bf16 v[88:91], v[56:59], v[194:197], v[88:91]
	v_mfma_f32_16x16x32_bf16 v[84:87], v[44:47], v[202:205], v[84:87]
	v_mfma_f32_16x16x32_bf16 v[76:79], v[56:59], v[202:205], v[76:79]
	v_mfma_f32_16x16x32_bf16 v[48:51], v[56:59], v[210:213], v[16:19]
	s_setprio 0
	s_setprio 1
	v_mfma_f32_16x16x32_bf16 v[4:7], v[60:63], v[72:75], v[4:7]
	v_mfma_f32_16x16x32_bf16 v[0:3], v[170:173], v[72:75], v[0:3]
	v_mfma_f32_16x16x32_bf16 v[16:19], v[60:63], v[178:181], v[24:27]
	v_mfma_f32_16x16x32_bf16 v[4:7], v[160:163], v[80:83], v[4:7]
	v_mfma_f32_16x16x32_bf16 v[0:3], v[174:177], v[80:83], v[0:3]
	v_mfma_f32_16x16x32_bf16 v[80:83], v[160:163], v[194:197], v[16:19]
	v_mfma_f32_16x16x32_bf16 v[16:19], v[170:173], v[178:181], v[28:31]
	v_mfma_f32_16x16x32_bf16 v[72:75], v[174:177], v[194:197], v[16:19]
	v_mfma_f32_16x16x32_bf16 v[16:19], v[60:63], v[198:201], v[68:71]
	v_mfma_f32_16x16x32_bf16 v[68:71], v[160:163], v[202:205], v[16:19]
	v_mfma_f32_16x16x32_bf16 v[16:19], v[170:173], v[198:201], v[64:67]
	v_mfma_f32_16x16x32_bf16 v[64:67], v[174:177], v[202:205], v[16:19]
	v_mfma_f32_16x16x32_bf16 v[16:19], v[60:63], v[206:209], v[32:35]
	v_mfma_f32_16x16x32_bf16 v[60:63], v[160:163], v[210:213], v[16:19]
	v_mfma_f32_16x16x32_bf16 v[16:19], v[170:173], v[206:209], v[36:39]
	v_mfma_f32_16x16x32_bf16 v[56:59], v[174:177], v[210:213], v[16:19]
	s_setprio 0
	s_add_i32 s48, s48, 2
	s_addk_i32 s8, 0x100
	s_addk_i32 s9, 0x100
	s_cmp_gt_u32 s48, 29
	s_cbranch_scc0 .Lrot_2037
	s_barrier
	s_and_b64 vcc, exec, s[28:29]
	s_cbranch_vccz .LBB0_2040
	s_barrier

; template <class Epi, class Sched, bool ALIGN_EPI = false, bool SP2 = false>
; __device__ __forceinline__ void gemm_phase(PG8_LAS unsigned char* lds, const Gemm g, const Sched& S, const Epi& E, const int wid  ) {
;     ...
;         const bool has_next = S.next(ui + 1, nxt); nxt.same = (has_next && nxt.pm == cur.pm) ? 1 : 0;
;         const unsigned nA = has_next ? (unsigned)g.asel(nxt.pn) * (unsigned)g.a_stride + (unsigned)nxt.pm * tstep : cA, nB = has_next ? (unsigned)nxt.pn * tstep : cB;
;     ...
; #pragma unroll
;         for (int a = 0; a < 2; ++a)
; #pragma unroll
;             for (int b = 0; b < 2; ++b)
; #pragma unroll
;                 for (int m = 0; m < 4; ++m)
; #pragma unroll
;                     for (int n = 0; n < 2; ++n) acc[a][b][m][n] = (f32x4){0.f, 0.f, 0.f, 0.f};
;         cur = nxt; cA = nA; cB = nB; ++ui;
.LBB0_2379:
	s_mul_i32 s50, s49, 0x2c0000
	s_and_b64 s[0:1], s[4:5], exec
	s_mul_i32 s51, s48, 0x2c0000
	v_mov_b32_e32 v0, 0
	s_cselect_b32 s0, s50, s16
	s_cselect_b32 s1, s51, s55
	s_add_i32 s16, s16, 0x160080
	s_addk_i32 s55, 0x100
	s_mov_b32 s58, -2
	s_waitcnt lgkmcnt(0)
	v_mov_b32_e32 v1, v0
	v_mov_b32_e32 v2, v0
	v_mov_b32_e32 v3, v0
	v_mov_b32_e32 v4, v0
	v_mov_b32_e32 v5, v0
	v_mov_b32_e32 v6, v0
	v_mov_b32_e32 v7, v0
	v_mov_b32_e32 v16, v0
	v_mov_b32_e32 v17, v0
	v_mov_b32_e32 v18, v0
	v_mov_b32_e32 v19, v0
	v_mov_b32_e32 v20, v0
	v_mov_b32_e32 v21, v0
	v_mov_b32_e32 v22, v0
	v_mov_b32_e32 v23, v0
	v_mov_b32_e32 v32, v0
	v_mov_b32_e32 v33, v0
	v_mov_b32_e32 v34, v0
	v_mov_b32_e32 v35, v0
	v_mov_b32_e32 v36, v0
	v_mov_b32_e32 v37, v0
	v_mov_b32_e32 v38, v0
	v_mov_b32_e32 v39, v0
	v_mov_b32_e32 v48, v0
	v_mov_b32_e32 v49, v0
	v_mov_b32_e32 v50, v0
	v_mov_b32_e32 v51, v0
	v_mov_b32_e32 v52, v0
	v_mov_b32_e32 v53, v0
	v_mov_b32_e32 v54, v0
	v_mov_b32_e32 v55, v0
	v_mov_b32_e32 v8, v0
	v_mov_b32_e32 v9, v0
	v_mov_b32_e32 v10, v0
	v_mov_b32_e32 v11, v0
	v_mov_b32_e32 v12, v0
	v_mov_b32_e32 v13, v0
	v_mov_b32_e32 v14, v0
	v_mov_b32_e32 v15, v0
	v_mov_b32_e32 v24, v0
	v_mov_b32_e32 v25, v0
	v_mov_b32_e32 v26, v0
	v_mov_b32_e32 v27, v0
	v_mov_b32_e32 v28, v0
	v_mov_b32_e32 v29, v0
	v_mov_b32_e32 v30, v0
	v_mov_b32_e32 v31, v0
	v_mov_b32_e32 v40, v0
	v_mov_b32_e32 v41, v0
	v_mov_b32_e32 v42, v0
	v_mov_b32_e32 v43, v0
	v_mov_b32_e32 v44, v0
	v_mov_b32_e32 v45, v0
	v_mov_b32_e32 v46, v0
	v_mov_b32_e32 v47, v0
	v_mov_b32_e32 v56, v0
	v_mov_b32_e32 v57, v0
	v_mov_b32_e32 v58, v0
	v_mov_b32_e32 v59, v0
	v_mov_b32_e32 v60, v0
	v_mov_b32_e32 v61, v0
	v_mov_b32_e32 v62, v0
	v_mov_b32_e32 v63, v0
	v_mov_b32_e32 v64, v0
	v_mov_b32_e32 v65, v0
	s_waitcnt vmcnt(15)
	v_mov_b32_e32 v66, v0
	v_mov_b32_e32 v67, v0
	v_mov_b32_e32 v68, v0
	v_mov_b32_e32 v69, v0
	v_mov_b32_e32 v70, v0
	v_mov_b32_e32 v71, v0
	v_mov_b32_e32 v80, v0
	v_mov_b32_e32 v81, v0
	v_mov_b32_e32 v82, v0
	v_mov_b32_e32 v83, v0
	v_mov_b32_e32 v84, v0
	v_mov_b32_e32 v85, v0
	v_mov_b32_e32 v86, v0
	v_mov_b32_e32 v87, v0
	v_mov_b32_e32 v96, v0
	v_mov_b32_e32 v97, v0
	v_mov_b32_e32 v98, v0
	v_mov_b32_e32 v99, v0
	v_mov_b32_e32 v100, v0
	v_mov_b32_e32 v101, v0
	v_mov_b32_e32 v102, v0
	v_mov_b32_e32 v103, v0
	v_mov_b32_e32 v112, v0
	v_mov_b32_e32 v113, v0
	v_mov_b32_e32 v114, v0
	v_mov_b32_e32 v115, v0
	v_mov_b32_e32 v116, v0
	v_mov_b32_e32 v117, v0
	v_mov_b32_e32 v118, v0
	v_mov_b32_e32 v119, v0
	v_mov_b32_e32 v72, v0
	v_mov_b32_e32 v73, v0
	v_mov_b32_e32 v74, v0
	v_mov_b32_e32 v75, v0
	v_mov_b32_e32 v76, v0
	v_mov_b32_e32 v77, v0
	v_mov_b32_e32 v78, v0
	v_mov_b32_e32 v79, v0
	v_mov_b32_e32 v88, v0
	v_mov_b32_e32 v89, v0
	v_mov_b32_e32 v90, v0
	v_mov_b32_e32 v91, v0
	v_mov_b32_e32 v92, v0
	v_mov_b32_e32 v93, v0
	v_mov_b32_e32 v94, v0
	v_mov_b32_e32 v95, v0
	v_mov_b32_e32 v104, v0
	v_mov_b32_e32 v105, v0
	v_mov_b32_e32 v106, v0
	v_mov_b32_e32 v107, v0
	v_mov_b32_e32 v108, v0
	v_mov_b32_e32 v109, v0
	v_mov_b32_e32 v110, v0
	v_mov_b32_e32 v111, v0
	v_mov_b32_e32 v120, v0
	v_mov_b32_e32 v121, v0
	v_mov_b32_e32 v122, v0
	v_mov_b32_e32 v123, v0
	v_mov_b32_e32 v124, v0
	v_mov_b32_e32 v125, v0
	v_mov_b32_e32 v126, v0
	v_mov_b32_e32 v127, v0
	s_branch .LBB0_2380

; #define PG8_STAGE(bufoff, soff, voff) do { _Pragma("unroll") for (int _i = 0; _i < 2; ++_i) \
;         __builtin_amdgcn_raw_ptr_buffer_load_lds(rs_##voff, (PG8_LAS unsigned*)(lds + (bufoff) + ldsw + _i * 8192), 16, (int)(voff)[_i], (int)(soff), 0, 0); } while (0)
; #define PG8_LDA(dst, b, h) do { _Pragma("unroll") for (int m = 0; m < 4; ++m) _Pragma("unroll") for (int k = 0; k < 2; ++k) dst[m][k] = *(const PG8_LAS bf16x8*)(lds + PG8_SA(b, h) + aoff + m * 2048 + k * 1024); } while (0)
; #define PG8_LDB(dst, b, h) do { _Pragma("unroll") for (int n = 0; n < 2; ++n) _Pragma("unroll") for (int k = 0; k < 2; ++k) dst[n][k] = *(const PG8_LAS bf16x8*)(lds + PG8_SB(b, h) + boff + n * 2048 + k * 1024); } while (0)
; #define PG8_MMA(ai, bj, At, Bt) do { __builtin_amdgcn_s_setprio(1); _Pragma("unroll") for (int m = 0; m < 4; ++m) _Pragma("unroll") for (int n = 0; n < 2; ++n) _Pragma("unroll") for (int k = 0; k < 2; ++k) \
;         acc[ai][bj][m][n] = __builtin_amdgcn_mfma_f32_16x16x32_bf16(Bt[n][k], At[m][k], acc[ai][bj][m][n], 0, 0, 0); __builtin_amdgcn_s_setprio(0); } while (0)
; #define PG8_WAIT_V(n) asm volatile("s_waitcnt vmcnt(" #n ")" ::: "memory")
; #define PG8_BAR __builtin_amdgcn_s_barrier()
; template <class Epi, class Sched, bool ALIGN_EPI = false, bool SP2 = false>
; __device__ __forceinline__ void gemm_phase(PG8_LAS unsigned char* lds, const Gemm g, const Sched& S, const Epi& E, const int wid  ) {
;     ...
;         for (int t = 0; t < nt; t += 2) {
;             const bool last = (t == nt - 2);
;             const unsigned a1 = cA + (unsigned)(t + 1) * kstep;
;             const unsigned a2 = last ? nA : cA + (unsigned)(t + 2) * kstep, b2 = last ? nB : cB + (unsigned)(t + 2) * kstep;
;             const unsigned a3 = a2 + kstep, b3 = b2 + kstep;
;             if (last && has_next) S.a_ready(nxt);
;             if constexpr (SP2) {
;             PG8_LDB(B0, 0, 0); PG8_LDB(B1, 0, 1); PG8_SCHED; PG8_LDA(At, 0, 0); PG8_STAGE(PG8_SA(1, 1), a1 + hstep, voffA);
;             PG8_WAIT_V(8); PG8_WAIT_L(0); PG8_BAR; PG8_MMA(0, 0, At, B0); PG8_MMA(0, 1, At, B1); PG8_BAR; PG8_SCHED;
;             PG8_LDA(At, 0, 1); PG8_STAGE(PG8_SB(0, 0), b2, voffB); PG8_STAGE(PG8_SB(0, 1), b2 + hstep, voffB); PG8_STAGE(PG8_SA(0, 0), a2, voffA);
;             PG8_WAIT_V(8); PG8_WAIT_L(0); PG8_BAR; PG8_MMA(1, 0, At, B0); PG8_MMA(1, 1, At, B1); PG8_BAR; PG8_SCHED;
.LBB0_2380:
	ds_read_b128 v[132:135], v140
	ds_read_b128 v[146:149], v140 offset:1024
	ds_read_b128 v[150:153], v140 offset:2048
	ds_read_b128 v[154:157], v140 offset:3072
	ds_read_b128 v[158:161], v141
	ds_read_b128 v[162:165], v141 offset:1024
	ds_read_b128 v[166:169], v141 offset:2048
	ds_read_b128 v[170:173], v141 offset:3072
	s_add_i32 s14, s16, 0xffea0080
	s_cmpk_eq_i32 s58, 0x54
	s_cselect_b32 s61, s0, s14
	s_cselect_b32 s60, s1, s55
	s_or_b32 s59, s61, 0x80
	s_mov_b32 m0, s45
	ds_read_b128 v[174:177], v142
	ds_read_b128 v[178:181], v142 offset:1024
	ds_read_b128 v[182:185], v142 offset:2048
	ds_read_b128 v[186:189], v142 offset:3072
	ds_read_b128 v[190:193], v142 offset:4096
	ds_read_b128 v[194:197], v142 offset:5120
	ds_read_b128 v[198:201], v142 offset:6144
	ds_read_b128 v[202:205], v142 offset:7168
	buffer_load_dwordx4 v136, s[8:11], s16 offen lds
	s_mov_b32 m0, s46
	s_nop 0
	buffer_load_dwordx4 v138, s[8:11], s16 offen lds
	s_waitcnt vmcnt(8)
	s_waitcnt lgkmcnt(0)
	s_barrier
	s_setprio 1
	s_waitcnt lgkmcnt(7)
	v_mfma_f32_16x16x32_bf16 v[124:127], v[132:135], v[174:177], v[124:127]
	v_mfma_f32_16x16x32_bf16 v[120:123], v[150:153], v[174:177], v[120:123]
	s_waitcnt lgkmcnt(5)
	v_mfma_f32_16x16x32_bf16 v[108:111], v[132:135], v[182:185], v[108:111]
	v_mfma_f32_16x16x32_bf16 v[104:107], v[150:153], v[182:185], v[104:107]
	s_waitcnt lgkmcnt(3)
	v_mfma_f32_16x16x32_bf16 v[92:95], v[132:135], v[190:193], v[92:95]
	v_mfma_f32_16x16x32_bf16 v[88:91], v[150:153], v[190:193], v[88:91]
	s_waitcnt lgkmcnt(1)
	v_mfma_f32_16x16x32_bf16 v[76:79], v[132:135], v[198:201], v[76:79]
	v_mfma_f32_16x16x32_bf16 v[72:75], v[150:153], v[198:201], v[72:75]
	v_mfma_f32_16x16x32_bf16 v[124:127], v[146:149], v[178:181], v[124:127]
	v_mfma_f32_16x16x32_bf16 v[120:123], v[154:157], v[178:181], v[120:123]
	v_mfma_f32_16x16x32_bf16 v[108:111], v[146:149], v[186:189], v[108:111]
	v_mfma_f32_16x16x32_bf16 v[104:107], v[154:157], v[186:189], v[104:107]
	v_mfma_f32_16x16x32_bf16 v[92:95], v[146:149], v[194:197], v[92:95]
	v_mfma_f32_16x16x32_bf16 v[88:91], v[154:157], v[194:197], v[88:91]
	s_waitcnt lgkmcnt(0)
	v_mfma_f32_16x16x32_bf16 v[76:79], v[146:149], v[202:205], v[76:79]
	v_mfma_f32_16x16x32_bf16 v[72:75], v[154:157], v[202:205], v[72:75]
	s_setprio 0
	s_setprio 1
	v_mfma_f32_16x16x32_bf16 v[116:119], v[158:161], v[174:177], v[116:119]
	v_mfma_f32_16x16x32_bf16 v[112:115], v[166:169], v[174:177], v[112:115]
	v_mfma_f32_16x16x32_bf16 v[100:103], v[158:161], v[182:185], v[100:103]
	v_mfma_f32_16x16x32_bf16 v[96:99], v[166:169], v[182:185], v[96:99]
	v_mfma_f32_16x16x32_bf16 v[84:87], v[158:161], v[190:193], v[84:87]
	v_mfma_f32_16x16x32_bf16 v[80:83], v[166:169], v[190:193], v[80:83]
	v_mfma_f32_16x16x32_bf16 v[68:71], v[158:161], v[198:201], v[68:71]
	v_mfma_f32_16x16x32_bf16 v[64:67], v[166:169], v[198:201], v[64:67]
	v_mfma_f32_16x16x32_bf16 v[116:119], v[162:165], v[178:181], v[116:119]
	v_mfma_f32_16x16x32_bf16 v[112:115], v[170:173], v[178:181], v[112:115]
	v_mfma_f32_16x16x32_bf16 v[100:103], v[162:165], v[186:189], v[100:103]
	v_mfma_f32_16x16x32_bf16 v[96:99], v[170:173], v[186:189], v[96:99]
	v_mfma_f32_16x16x32_bf16 v[84:87], v[162:165], v[194:197], v[84:87]
	v_mfma_f32_16x16x32_bf16 v[80:83], v[170:173], v[194:197], v[80:83]
	v_mfma_f32_16x16x32_bf16 v[68:71], v[162:165], v[202:205], v[68:71]
	v_mfma_f32_16x16x32_bf16 v[64:67], v[170:173], v[202:205], v[64:67]
	s_setprio 0
	s_barrier
	s_mov_b32 m0, s28
	s_mov_b32 s14, s10
	s_mov_b32 s15, s11
	ds_read_b128 v[174:177], v142 offset:16384
	ds_read_b128 v[178:181], v142 offset:17408
	ds_read_b128 v[182:185], v142 offset:18432
	ds_read_b128 v[186:189], v142 offset:19456
	ds_read_b128 v[190:193], v142 offset:20480
	ds_read_b128 v[194:197], v142 offset:21504
	ds_read_b128 v[198:201], v142 offset:22528
	ds_read_b128 v[202:205], v142 offset:23552
	buffer_load_dwordx4 v137, s[12:15], s60 offen lds
	s_mov_b32 m0, s29
	s_add_i32 s62, s60, 0x160000
	buffer_load_dwordx4 v139, s[12:15], s60 offen lds
	s_mov_b32 m0, s30
	s_nop 0
	buffer_load_dwordx4 v137, s[12:15], s62 offen lds
	s_mov_b32 m0, s31
	s_nop 0
	buffer_load_dwordx4 v139, s[12:15], s62 offen lds
	s_mov_b32 m0, s27
	s_nop 0
	buffer_load_dwordx4 v136, s[8:11], s61 offen lds
	s_mov_b32 m0, s33
	s_nop 0
	buffer_load_dwordx4 v138, s[8:11], s61 offen lds
	s_waitcnt vmcnt(8)
	s_waitcnt lgkmcnt(0)
	s_barrier
	s_setprio 1
	s_waitcnt lgkmcnt(7)
	v_mfma_f32_16x16x32_bf16 v[60:63], v[132:135], v[174:177], v[60:63]
	v_mfma_f32_16x16x32_bf16 v[56:59], v[150:153], v[174:177], v[56:59]
	s_waitcnt lgkmcnt(5)
	v_mfma_f32_16x16x32_bf16 v[44:47], v[132:135], v[182:185], v[44:47]
	v_mfma_f32_16x16x32_bf16 v[40:43], v[150:153], v[182:185], v[40:43]
	s_waitcnt lgkmcnt(3)
	v_mfma_f32_16x16x32_bf16 v[28:31], v[132:135], v[190:193], v[28:31]
	v_mfma_f32_16x16x32_bf16 v[24:27], v[150:153], v[190:193], v[24:27]
	s_waitcnt lgkmcnt(1)
	v_mfma_f32_16x16x32_bf16 v[12:15], v[132:135], v[198:201], v[12:15]
	v_mfma_f32_16x16x32_bf16 v[8:11], v[150:153], v[198:201], v[8:11]
	v_mfma_f32_16x16x32_bf16 v[60:63], v[146:149], v[178:181], v[60:63]
	v_mfma_f32_16x16x32_bf16 v[56:59], v[154:157], v[178:181], v[56:59]
	v_mfma_f32_16x16x32_bf16 v[44:47], v[146:149], v[186:189], v[44:47]
	v_mfma_f32_16x16x32_bf16 v[40:43], v[154:157], v[186:189], v[40:43]
	v_mfma_f32_16x16x32_bf16 v[28:31], v[146:149], v[194:197], v[28:31]
	v_mfma_f32_16x16x32_bf16 v[24:27], v[154:157], v[194:197], v[24:27]
	s_waitcnt lgkmcnt(0)
	v_mfma_f32_16x16x32_bf16 v[12:15], v[146:149], v[202:205], v[12:15]
	v_mfma_f32_16x16x32_bf16 v[8:11], v[154:157], v[202:205], v[8:11]
	s_setprio 0
	s_setprio 1
	v_mfma_f32_16x16x32_bf16 v[52:55], v[158:161], v[174:177], v[52:55]
	v_mfma_f32_16x16x32_bf16 v[48:51], v[166:169], v[174:177], v[48:51]
	v_mfma_f32_16x16x32_bf16 v[36:39], v[158:161], v[182:185], v[36:39]
	v_mfma_f32_16x16x32_bf16 v[32:35], v[166:169], v[182:185], v[32:35]
	v_mfma_f32_16x16x32_bf16 v[20:23], v[158:161], v[190:193], v[20:23]
	v_mfma_f32_16x16x32_bf16 v[16:19], v[166:169], v[190:193], v[16:19]
	v_mfma_f32_16x16x32_bf16 v[4:7], v[158:161], v[198:201], v[4:7]
	v_mfma_f32_16x16x32_bf16 v[0:3], v[166:169], v[198:201], v[0:3]
	v_mfma_f32_16x16x32_bf16 v[52:55], v[162:165], v[178:181], v[52:55]
	v_mfma_f32_16x16x32_bf16 v[48:51], v[170:173], v[178:181], v[48:51]
	v_mfma_f32_16x16x32_bf16 v[36:39], v[162:165], v[186:189], v[36:39]
	v_mfma_f32_16x16x32_bf16 v[32:35], v[170:173], v[186:189], v[32:35]
	v_mfma_f32_16x16x32_bf16 v[20:23], v[162:165], v[194:197], v[20:23]
	v_mfma_f32_16x16x32_bf16 v[16:19], v[170:173], v[194:197], v[16:19]
	v_mfma_f32_16x16x32_bf16 v[4:7], v[162:165], v[202:205], v[4:7]
	v_mfma_f32_16x16x32_bf16 v[0:3], v[170:173], v[202:205], v[0:3]
	s_setprio 0
	s_barrier
; #define PG8_STAGE(bufoff, soff, voff) do { _Pragma("unroll") for (int _i = 0; _i < 2; ++_i) \
;         __builtin_amdgcn_raw_ptr_buffer_load_lds(rs_##voff, (PG8_LAS unsigned*)(lds + (bufoff) + ldsw + _i * 8192), 16, (int)(voff)[_i], (int)(soff), 0, 0); } while (0)
; #define PG8_LDA(dst, b, h) do { _Pragma("unroll") for (int m = 0; m < 4; ++m) _Pragma("unroll") for (int k = 0; k < 2; ++k) dst[m][k] = *(const PG8_LAS bf16x8*)(lds + PG8_SA(b, h) + aoff + m * 2048 + k * 1024); } while (0)
; #define PG8_LDB(dst, b, h) do { _Pragma("unroll") for (int n = 0; n < 2; ++n) _Pragma("unroll") for (int k = 0; k < 2; ++k) dst[n][k] = *(const PG8_LAS bf16x8*)(lds + PG8_SB(b, h) + boff + n * 2048 + k * 1024); } while (0)
; #define PG8_MMA(ai, bj, At, Bt) do { __builtin_amdgcn_s_setprio(1); _Pragma("unroll") for (int m = 0; m < 4; ++m) _Pragma("unroll") for (int n = 0; n < 2; ++n) _Pragma("unroll") for (int k = 0; k < 2; ++k) \
;         acc[ai][bj][m][n] = __builtin_amdgcn_mfma_f32_16x16x32_bf16(Bt[n][k], At[m][k], acc[ai][bj][m][n], 0, 0, 0); __builtin_amdgcn_s_setprio(0); } while (0)
; #define PG8_WAIT_V(n) asm volatile("s_waitcnt vmcnt(" #n ")" ::: "memory")
; #define PG8_WAIT_L(n) asm volatile("s_waitcnt lgkmcnt(" #n ")" ::: "memory")
; #define PG8_BAR __builtin_amdgcn_s_barrier()
; #define PG8_SCHED __builtin_amdgcn_sched_barrier(0)
; template <class Epi, class Sched, bool ALIGN_EPI = false, bool SP2 = false>
; __device__ __forceinline__ void gemm_phase(PG8_LAS unsigned char* lds, const Gemm g, const Sched& S, const Epi& E, const int wid  ) {
;     ...
;             PG8_LDB(B0, 1, 0); PG8_LDB(B1, 1, 1); PG8_SCHED; PG8_LDA(At, 1, 0); PG8_STAGE(PG8_SA(0, 1), a2 + hstep, voffA);
;             PG8_WAIT_V(8); PG8_WAIT_L(0); PG8_BAR; PG8_MMA(0, 0, At, B0); PG8_MMA(0, 1, At, B1); PG8_BAR; PG8_SCHED;
;             PG8_LDA(At, 1, 1); PG8_STAGE(PG8_SB(1, 0), b3, voffB); PG8_STAGE(PG8_SB(1, 1), b3 + hstep, voffB); PG8_STAGE(PG8_SA(1, 0), a3, voffA);
;             PG8_WAIT_V(8); PG8_WAIT_L(0); PG8_BAR; PG8_MMA(1, 0, At, B0); PG8_MMA(1, 1, At, B1); PG8_BAR; PG8_SCHED;
;     ...
;         if constexpr (ALIGN_EPI) { if (wr == 0) PG8_BAR; }
	ds_read_b128 v[132:135], v143
	ds_read_b128 v[146:149], v143 offset:1024
	ds_read_b128 v[150:153], v143 offset:2048
	ds_read_b128 v[154:157], v143 offset:3072
	ds_read_b128 v[158:161], v144
	ds_read_b128 v[162:165], v144 offset:1024
	ds_read_b128 v[166:169], v144 offset:2048
	ds_read_b128 v[170:173], v144 offset:3072
	s_add_i32 s61, s61, 0x160000
	s_mov_b32 m0, s34
	ds_read_b128 v[174:177], v142 offset:32768
	ds_read_b128 v[178:181], v142 offset:33792
	ds_read_b128 v[182:185], v142 offset:34816
	ds_read_b128 v[186:189], v142 offset:35840
	ds_read_b128 v[190:193], v142 offset:36864
	ds_read_b128 v[194:197], v142 offset:37888
	ds_read_b128 v[198:201], v142 offset:38912
	ds_read_b128 v[202:205], v142 offset:39936
	buffer_load_dwordx4 v136, s[8:11], s61 offen lds
	s_mov_b32 m0, s35
	s_nop 0
	buffer_load_dwordx4 v138, s[8:11], s61 offen lds
	s_waitcnt vmcnt(8)
	s_waitcnt lgkmcnt(0)
	s_barrier
	s_setprio 1
	s_waitcnt lgkmcnt(7)
	v_mfma_f32_16x16x32_bf16 v[124:127], v[132:135], v[174:177], v[124:127]
	v_mfma_f32_16x16x32_bf16 v[120:123], v[150:153], v[174:177], v[120:123]
	s_waitcnt lgkmcnt(5)
	v_mfma_f32_16x16x32_bf16 v[108:111], v[132:135], v[182:185], v[108:111]
	v_mfma_f32_16x16x32_bf16 v[104:107], v[150:153], v[182:185], v[104:107]
	s_waitcnt lgkmcnt(3)
	v_mfma_f32_16x16x32_bf16 v[92:95], v[132:135], v[190:193], v[92:95]
	v_mfma_f32_16x16x32_bf16 v[88:91], v[150:153], v[190:193], v[88:91]
	s_waitcnt lgkmcnt(1)
	v_mfma_f32_16x16x32_bf16 v[76:79], v[132:135], v[198:201], v[76:79]
	v_mfma_f32_16x16x32_bf16 v[72:75], v[150:153], v[198:201], v[72:75]
	v_mfma_f32_16x16x32_bf16 v[124:127], v[146:149], v[178:181], v[124:127]
	v_mfma_f32_16x16x32_bf16 v[120:123], v[154:157], v[178:181], v[120:123]
	v_mfma_f32_16x16x32_bf16 v[108:111], v[146:149], v[186:189], v[108:111]
	v_mfma_f32_16x16x32_bf16 v[104:107], v[154:157], v[186:189], v[104:107]
	v_mfma_f32_16x16x32_bf16 v[92:95], v[146:149], v[194:197], v[92:95]
	v_mfma_f32_16x16x32_bf16 v[88:91], v[154:157], v[194:197], v[88:91]
	s_waitcnt lgkmcnt(0)
	v_mfma_f32_16x16x32_bf16 v[76:79], v[146:149], v[202:205], v[76:79]
	v_mfma_f32_16x16x32_bf16 v[72:75], v[154:157], v[202:205], v[72:75]
	s_setprio 0
	s_setprio 1
	v_mfma_f32_16x16x32_bf16 v[116:119], v[158:161], v[174:177], v[116:119]
	v_mfma_f32_16x16x32_bf16 v[112:115], v[166:169], v[174:177], v[112:115]
	v_mfma_f32_16x16x32_bf16 v[100:103], v[158:161], v[182:185], v[100:103]
	v_mfma_f32_16x16x32_bf16 v[96:99], v[166:169], v[182:185], v[96:99]
	v_mfma_f32_16x16x32_bf16 v[84:87], v[158:161], v[190:193], v[84:87]
	v_mfma_f32_16x16x32_bf16 v[80:83], v[166:169], v[190:193], v[80:83]
	v_mfma_f32_16x16x32_bf16 v[68:71], v[158:161], v[198:201], v[68:71]
	v_mfma_f32_16x16x32_bf16 v[64:67], v[166:169], v[198:201], v[64:67]
	v_mfma_f32_16x16x32_bf16 v[116:119], v[162:165], v[178:181], v[116:119]
	v_mfma_f32_16x16x32_bf16 v[112:115], v[170:173], v[178:181], v[112:115]
	v_mfma_f32_16x16x32_bf16 v[100:103], v[162:165], v[186:189], v[100:103]
	v_mfma_f32_16x16x32_bf16 v[96:99], v[170:173], v[186:189], v[96:99]
	v_mfma_f32_16x16x32_bf16 v[84:87], v[162:165], v[194:197], v[84:87]
	v_mfma_f32_16x16x32_bf16 v[80:83], v[170:173], v[194:197], v[80:83]
	v_mfma_f32_16x16x32_bf16 v[68:71], v[162:165], v[202:205], v[68:71]
	v_mfma_f32_16x16x32_bf16 v[64:67], v[170:173], v[202:205], v[64:67]
	s_setprio 0
	s_barrier
	s_mov_b32 m0, s36
	s_or_b32 s61, s60, 0x80
	ds_read_b128 v[174:177], v142 offset:49152
	ds_read_b128 v[178:181], v142 offset:50176
	ds_read_b128 v[182:185], v142 offset:51200
	ds_read_b128 v[186:189], v142 offset:52224
	ds_read_b128 v[190:193], v142 offset:53248
	ds_read_b128 v[194:197], v142 offset:54272
	ds_read_b128 v[198:201], v142 offset:55296
	ds_read_b128 v[202:205], v142 offset:56320
	buffer_load_dwordx4 v137, s[12:15], s61 offen lds
	s_mov_b32 m0, s37
	s_add_i32 s60, s60, 0x160080
	buffer_load_dwordx4 v139, s[12:15], s61 offen lds
	s_mov_b32 m0, s40
	s_nop 0
	buffer_load_dwordx4 v137, s[12:15], s60 offen lds
	s_mov_b32 m0, s41
	s_nop 0
	buffer_load_dwordx4 v139, s[12:15], s60 offen lds
	s_mov_b32 m0, s38
	s_nop 0
	buffer_load_dwordx4 v136, s[8:11], s59 offen lds
	s_mov_b32 m0, s39
	s_nop 0
	buffer_load_dwordx4 v138, s[8:11], s59 offen lds
	s_waitcnt vmcnt(8)
	s_waitcnt lgkmcnt(0)
	s_barrier
	s_setprio 1
	s_waitcnt lgkmcnt(7)
	v_mfma_f32_16x16x32_bf16 v[60:63], v[132:135], v[174:177], v[60:63]
	v_mfma_f32_16x16x32_bf16 v[56:59], v[150:153], v[174:177], v[56:59]
	s_waitcnt lgkmcnt(5)
	v_mfma_f32_16x16x32_bf16 v[44:47], v[132:135], v[182:185], v[44:47]
	v_mfma_f32_16x16x32_bf16 v[40:43], v[150:153], v[182:185], v[40:43]
	s_waitcnt lgkmcnt(3)
	v_mfma_f32_16x16x32_bf16 v[28:31], v[132:135], v[190:193], v[28:31]
	v_mfma_f32_16x16x32_bf16 v[24:27], v[150:153], v[190:193], v[24:27]
	s_waitcnt lgkmcnt(1)
	v_mfma_f32_16x16x32_bf16 v[12:15], v[132:135], v[198:201], v[12:15]
	v_mfma_f32_16x16x32_bf16 v[8:11], v[150:153], v[198:201], v[8:11]
	v_mfma_f32_16x16x32_bf16 v[60:63], v[146:149], v[178:181], v[60:63]
	v_mfma_f32_16x16x32_bf16 v[56:59], v[154:157], v[178:181], v[56:59]
	v_mfma_f32_16x16x32_bf16 v[44:47], v[146:149], v[186:189], v[44:47]
	v_mfma_f32_16x16x32_bf16 v[40:43], v[154:157], v[186:189], v[40:43]
	v_mfma_f32_16x16x32_bf16 v[28:31], v[146:149], v[194:197], v[28:31]
	v_mfma_f32_16x16x32_bf16 v[24:27], v[154:157], v[194:197], v[24:27]
	s_waitcnt lgkmcnt(0)
	v_mfma_f32_16x16x32_bf16 v[12:15], v[146:149], v[202:205], v[12:15]
	v_mfma_f32_16x16x32_bf16 v[8:11], v[154:157], v[202:205], v[8:11]
	s_setprio 0
	s_setprio 1
	v_mfma_f32_16x16x32_bf16 v[52:55], v[158:161], v[174:177], v[52:55]
	v_mfma_f32_16x16x32_bf16 v[48:51], v[166:169], v[174:177], v[48:51]
	v_mfma_f32_16x16x32_bf16 v[36:39], v[158:161], v[182:185], v[36:39]
	v_mfma_f32_16x16x32_bf16 v[32:35], v[166:169], v[182:185], v[32:35]
	v_mfma_f32_16x16x32_bf16 v[20:23], v[158:161], v[190:193], v[20:23]
	v_mfma_f32_16x16x32_bf16 v[16:19], v[166:169], v[190:193], v[16:19]
	v_mfma_f32_16x16x32_bf16 v[4:7], v[158:161], v[198:201], v[4:7]
	v_mfma_f32_16x16x32_bf16 v[0:3], v[166:169], v[198:201], v[0:3]
	v_mfma_f32_16x16x32_bf16 v[52:55], v[162:165], v[178:181], v[52:55]
	v_mfma_f32_16x16x32_bf16 v[48:51], v[170:173], v[178:181], v[48:51]
	v_mfma_f32_16x16x32_bf16 v[36:39], v[162:165], v[186:189], v[36:39]
	v_mfma_f32_16x16x32_bf16 v[32:35], v[170:173], v[186:189], v[32:35]
	v_mfma_f32_16x16x32_bf16 v[20:23], v[162:165], v[194:197], v[20:23]
	v_mfma_f32_16x16x32_bf16 v[16:19], v[170:173], v[194:197], v[16:19]
	v_mfma_f32_16x16x32_bf16 v[4:7], v[162:165], v[202:205], v[4:7]
	v_mfma_f32_16x16x32_bf16 v[0:3], v[170:173], v[202:205], v[0:3]
	s_setprio 0
	s_add_i32 s58, s58, 2
	s_addk_i32 s16, 0x100
	s_addk_i32 s55, 0x100
	s_cmpk_gt_u32 s58, 0x55
	s_cbranch_scc0 .Lrot_2380
	s_barrier
	s_and_b64 vcc, exec, s[24:25]
	s_cbranch_vccz .LBB0_2383
	s_barrier

; #define PG8_STAGE(bufoff, soff, voff) do { _Pragma("unroll") for (int _i = 0; _i < 2; ++_i) \
;         __builtin_amdgcn_raw_ptr_buffer_load_lds(rs_##voff, (PG8_LAS unsigned*)(lds + (bufoff) + ldsw + _i * 8192), 16, (int)(voff)[_i], (int)(soff), 0, 0); } while (0)
; #define PG8_LDA(dst, b, h) do { _Pragma("unroll") for (int m = 0; m < 4; ++m) _Pragma("unroll") for (int k = 0; k < 2; ++k) dst[m][k] = *(const PG8_LAS bf16x8*)(lds + PG8_SA(b, h) + aoff + m * 2048 + k * 1024); } while (0)
; #define PG8_LDB(dst, b, h) do { _Pragma("unroll") for (int n = 0; n < 2; ++n) _Pragma("unroll") for (int k = 0; k < 2; ++k) dst[n][k] = *(const PG8_LAS bf16x8*)(lds + PG8_SB(b, h) + boff + n * 2048 + k * 1024); } while (0)
; #define PG8_MMA(ai, bj, At, Bt) do { __builtin_amdgcn_s_setprio(1); _Pragma("unroll") for (int m = 0; m < 4; ++m) _Pragma("unroll") for (int n = 0; n < 2; ++n) _Pragma("unroll") for (int k = 0; k < 2; ++k) \
;         acc[ai][bj][m][n] = __builtin_amdgcn_mfma_f32_16x16x32_bf16(Bt[n][k], At[m][k], acc[ai][bj][m][n], 0, 0, 0); __builtin_amdgcn_s_setprio(0); } while (0)
; #define PG8_WAIT_V(n) asm volatile("s_waitcnt vmcnt(" #n ")" ::: "memory")
; #define PG8_BAR __builtin_amdgcn_s_barrier()
; template <class Epi, class Sched, bool ALIGN_EPI = false, bool SP2 = false>
; __device__ __forceinline__ void gemm_phase(PG8_LAS unsigned char* lds, const Gemm g, const Sched& S, const Epi& E, const int wid  ) {
;     ...
;         for (int t = 0; t < nt; t += 2) {
;             const bool last = (t == nt - 2);
;             const unsigned a1 = cA + (unsigned)(t + 1) * kstep;
;             const unsigned a2 = last ? nA : cA + (unsigned)(t + 2) * kstep, b2 = last ? nB : cB + (unsigned)(t + 2) * kstep;
;             const unsigned a3 = a2 + kstep, b3 = b2 + kstep;
;             if (last && has_next) S.a_ready(nxt);
;             if constexpr (SP2) {
;             PG8_LDB(B0, 0, 0); PG8_LDB(B1, 0, 1); PG8_SCHED; PG8_LDA(At, 0, 0); PG8_STAGE(PG8_SA(1, 1), a1 + hstep, voffA);
;             PG8_WAIT_V(8); PG8_WAIT_L(0); PG8_BAR; PG8_MMA(0, 0, At, B0); PG8_MMA(0, 1, At, B1); PG8_BAR; PG8_SCHED;
;             PG8_LDA(At, 0, 1); PG8_STAGE(PG8_SB(0, 0), b2, voffB); PG8_STAGE(PG8_SB(0, 1), b2 + hstep, voffB); PG8_STAGE(PG8_SA(0, 0), a2, voffA);
;             PG8_WAIT_V(8); PG8_WAIT_L(0); PG8_BAR; PG8_MMA(1, 0, At, B0); PG8_MMA(1, 1, At, B1); PG8_BAR; PG8_SCHED;
.LBB0_2575:
	ds_read_b128 v[132:135], v144
	ds_read_b128 v[150:153], v144 offset:1024
	ds_read_b128 v[154:157], v144 offset:2048
	ds_read_b128 v[158:161], v144 offset:3072
	ds_read_b128 v[162:165], v145
	ds_read_b128 v[166:169], v145 offset:1024
	ds_read_b128 v[170:173], v145 offset:2048
	ds_read_b128 v[174:177], v145 offset:3072
	s_add_i32 s14, s65, 0xfff80080
	s_cmp_eq_u32 s67, 28
	s_cselect_b32 s70, s63, s14
	s_cselect_b32 s69, s64, s66
	s_or_b32 s68, s70, 0x80
	s_mov_b32 m0, s47
	ds_read_b128 v[178:181], v146
	ds_read_b128 v[182:185], v146 offset:1024
	ds_read_b128 v[186:189], v146 offset:2048
	ds_read_b128 v[190:193], v146 offset:3072
	ds_read_b128 v[194:197], v146 offset:4096
	ds_read_b128 v[198:201], v146 offset:5120
	ds_read_b128 v[202:205], v146 offset:6144
	ds_read_b128 v[206:209], v146 offset:7168
	buffer_load_dwordx4 v138, s[8:11], s65 offen lds
	s_mov_b32 m0, s48
	s_nop 0
	buffer_load_dwordx4 v140, s[8:11], s65 offen lds
	s_waitcnt vmcnt(8)
	s_waitcnt lgkmcnt(0)
	s_barrier
	s_setprio 1
	s_waitcnt lgkmcnt(7)
	v_mfma_f32_16x16x32_bf16 v[124:127], v[132:135], v[178:181], v[124:127]
	v_mfma_f32_16x16x32_bf16 v[120:123], v[154:157], v[178:181], v[120:123]
	s_waitcnt lgkmcnt(5)
	v_mfma_f32_16x16x32_bf16 v[112:115], v[132:135], v[186:189], v[112:115]
	v_mfma_f32_16x16x32_bf16 v[104:107], v[154:157], v[186:189], v[104:107]
	s_waitcnt lgkmcnt(3)
	v_mfma_f32_16x16x32_bf16 v[96:99], v[132:135], v[194:197], v[96:99]
	v_mfma_f32_16x16x32_bf16 v[88:91], v[154:157], v[194:197], v[88:91]
	s_waitcnt lgkmcnt(1)
	v_mfma_f32_16x16x32_bf16 v[80:83], v[132:135], v[202:205], v[80:83]
	v_mfma_f32_16x16x32_bf16 v[72:75], v[154:157], v[202:205], v[72:75]
	v_mfma_f32_16x16x32_bf16 v[124:127], v[150:153], v[182:185], v[124:127]
	v_mfma_f32_16x16x32_bf16 v[120:123], v[158:161], v[182:185], v[120:123]
	v_mfma_f32_16x16x32_bf16 v[112:115], v[150:153], v[190:193], v[112:115]
	v_mfma_f32_16x16x32_bf16 v[104:107], v[158:161], v[190:193], v[104:107]
	v_mfma_f32_16x16x32_bf16 v[96:99], v[150:153], v[198:201], v[96:99]
	v_mfma_f32_16x16x32_bf16 v[88:91], v[158:161], v[198:201], v[88:91]
	s_waitcnt lgkmcnt(0)
	v_mfma_f32_16x16x32_bf16 v[80:83], v[150:153], v[206:209], v[80:83]
	v_mfma_f32_16x16x32_bf16 v[72:75], v[158:161], v[206:209], v[72:75]
	s_setprio 0
	s_setprio 1
	v_mfma_f32_16x16x32_bf16 v[116:119], v[162:165], v[178:181], v[116:119]
	v_mfma_f32_16x16x32_bf16 v[108:111], v[170:173], v[178:181], v[108:111]
	v_mfma_f32_16x16x32_bf16 v[100:103], v[162:165], v[186:189], v[100:103]
	v_mfma_f32_16x16x32_bf16 v[92:95], v[170:173], v[186:189], v[92:95]
	v_mfma_f32_16x16x32_bf16 v[84:87], v[162:165], v[194:197], v[84:87]
	v_mfma_f32_16x16x32_bf16 v[76:79], v[170:173], v[194:197], v[76:79]
	v_mfma_f32_16x16x32_bf16 v[68:71], v[162:165], v[202:205], v[68:71]
	v_mfma_f32_16x16x32_bf16 v[64:67], v[170:173], v[202:205], v[64:67]
	v_mfma_f32_16x16x32_bf16 v[116:119], v[166:169], v[182:185], v[116:119]
	v_mfma_f32_16x16x32_bf16 v[108:111], v[174:177], v[182:185], v[108:111]
	v_mfma_f32_16x16x32_bf16 v[100:103], v[166:169], v[190:193], v[100:103]
	v_mfma_f32_16x16x32_bf16 v[92:95], v[174:177], v[190:193], v[92:95]
	v_mfma_f32_16x16x32_bf16 v[84:87], v[166:169], v[198:201], v[84:87]
	v_mfma_f32_16x16x32_bf16 v[76:79], v[174:177], v[198:201], v[76:79]
	v_mfma_f32_16x16x32_bf16 v[68:71], v[166:169], v[206:209], v[68:71]
	v_mfma_f32_16x16x32_bf16 v[64:67], v[174:177], v[206:209], v[64:67]
	s_setprio 0
	s_barrier
	s_mov_b32 m0, s30
	s_mov_b32 s14, s10
	s_mov_b32 s15, s11
	ds_read_b128 v[178:181], v146 offset:16384
	ds_read_b128 v[182:185], v146 offset:17408
	ds_read_b128 v[186:189], v146 offset:18432
	ds_read_b128 v[190:193], v146 offset:19456
	ds_read_b128 v[194:197], v146 offset:20480
	ds_read_b128 v[198:201], v146 offset:21504
	ds_read_b128 v[202:205], v146 offset:22528
	ds_read_b128 v[206:209], v146 offset:23552
	buffer_load_dwordx4 v139, s[12:15], s69 offen lds
	s_mov_b32 m0, s31
	s_add_i32 s71, s69, 0x80000
	buffer_load_dwordx4 v141, s[12:15], s69 offen lds
	s_mov_b32 m0, s33
	s_nop 0
	buffer_load_dwordx4 v139, s[12:15], s71 offen lds
	s_mov_b32 m0, s34
	s_nop 0
	buffer_load_dwordx4 v141, s[12:15], s71 offen lds
	s_mov_b32 m0, s29
	s_nop 0
	buffer_load_dwordx4 v138, s[8:11], s70 offen lds
	s_mov_b32 m0, s35
	s_nop 0
	buffer_load_dwordx4 v140, s[8:11], s70 offen lds
	s_waitcnt vmcnt(8)
	s_waitcnt lgkmcnt(0)
	s_barrier
	s_setprio 1
	s_waitcnt lgkmcnt(7)
	v_mfma_f32_16x16x32_bf16 v[60:63], v[132:135], v[178:181], v[60:63]
	v_mfma_f32_16x16x32_bf16 v[56:59], v[154:157], v[178:181], v[56:59]
	s_waitcnt lgkmcnt(5)
	v_mfma_f32_16x16x32_bf16 v[48:51], v[132:135], v[186:189], v[48:51]
	v_mfma_f32_16x16x32_bf16 v[40:43], v[154:157], v[186:189], v[40:43]
	s_waitcnt lgkmcnt(3)
	v_mfma_f32_16x16x32_bf16 v[32:35], v[132:135], v[194:197], v[32:35]
	v_mfma_f32_16x16x32_bf16 v[24:27], v[154:157], v[194:197], v[24:27]
	s_waitcnt lgkmcnt(1)
	v_mfma_f32_16x16x32_bf16 v[16:19], v[132:135], v[202:205], v[16:19]
	v_mfma_f32_16x16x32_bf16 v[8:11], v[154:157], v[202:205], v[8:11]
	v_mfma_f32_16x16x32_bf16 v[60:63], v[150:153], v[182:185], v[60:63]
	v_mfma_f32_16x16x32_bf16 v[56:59], v[158:161], v[182:185], v[56:59]
	v_mfma_f32_16x16x32_bf16 v[48:51], v[150:153], v[190:193], v[48:51]
	v_mfma_f32_16x16x32_bf16 v[40:43], v[158:161], v[190:193], v[40:43]
	v_mfma_f32_16x16x32_bf16 v[32:35], v[150:153], v[198:201], v[32:35]
	v_mfma_f32_16x16x32_bf16 v[24:27], v[158:161], v[198:201], v[24:27]
	s_waitcnt lgkmcnt(0)
	v_mfma_f32_16x16x32_bf16 v[16:19], v[150:153], v[206:209], v[16:19]
	v_mfma_f32_16x16x32_bf16 v[8:11], v[158:161], v[206:209], v[8:11]
	s_setprio 0
	s_setprio 1
	v_mfma_f32_16x16x32_bf16 v[52:55], v[162:165], v[178:181], v[52:55]
	v_mfma_f32_16x16x32_bf16 v[44:47], v[170:173], v[178:181], v[44:47]
	v_mfma_f32_16x16x32_bf16 v[36:39], v[162:165], v[186:189], v[36:39]
	v_mfma_f32_16x16x32_bf16 v[28:31], v[170:173], v[186:189], v[28:31]
	v_mfma_f32_16x16x32_bf16 v[20:23], v[162:165], v[194:197], v[20:23]
	v_mfma_f32_16x16x32_bf16 v[12:15], v[170:173], v[194:197], v[12:15]
	v_mfma_f32_16x16x32_bf16 v[4:7], v[162:165], v[202:205], v[4:7]
	v_mfma_f32_16x16x32_bf16 v[0:3], v[170:173], v[202:205], v[0:3]
	v_mfma_f32_16x16x32_bf16 v[52:55], v[166:169], v[182:185], v[52:55]
	v_mfma_f32_16x16x32_bf16 v[44:47], v[174:177], v[182:185], v[44:47]
	v_mfma_f32_16x16x32_bf16 v[36:39], v[166:169], v[190:193], v[36:39]
	v_mfma_f32_16x16x32_bf16 v[28:31], v[174:177], v[190:193], v[28:31]
	v_mfma_f32_16x16x32_bf16 v[20:23], v[166:169], v[198:201], v[20:23]
	v_mfma_f32_16x16x32_bf16 v[12:15], v[174:177], v[198:201], v[12:15]
	v_mfma_f32_16x16x32_bf16 v[4:7], v[166:169], v[206:209], v[4:7]
	v_mfma_f32_16x16x32_bf16 v[0:3], v[174:177], v[206:209], v[0:3]
	s_setprio 0
	s_barrier
; #define PG8_STAGE(bufoff, soff, voff) do { _Pragma("unroll") for (int _i = 0; _i < 2; ++_i) \
;         __builtin_amdgcn_raw_ptr_buffer_load_lds(rs_##voff, (PG8_LAS unsigned*)(lds + (bufoff) + ldsw + _i * 8192), 16, (int)(voff)[_i], (int)(soff), 0, 0); } while (0)
; #define PG8_LDA(dst, b, h) do { _Pragma("unroll") for (int m = 0; m < 4; ++m) _Pragma("unroll") for (int k = 0; k < 2; ++k) dst[m][k] = *(const PG8_LAS bf16x8*)(lds + PG8_SA(b, h) + aoff + m * 2048 + k * 1024); } while (0)
; #define PG8_LDB(dst, b, h) do { _Pragma("unroll") for (int n = 0; n < 2; ++n) _Pragma("unroll") for (int k = 0; k < 2; ++k) dst[n][k] = *(const PG8_LAS bf16x8*)(lds + PG8_SB(b, h) + boff + n * 2048 + k * 1024); } while (0)
; #define PG8_MMA(ai, bj, At, Bt) do { __builtin_amdgcn_s_setprio(1); _Pragma("unroll") for (int m = 0; m < 4; ++m) _Pragma("unroll") for (int n = 0; n < 2; ++n) _Pragma("unroll") for (int k = 0; k < 2; ++k) \
;         acc[ai][bj][m][n] = __builtin_amdgcn_mfma_f32_16x16x32_bf16(Bt[n][k], At[m][k], acc[ai][bj][m][n], 0, 0, 0); __builtin_amdgcn_s_setprio(0); } while (0)
; #define PG8_WAIT_V(n) asm volatile("s_waitcnt vmcnt(" #n ")" ::: "memory")
; #define PG8_WAIT_L(n) asm volatile("s_waitcnt lgkmcnt(" #n ")" ::: "memory")
; #define PG8_BAR __builtin_amdgcn_s_barrier()
; #define PG8_SCHED __builtin_amdgcn_sched_barrier(0)
; template <class Epi, class Sched, bool ALIGN_EPI = false, bool SP2 = false>
; __device__ __forceinline__ void gemm_phase(PG8_LAS unsigned char* lds, const Gemm g, const Sched& S, const Epi& E, const int wid  ) {
;     ...
;             PG8_LDB(B0, 1, 0); PG8_LDB(B1, 1, 1); PG8_SCHED; PG8_LDA(At, 1, 0); PG8_STAGE(PG8_SA(0, 1), a2 + hstep, voffA);
;             PG8_WAIT_V(8); PG8_WAIT_L(0); PG8_BAR; PG8_MMA(0, 0, At, B0); PG8_MMA(0, 1, At, B1); PG8_BAR; PG8_SCHED;
;             PG8_LDA(At, 1, 1); PG8_STAGE(PG8_SB(1, 0), b3, voffB); PG8_STAGE(PG8_SB(1, 1), b3 + hstep, voffB); PG8_STAGE(PG8_SA(1, 0), a3, voffA);
;             PG8_WAIT_V(8); PG8_WAIT_L(0); PG8_BAR; PG8_MMA(1, 0, At, B0); PG8_MMA(1, 1, At, B1); PG8_BAR; PG8_SCHED;
;     ...
;         if constexpr (ALIGN_EPI) { if (wr == 0) PG8_BAR; }
	ds_read_b128 v[132:135], v147
	ds_read_b128 v[150:153], v147 offset:1024
	ds_read_b128 v[154:157], v147 offset:2048
	ds_read_b128 v[158:161], v147 offset:3072
	ds_read_b128 v[162:165], v148
	ds_read_b128 v[166:169], v148 offset:1024
	ds_read_b128 v[170:173], v148 offset:2048
	ds_read_b128 v[174:177], v148 offset:3072
	s_add_i32 s70, s70, 0x80000
	s_mov_b32 m0, s36
	ds_read_b128 v[178:181], v146 offset:32768
	ds_read_b128 v[182:185], v146 offset:33792
	ds_read_b128 v[186:189], v146 offset:34816
	ds_read_b128 v[190:193], v146 offset:35840
	ds_read_b128 v[194:197], v146 offset:36864
	ds_read_b128 v[198:201], v146 offset:37888
	ds_read_b128 v[202:205], v146 offset:38912
	ds_read_b128 v[206:209], v146 offset:39936
	buffer_load_dwordx4 v138, s[8:11], s70 offen lds
	s_mov_b32 m0, s37
	s_nop 0
	buffer_load_dwordx4 v140, s[8:11], s70 offen lds
	s_waitcnt vmcnt(8)
	s_waitcnt lgkmcnt(0)
	s_barrier
	s_setprio 1
	s_waitcnt lgkmcnt(7)
	v_mfma_f32_16x16x32_bf16 v[124:127], v[132:135], v[178:181], v[124:127]
	v_mfma_f32_16x16x32_bf16 v[120:123], v[154:157], v[178:181], v[120:123]
	s_waitcnt lgkmcnt(5)
	v_mfma_f32_16x16x32_bf16 v[112:115], v[132:135], v[186:189], v[112:115]
	v_mfma_f32_16x16x32_bf16 v[104:107], v[154:157], v[186:189], v[104:107]
	s_waitcnt lgkmcnt(3)
	v_mfma_f32_16x16x32_bf16 v[96:99], v[132:135], v[194:197], v[96:99]
	v_mfma_f32_16x16x32_bf16 v[88:91], v[154:157], v[194:197], v[88:91]
	s_waitcnt lgkmcnt(1)
	v_mfma_f32_16x16x32_bf16 v[80:83], v[132:135], v[202:205], v[80:83]
	v_mfma_f32_16x16x32_bf16 v[72:75], v[154:157], v[202:205], v[72:75]
	v_mfma_f32_16x16x32_bf16 v[124:127], v[150:153], v[182:185], v[124:127]
	v_mfma_f32_16x16x32_bf16 v[120:123], v[158:161], v[182:185], v[120:123]
	v_mfma_f32_16x16x32_bf16 v[112:115], v[150:153], v[190:193], v[112:115]
	v_mfma_f32_16x16x32_bf16 v[104:107], v[158:161], v[190:193], v[104:107]
	v_mfma_f32_16x16x32_bf16 v[96:99], v[150:153], v[198:201], v[96:99]
	v_mfma_f32_16x16x32_bf16 v[88:91], v[158:161], v[198:201], v[88:91]
	s_waitcnt lgkmcnt(0)
	v_mfma_f32_16x16x32_bf16 v[80:83], v[150:153], v[206:209], v[80:83]
	v_mfma_f32_16x16x32_bf16 v[72:75], v[158:161], v[206:209], v[72:75]
	s_setprio 0
	s_setprio 1
	v_mfma_f32_16x16x32_bf16 v[116:119], v[162:165], v[178:181], v[116:119]
	v_mfma_f32_16x16x32_bf16 v[108:111], v[170:173], v[178:181], v[108:111]
	v_mfma_f32_16x16x32_bf16 v[100:103], v[162:165], v[186:189], v[100:103]
	v_mfma_f32_16x16x32_bf16 v[92:95], v[170:173], v[186:189], v[92:95]
	v_mfma_f32_16x16x32_bf16 v[84:87], v[162:165], v[194:197], v[84:87]
	v_mfma_f32_16x16x32_bf16 v[76:79], v[170:173], v[194:197], v[76:79]
	v_mfma_f32_16x16x32_bf16 v[68:71], v[162:165], v[202:205], v[68:71]
	v_mfma_f32_16x16x32_bf16 v[64:67], v[170:173], v[202:205], v[64:67]
	v_mfma_f32_16x16x32_bf16 v[116:119], v[166:169], v[182:185], v[116:119]
	v_mfma_f32_16x16x32_bf16 v[108:111], v[174:177], v[182:185], v[108:111]
	v_mfma_f32_16x16x32_bf16 v[100:103], v[166:169], v[190:193], v[100:103]
	v_mfma_f32_16x16x32_bf16 v[92:95], v[174:177], v[190:193], v[92:95]
	v_mfma_f32_16x16x32_bf16 v[84:87], v[166:169], v[198:201], v[84:87]
	v_mfma_f32_16x16x32_bf16 v[76:79], v[174:177], v[198:201], v[76:79]
	v_mfma_f32_16x16x32_bf16 v[68:71], v[166:169], v[206:209], v[68:71]
	v_mfma_f32_16x16x32_bf16 v[64:67], v[174:177], v[206:209], v[64:67]
	s_setprio 0
	s_barrier
	s_mov_b32 m0, s39
	s_or_b32 s70, s69, 0x80
	ds_read_b128 v[178:181], v146 offset:49152
	ds_read_b128 v[182:185], v146 offset:50176
	ds_read_b128 v[186:189], v146 offset:51200
	ds_read_b128 v[190:193], v146 offset:52224
	ds_read_b128 v[194:197], v146 offset:53248
	ds_read_b128 v[198:201], v146 offset:54272
	ds_read_b128 v[202:205], v146 offset:55296
	ds_read_b128 v[206:209], v146 offset:56320
	buffer_load_dwordx4 v139, s[12:15], s70 offen lds
	s_mov_b32 m0, s40
	s_add_i32 s69, s69, 0x80080
	buffer_load_dwordx4 v141, s[12:15], s70 offen lds
	s_mov_b32 m0, s43
	s_nop 0
	buffer_load_dwordx4 v139, s[12:15], s69 offen lds
	s_mov_b32 m0, s44
	s_nop 0
	buffer_load_dwordx4 v141, s[12:15], s69 offen lds
	s_mov_b32 m0, s41
	s_nop 0
	buffer_load_dwordx4 v138, s[8:11], s68 offen lds
	s_mov_b32 m0, s42
	s_nop 0
	buffer_load_dwordx4 v140, s[8:11], s68 offen lds
	s_waitcnt vmcnt(8)
	s_waitcnt lgkmcnt(0)
	s_barrier
	s_setprio 1
	s_waitcnt lgkmcnt(7)
	v_mfma_f32_16x16x32_bf16 v[60:63], v[132:135], v[178:181], v[60:63]
	v_mfma_f32_16x16x32_bf16 v[56:59], v[154:157], v[178:181], v[56:59]
	s_waitcnt lgkmcnt(5)
	v_mfma_f32_16x16x32_bf16 v[48:51], v[132:135], v[186:189], v[48:51]
	v_mfma_f32_16x16x32_bf16 v[40:43], v[154:157], v[186:189], v[40:43]
	s_waitcnt lgkmcnt(3)
	v_mfma_f32_16x16x32_bf16 v[32:35], v[132:135], v[194:197], v[32:35]
	v_mfma_f32_16x16x32_bf16 v[24:27], v[154:157], v[194:197], v[24:27]
	s_waitcnt lgkmcnt(1)
	v_mfma_f32_16x16x32_bf16 v[16:19], v[132:135], v[202:205], v[16:19]
	v_mfma_f32_16x16x32_bf16 v[8:11], v[154:157], v[202:205], v[8:11]
	v_mfma_f32_16x16x32_bf16 v[60:63], v[150:153], v[182:185], v[60:63]
	v_mfma_f32_16x16x32_bf16 v[56:59], v[158:161], v[182:185], v[56:59]
	v_mfma_f32_16x16x32_bf16 v[48:51], v[150:153], v[190:193], v[48:51]
	v_mfma_f32_16x16x32_bf16 v[40:43], v[158:161], v[190:193], v[40:43]
	v_mfma_f32_16x16x32_bf16 v[32:35], v[150:153], v[198:201], v[32:35]
	v_mfma_f32_16x16x32_bf16 v[24:27], v[158:161], v[198:201], v[24:27]
	s_waitcnt lgkmcnt(0)
	v_mfma_f32_16x16x32_bf16 v[16:19], v[150:153], v[206:209], v[16:19]
	v_mfma_f32_16x16x32_bf16 v[8:11], v[158:161], v[206:209], v[8:11]
	s_setprio 0
	s_setprio 1
	v_mfma_f32_16x16x32_bf16 v[52:55], v[162:165], v[178:181], v[52:55]
	v_mfma_f32_16x16x32_bf16 v[44:47], v[170:173], v[178:181], v[44:47]
	v_mfma_f32_16x16x32_bf16 v[36:39], v[162:165], v[186:189], v[36:39]
	v_mfma_f32_16x16x32_bf16 v[28:31], v[170:173], v[186:189], v[28:31]
	v_mfma_f32_16x16x32_bf16 v[20:23], v[162:165], v[194:197], v[20:23]
	v_mfma_f32_16x16x32_bf16 v[12:15], v[170:173], v[194:197], v[12:15]
	v_mfma_f32_16x16x32_bf16 v[4:7], v[162:165], v[202:205], v[4:7]
	v_mfma_f32_16x16x32_bf16 v[0:3], v[170:173], v[202:205], v[0:3]
	v_mfma_f32_16x16x32_bf16 v[52:55], v[166:169], v[182:185], v[52:55]
	v_mfma_f32_16x16x32_bf16 v[44:47], v[174:177], v[182:185], v[44:47]
	v_mfma_f32_16x16x32_bf16 v[36:39], v[166:169], v[190:193], v[36:39]
	v_mfma_f32_16x16x32_bf16 v[28:31], v[174:177], v[190:193], v[28:31]
	v_mfma_f32_16x16x32_bf16 v[20:23], v[166:169], v[198:201], v[20:23]
	v_mfma_f32_16x16x32_bf16 v[12:15], v[174:177], v[198:201], v[12:15]
	v_mfma_f32_16x16x32_bf16 v[4:7], v[166:169], v[206:209], v[4:7]
	v_mfma_f32_16x16x32_bf16 v[0:3], v[174:177], v[206:209], v[0:3]
	s_setprio 0
	s_add_i32 s67, s67, 2
	s_addk_i32 s65, 0x100
	s_addk_i32 s66, 0x100
	s_cmp_gt_u32 s67, 29
	s_cbranch_scc0 .Lrot_2575
	s_barrier
	s_and_b64 vcc, exec, s[18:19]
	s_cbranch_vccz .LBB0_2578
	s_barrier

; #define PG8_STAGE(bufoff, soff, voff) do { _Pragma("unroll") for (int _i = 0; _i < 2; ++_i) \
;         __builtin_amdgcn_raw_ptr_buffer_load_lds(rs_##voff, (PG8_LAS unsigned*)(lds + (bufoff) + ldsw + _i * 8192), 16, (int)(voff)[_i], (int)(soff), 0, 0); } while (0)
; #define PG8_LDA(dst, b, h) do { _Pragma("unroll") for (int m = 0; m < 4; ++m) _Pragma("unroll") for (int k = 0; k < 2; ++k) dst[m][k] = *(const PG8_LAS bf16x8*)(lds + PG8_SA(b, h) + aoff + m * 2048 + k * 1024); } while (0)
; #define PG8_LDB(dst, b, h) do { _Pragma("unroll") for (int n = 0; n < 2; ++n) _Pragma("unroll") for (int k = 0; k < 2; ++k) dst[n][k] = *(const PG8_LAS bf16x8*)(lds + PG8_SB(b, h) + boff + n * 2048 + k * 1024); } while (0)
; #define PG8_MMA(ai, bj, At, Bt) do { __builtin_amdgcn_s_setprio(1); _Pragma("unroll") for (int m = 0; m < 4; ++m) _Pragma("unroll") for (int n = 0; n < 2; ++n) _Pragma("unroll") for (int k = 0; k < 2; ++k) \
;         acc[ai][bj][m][n] = __builtin_amdgcn_mfma_f32_16x16x32_bf16(Bt[n][k], At[m][k], acc[ai][bj][m][n], 0, 0, 0); __builtin_amdgcn_s_setprio(0); } while (0)
; #define PG8_WAIT_V(n) asm volatile("s_waitcnt vmcnt(" #n ")" ::: "memory")
; #define PG8_BAR __builtin_amdgcn_s_barrier()
; template <class Epi, class Sched, bool ALIGN_EPI = false, bool SP2 = false>
; __device__ __forceinline__ void gemm_phase(PG8_LAS unsigned char* lds, const Gemm g, const Sched& S, const Epi& E, const int wid  ) {
;     ...
;         for (int t = 0; t < nt; t += 2) {
;             const bool last = (t == nt - 2);
;             const unsigned a1 = cA + (unsigned)(t + 1) * kstep;
;             const unsigned a2 = last ? nA : cA + (unsigned)(t + 2) * kstep, b2 = last ? nB : cB + (unsigned)(t + 2) * kstep;
;             const unsigned a3 = a2 + kstep, b3 = b2 + kstep;
;             if (last && has_next) S.a_ready(nxt);
;             if constexpr (SP2) {
;             PG8_LDB(B0, 0, 0); PG8_LDB(B1, 0, 1); PG8_SCHED; PG8_LDA(At, 0, 0); PG8_STAGE(PG8_SA(1, 1), a1 + hstep, voffA);
;             PG8_WAIT_V(8); PG8_WAIT_L(0); PG8_BAR; PG8_MMA(0, 0, At, B0); PG8_MMA(0, 1, At, B1); PG8_BAR; PG8_SCHED;
;             PG8_LDA(At, 0, 1); PG8_STAGE(PG8_SB(0, 0), b2, voffB); PG8_STAGE(PG8_SB(0, 1), b2 + hstep, voffB); PG8_STAGE(PG8_SA(0, 0), a2, voffA);
;             PG8_WAIT_V(8); PG8_WAIT_L(0); PG8_BAR; PG8_MMA(1, 0, At, B0); PG8_MMA(1, 1, At, B1); PG8_BAR; PG8_SCHED;
.LBB0_2813:
	s_waitcnt lgkmcnt(0)
	ds_read_b128 v[16:19], v188
	ds_read_b128 v[20:23], v188 offset:1024
	ds_read_b128 v[24:27], v188 offset:2048
	ds_read_b128 v[28:31], v188 offset:3072
	ds_read_b128 v[32:35], v189
	ds_read_b128 v[36:39], v189 offset:1024
	ds_read_b128 v[40:43], v189 offset:2048
	ds_read_b128 v[44:47], v189 offset:3072
	s_add_i32 s18, s8, 0xfff80080
	s_cmp_eq_u32 s48, 28
	s_cselect_b32 s93, s6, s18
	s_cselect_b32 s92, s7, s9
	s_or_b32 s49, s93, 0x80
	s_mov_b32 m0, s74
	ds_read_b128 v[160:163], v190
	ds_read_b128 v[170:173], v190 offset:1024
	ds_read_b128 v[174:177], v190 offset:2048
	ds_read_b128 v[178:181], v190 offset:3072
	ds_read_b128 v[194:197], v190 offset:4096
	ds_read_b128 v[198:201], v190 offset:5120
	ds_read_b128 v[202:205], v190 offset:6144
	ds_read_b128 v[206:209], v190 offset:7168
	buffer_load_dwordx4 v182, s[12:15], s8 offen lds
	s_mov_b32 m0, s76
	s_nop 0
	buffer_load_dwordx4 v184, s[12:15], s8 offen lds
	s_waitcnt vmcnt(8)
	s_waitcnt lgkmcnt(0)
	s_barrier
	s_setprio 1
	s_waitcnt lgkmcnt(7)
	v_mfma_f32_16x16x32_bf16 v[152:155], v[16:19], v[160:163], v[152:155]
	v_mfma_f32_16x16x32_bf16 v[52:55], v[24:27], v[160:163], v[52:55]
	s_waitcnt lgkmcnt(5)
	v_mfma_f32_16x16x32_bf16 v[148:151], v[16:19], v[174:177], v[148:151]
	v_mfma_f32_16x16x32_bf16 v[144:147], v[24:27], v[174:177], v[144:147]
	s_waitcnt lgkmcnt(3)
	v_mfma_f32_16x16x32_bf16 v[140:143], v[16:19], v[194:197], v[140:143]
	v_mfma_f32_16x16x32_bf16 v[132:135], v[24:27], v[194:197], v[132:135]
	s_waitcnt lgkmcnt(1)
	v_mfma_f32_16x16x32_bf16 v[156:159], v[16:19], v[202:205], v[156:159]
	v_mfma_f32_16x16x32_bf16 v[120:123], v[24:27], v[202:205], v[120:123]
	v_mfma_f32_16x16x32_bf16 v[152:155], v[20:23], v[170:173], v[152:155]
	v_mfma_f32_16x16x32_bf16 v[52:55], v[28:31], v[170:173], v[52:55]
	v_mfma_f32_16x16x32_bf16 v[148:151], v[20:23], v[178:181], v[148:151]
	v_mfma_f32_16x16x32_bf16 v[144:147], v[28:31], v[178:181], v[144:147]
	v_mfma_f32_16x16x32_bf16 v[140:143], v[20:23], v[198:201], v[140:143]
	v_mfma_f32_16x16x32_bf16 v[132:135], v[28:31], v[198:201], v[132:135]
	s_waitcnt lgkmcnt(0)
	v_mfma_f32_16x16x32_bf16 v[156:159], v[20:23], v[206:209], v[156:159]
	v_mfma_f32_16x16x32_bf16 v[120:123], v[28:31], v[206:209], v[120:123]
	s_setprio 0
	s_setprio 1
	v_mfma_f32_16x16x32_bf16 v[12:15], v[32:35], v[160:163], v[12:15]
	v_mfma_f32_16x16x32_bf16 v[8:11], v[40:43], v[160:163], v[8:11]
	v_mfma_f32_16x16x32_bf16 v[136:139], v[32:35], v[174:177], v[136:139]
	v_mfma_f32_16x16x32_bf16 v[128:131], v[40:43], v[174:177], v[128:131]
	v_mfma_f32_16x16x32_bf16 v[124:127], v[32:35], v[194:197], v[124:127]
	v_mfma_f32_16x16x32_bf16 v[116:119], v[40:43], v[194:197], v[116:119]
	v_mfma_f32_16x16x32_bf16 v[112:115], v[32:35], v[202:205], v[112:115]
	v_mfma_f32_16x16x32_bf16 v[108:111], v[40:43], v[202:205], v[108:111]
	v_mfma_f32_16x16x32_bf16 v[12:15], v[36:39], v[170:173], v[12:15]
	v_mfma_f32_16x16x32_bf16 v[8:11], v[44:47], v[170:173], v[8:11]
	v_mfma_f32_16x16x32_bf16 v[136:139], v[36:39], v[178:181], v[136:139]
	v_mfma_f32_16x16x32_bf16 v[128:131], v[44:47], v[178:181], v[128:131]
	v_mfma_f32_16x16x32_bf16 v[124:127], v[36:39], v[198:201], v[124:127]
	v_mfma_f32_16x16x32_bf16 v[116:119], v[44:47], v[198:201], v[116:119]
	v_mfma_f32_16x16x32_bf16 v[112:115], v[36:39], v[206:209], v[112:115]
	v_mfma_f32_16x16x32_bf16 v[108:111], v[44:47], v[206:209], v[108:111]
	s_setprio 0
	s_barrier
	s_mov_b32 m0, s34
	s_mov_b32 s18, s14
	s_mov_b32 s19, s15
	ds_read_b128 v[160:163], v190 offset:16384
	ds_read_b128 v[170:173], v190 offset:17408
	ds_read_b128 v[174:177], v190 offset:18432
	ds_read_b128 v[178:181], v190 offset:19456
	ds_read_b128 v[194:197], v190 offset:20480
	ds_read_b128 v[198:201], v190 offset:21504
	ds_read_b128 v[202:205], v190 offset:22528
	ds_read_b128 v[206:209], v190 offset:23552
	buffer_load_dwordx4 v183, s[16:19], s92 offen lds
	s_mov_b32 m0, s35
	s_add_i32 s94, s92, 0x80000
	buffer_load_dwordx4 v185, s[16:19], s92 offen lds
	s_mov_b32 m0, s50
	s_nop 0
	buffer_load_dwordx4 v183, s[16:19], s94 offen lds
	s_mov_b32 m0, s51
	s_nop 0
	buffer_load_dwordx4 v185, s[16:19], s94 offen lds
	s_mov_b32 m0, s33
	s_nop 0
	buffer_load_dwordx4 v182, s[12:15], s93 offen lds
	s_mov_b32 m0, s53
	s_nop 0
	buffer_load_dwordx4 v184, s[12:15], s93 offen lds
	s_waitcnt vmcnt(8)
	s_waitcnt lgkmcnt(0)
	s_barrier
	s_setprio 1
	s_waitcnt lgkmcnt(7)
	v_mfma_f32_16x16x32_bf16 v[104:107], v[16:19], v[160:163], v[104:107]
	v_mfma_f32_16x16x32_bf16 v[100:103], v[24:27], v[160:163], v[100:103]
	s_waitcnt lgkmcnt(5)
	v_mfma_f32_16x16x32_bf16 v[96:99], v[16:19], v[174:177], v[96:99]
	v_mfma_f32_16x16x32_bf16 v[88:91], v[24:27], v[174:177], v[88:91]
	s_waitcnt lgkmcnt(3)
	v_mfma_f32_16x16x32_bf16 v[84:87], v[16:19], v[194:197], v[84:87]
	v_mfma_f32_16x16x32_bf16 v[76:79], v[24:27], v[194:197], v[76:79]
	s_waitcnt lgkmcnt(1)
	v_mfma_f32_16x16x32_bf16 v[16:19], v[16:19], v[202:205], v[92:95]
	v_mfma_f32_16x16x32_bf16 v[104:107], v[20:23], v[170:173], v[104:107]
	v_mfma_f32_16x16x32_bf16 v[100:103], v[28:31], v[170:173], v[100:103]
	v_mfma_f32_16x16x32_bf16 v[96:99], v[20:23], v[178:181], v[96:99]
	v_mfma_f32_16x16x32_bf16 v[88:91], v[28:31], v[178:181], v[88:91]
	v_mfma_f32_16x16x32_bf16 v[84:87], v[20:23], v[198:201], v[84:87]
	v_mfma_f32_16x16x32_bf16 v[76:79], v[28:31], v[198:201], v[76:79]
	s_waitcnt lgkmcnt(0)
	v_mfma_f32_16x16x32_bf16 v[16:19], v[20:23], v[206:209], v[16:19]
	v_mfma_f32_16x16x32_bf16 v[20:23], v[24:27], v[202:205], v[48:51]
	v_mfma_f32_16x16x32_bf16 v[20:23], v[28:31], v[206:209], v[20:23]
	s_setprio 0
	s_setprio 1
	v_mfma_f32_16x16x32_bf16 v[48:51], v[32:35], v[194:197], v[68:71]
	v_mfma_f32_16x16x32_bf16 v[4:7], v[32:35], v[160:163], v[4:7]
	v_mfma_f32_16x16x32_bf16 v[0:3], v[40:43], v[160:163], v[0:3]
	v_mfma_f32_16x16x32_bf16 v[24:27], v[32:35], v[174:177], v[80:83]
	v_mfma_f32_16x16x32_bf16 v[68:71], v[36:39], v[198:201], v[48:51]
	v_mfma_f32_16x16x32_bf16 v[48:51], v[40:43], v[194:197], v[64:67]
	v_mfma_f32_16x16x32_bf16 v[32:35], v[32:35], v[202:205], v[60:63]
	v_mfma_f32_16x16x32_bf16 v[4:7], v[36:39], v[170:173], v[4:7]
	v_mfma_f32_16x16x32_bf16 v[0:3], v[44:47], v[170:173], v[0:3]
	v_mfma_f32_16x16x32_bf16 v[24:27], v[36:39], v[178:181], v[24:27]
	v_mfma_f32_16x16x32_bf16 v[28:31], v[40:43], v[174:177], v[72:75]
	v_mfma_f32_16x16x32_bf16 v[64:67], v[44:47], v[198:201], v[48:51]
	v_mfma_f32_16x16x32_bf16 v[32:35], v[36:39], v[206:209], v[32:35]
	v_mfma_f32_16x16x32_bf16 v[36:39], v[40:43], v[202:205], v[56:59]
	v_mfma_f32_16x16x32_bf16 v[28:31], v[44:47], v[178:181], v[28:31]
	v_mfma_f32_16x16x32_bf16 v[36:39], v[44:47], v[206:209], v[36:39]
	s_setprio 0
	s_barrier
; #define PG8_STAGE(bufoff, soff, voff) do { _Pragma("unroll") for (int _i = 0; _i < 2; ++_i) \
;         __builtin_amdgcn_raw_ptr_buffer_load_lds(rs_##voff, (PG8_LAS unsigned*)(lds + (bufoff) + ldsw + _i * 8192), 16, (int)(voff)[_i], (int)(soff), 0, 0); } while (0)
; #define PG8_LDA(dst, b, h) do { _Pragma("unroll") for (int m = 0; m < 4; ++m) _Pragma("unroll") for (int k = 0; k < 2; ++k) dst[m][k] = *(const PG8_LAS bf16x8*)(lds + PG8_SA(b, h) + aoff + m * 2048 + k * 1024); } while (0)
; #define PG8_LDB(dst, b, h) do { _Pragma("unroll") for (int n = 0; n < 2; ++n) _Pragma("unroll") for (int k = 0; k < 2; ++k) dst[n][k] = *(const PG8_LAS bf16x8*)(lds + PG8_SB(b, h) + boff + n * 2048 + k * 1024); } while (0)
; #define PG8_MMA(ai, bj, At, Bt) do { __builtin_amdgcn_s_setprio(1); _Pragma("unroll") for (int m = 0; m < 4; ++m) _Pragma("unroll") for (int n = 0; n < 2; ++n) _Pragma("unroll") for (int k = 0; k < 2; ++k) \
;         acc[ai][bj][m][n] = __builtin_amdgcn_mfma_f32_16x16x32_bf16(Bt[n][k], At[m][k], acc[ai][bj][m][n], 0, 0, 0); __builtin_amdgcn_s_setprio(0); } while (0)
; #define PG8_WAIT_V(n) asm volatile("s_waitcnt vmcnt(" #n ")" ::: "memory")
; #define PG8_WAIT_L(n) asm volatile("s_waitcnt lgkmcnt(" #n ")" ::: "memory")
; #define PG8_BAR __builtin_amdgcn_s_barrier()
; #define PG8_SCHED __builtin_amdgcn_sched_barrier(0)
; template <class Epi, class Sched, bool ALIGN_EPI = false, bool SP2 = false>
; __device__ __forceinline__ void gemm_phase(PG8_LAS unsigned char* lds, const Gemm g, const Sched& S, const Epi& E, const int wid  ) {
;     ...
;             PG8_LDB(B0, 1, 0); PG8_LDB(B1, 1, 1); PG8_SCHED; PG8_LDA(At, 1, 0); PG8_STAGE(PG8_SA(0, 1), a2 + hstep, voffA);
;             PG8_WAIT_V(8); PG8_WAIT_L(0); PG8_BAR; PG8_MMA(0, 0, At, B0); PG8_MMA(0, 1, At, B1); PG8_BAR; PG8_SCHED;
;             PG8_LDA(At, 1, 1); PG8_STAGE(PG8_SB(1, 0), b3, voffB); PG8_STAGE(PG8_SB(1, 1), b3 + hstep, voffB); PG8_STAGE(PG8_SA(1, 0), a3, voffA);
;             PG8_WAIT_V(8); PG8_WAIT_L(0); PG8_BAR; PG8_MMA(1, 0, At, B0); PG8_MMA(1, 1, At, B1); PG8_BAR; PG8_SCHED;
;     ...
;         if constexpr (ALIGN_EPI) { if (wr == 0) PG8_BAR; }
	ds_read_b128 v[40:43], v191
	ds_read_b128 v[44:47], v191 offset:1024
	ds_read_b128 v[48:51], v191 offset:2048
	ds_read_b128 v[56:59], v191 offset:3072
	ds_read_b128 v[60:63], v192
	ds_read_b128 v[160:163], v192 offset:1024
	ds_read_b128 v[170:173], v192 offset:2048
	ds_read_b128 v[174:177], v192 offset:3072
	s_add_i32 s93, s93, 0x80000
	s_mov_b32 m0, s54
	ds_read_b128 v[72:75], v190 offset:32768
	ds_read_b128 v[80:83], v190 offset:33792
	ds_read_b128 v[92:95], v190 offset:34816
	ds_read_b128 v[178:181], v190 offset:35840
	ds_read_b128 v[194:197], v190 offset:36864
	ds_read_b128 v[198:201], v190 offset:37888
	ds_read_b128 v[202:205], v190 offset:38912
	ds_read_b128 v[206:209], v190 offset:39936
	buffer_load_dwordx4 v182, s[12:15], s93 offen lds
	s_mov_b32 m0, s58
	s_nop 0
	buffer_load_dwordx4 v184, s[12:15], s93 offen lds
	s_waitcnt vmcnt(8)
	s_waitcnt lgkmcnt(0)
	s_barrier
	s_setprio 1
	s_waitcnt lgkmcnt(7)
	v_mfma_f32_16x16x32_bf16 v[152:155], v[40:43], v[72:75], v[152:155]
	v_mfma_f32_16x16x32_bf16 v[52:55], v[48:51], v[72:75], v[52:55]
	s_waitcnt lgkmcnt(5)
	v_mfma_f32_16x16x32_bf16 v[148:151], v[40:43], v[92:95], v[148:151]
	v_mfma_f32_16x16x32_bf16 v[144:147], v[48:51], v[92:95], v[144:147]
	s_waitcnt lgkmcnt(3)
	v_mfma_f32_16x16x32_bf16 v[140:143], v[40:43], v[194:197], v[140:143]
	v_mfma_f32_16x16x32_bf16 v[132:135], v[48:51], v[194:197], v[132:135]
	s_waitcnt lgkmcnt(1)
	v_mfma_f32_16x16x32_bf16 v[156:159], v[40:43], v[202:205], v[156:159]
	v_mfma_f32_16x16x32_bf16 v[120:123], v[48:51], v[202:205], v[120:123]
	v_mfma_f32_16x16x32_bf16 v[152:155], v[44:47], v[80:83], v[152:155]
	v_mfma_f32_16x16x32_bf16 v[52:55], v[56:59], v[80:83], v[52:55]
	v_mfma_f32_16x16x32_bf16 v[148:151], v[44:47], v[178:181], v[148:151]
	v_mfma_f32_16x16x32_bf16 v[144:147], v[56:59], v[178:181], v[144:147]
	v_mfma_f32_16x16x32_bf16 v[140:143], v[44:47], v[198:201], v[140:143]
	v_mfma_f32_16x16x32_bf16 v[132:135], v[56:59], v[198:201], v[132:135]
	s_waitcnt lgkmcnt(0)
	v_mfma_f32_16x16x32_bf16 v[156:159], v[44:47], v[206:209], v[156:159]
	v_mfma_f32_16x16x32_bf16 v[120:123], v[56:59], v[206:209], v[120:123]
	s_setprio 0
	s_setprio 1
	v_mfma_f32_16x16x32_bf16 v[12:15], v[60:63], v[72:75], v[12:15]
	v_mfma_f32_16x16x32_bf16 v[8:11], v[170:173], v[72:75], v[8:11]
	v_mfma_f32_16x16x32_bf16 v[72:75], v[60:63], v[92:95], v[136:139]
	v_mfma_f32_16x16x32_bf16 v[136:139], v[160:163], v[178:181], v[72:75]
	v_mfma_f32_16x16x32_bf16 v[72:75], v[170:173], v[92:95], v[128:131]
	v_mfma_f32_16x16x32_bf16 v[128:131], v[174:177], v[178:181], v[72:75]
	v_mfma_f32_16x16x32_bf16 v[72:75], v[60:63], v[194:197], v[124:127]
	v_mfma_f32_16x16x32_bf16 v[124:127], v[160:163], v[198:201], v[72:75]
	v_mfma_f32_16x16x32_bf16 v[72:75], v[170:173], v[194:197], v[116:119]
	v_mfma_f32_16x16x32_bf16 v[116:119], v[174:177], v[198:201], v[72:75]
	v_mfma_f32_16x16x32_bf16 v[72:75], v[60:63], v[202:205], v[112:115]
	v_mfma_f32_16x16x32_bf16 v[112:115], v[160:163], v[206:209], v[72:75]
	v_mfma_f32_16x16x32_bf16 v[72:75], v[170:173], v[202:205], v[108:111]
	v_mfma_f32_16x16x32_bf16 v[12:15], v[160:163], v[80:83], v[12:15]
	v_mfma_f32_16x16x32_bf16 v[8:11], v[174:177], v[80:83], v[8:11]
	v_mfma_f32_16x16x32_bf16 v[108:111], v[174:177], v[206:209], v[72:75]
	s_setprio 0
	s_barrier
	s_mov_b32 m0, s63
	s_or_b32 s93, s92, 0x80
	s_nop 0
	ds_read_b128 v[72:75], v190 offset:49152
	ds_read_b128 v[80:83], v190 offset:50176
	ds_read_b128 v[178:181], v190 offset:51200
	ds_read_b128 v[194:197], v190 offset:52224
	ds_read_b128 v[198:201], v190 offset:53248
	ds_read_b128 v[202:205], v190 offset:54272
	ds_read_b128 v[206:209], v190 offset:55296
	ds_read_b128 v[210:213], v190 offset:56320
	buffer_load_dwordx4 v183, s[16:19], s93 offen lds
	s_mov_b32 m0, s65
	s_add_i32 s92, s92, 0x80080
	buffer_load_dwordx4 v185, s[16:19], s93 offen lds
	s_mov_b32 m0, s68
	s_nop 0
	buffer_load_dwordx4 v183, s[16:19], s92 offen lds
	s_mov_b32 m0, s69
	s_nop 0
	buffer_load_dwordx4 v185, s[16:19], s92 offen lds
	s_mov_b32 m0, s66
	s_nop 0
	buffer_load_dwordx4 v182, s[12:15], s49 offen lds
	s_mov_b32 m0, s67
	s_nop 0
	buffer_load_dwordx4 v184, s[12:15], s49 offen lds
	s_waitcnt vmcnt(8)
	s_waitcnt lgkmcnt(0)
	s_barrier
	s_setprio 1
	s_waitcnt lgkmcnt(7)
	v_mfma_f32_16x16x32_bf16 v[92:95], v[40:43], v[72:75], v[104:107]
	s_waitcnt lgkmcnt(6)
	v_mfma_f32_16x16x32_bf16 v[104:107], v[44:47], v[80:83], v[92:95]
	v_mfma_f32_16x16x32_bf16 v[92:95], v[48:51], v[72:75], v[100:103]
	v_mfma_f32_16x16x32_bf16 v[100:103], v[56:59], v[80:83], v[92:95]
	s_waitcnt lgkmcnt(5)
	v_mfma_f32_16x16x32_bf16 v[92:95], v[40:43], v[178:181], v[96:99]
	s_waitcnt lgkmcnt(1)
	v_mfma_f32_16x16x32_bf16 v[16:19], v[40:43], v[206:209], v[16:19]
	v_mfma_f32_16x16x32_bf16 v[96:99], v[44:47], v[194:197], v[92:95]
	v_mfma_f32_16x16x32_bf16 v[88:91], v[48:51], v[178:181], v[88:91]
	v_mfma_f32_16x16x32_bf16 v[84:87], v[40:43], v[198:201], v[84:87]
	v_mfma_f32_16x16x32_bf16 v[76:79], v[48:51], v[198:201], v[76:79]
	s_waitcnt lgkmcnt(0)
	v_mfma_f32_16x16x32_bf16 v[92:95], v[44:47], v[210:213], v[16:19]
	v_mfma_f32_16x16x32_bf16 v[16:19], v[48:51], v[206:209], v[20:23]
	v_mfma_f32_16x16x32_bf16 v[88:91], v[56:59], v[194:197], v[88:91]
	v_mfma_f32_16x16x32_bf16 v[84:87], v[44:47], v[202:205], v[84:87]
	v_mfma_f32_16x16x32_bf16 v[76:79], v[56:59], v[202:205], v[76:79]
	v_mfma_f32_16x16x32_bf16 v[48:51], v[56:59], v[210:213], v[16:19]
	s_setprio 0
	s_setprio 1
	v_mfma_f32_16x16x32_bf16 v[4:7], v[60:63], v[72:75], v[4:7]
	v_mfma_f32_16x16x32_bf16 v[0:3], v[170:173], v[72:75], v[0:3]
	v_mfma_f32_16x16x32_bf16 v[16:19], v[60:63], v[178:181], v[24:27]
	v_mfma_f32_16x16x32_bf16 v[4:7], v[160:163], v[80:83], v[4:7]
	v_mfma_f32_16x16x32_bf16 v[0:3], v[174:177], v[80:83], v[0:3]
	v_mfma_f32_16x16x32_bf16 v[80:83], v[160:163], v[194:197], v[16:19]
	v_mfma_f32_16x16x32_bf16 v[16:19], v[170:173], v[178:181], v[28:31]
	v_mfma_f32_16x16x32_bf16 v[72:75], v[174:177], v[194:197], v[16:19]
	v_mfma_f32_16x16x32_bf16 v[16:19], v[60:63], v[198:201], v[68:71]
	v_mfma_f32_16x16x32_bf16 v[68:71], v[160:163], v[202:205], v[16:19]
	v_mfma_f32_16x16x32_bf16 v[16:19], v[170:173], v[198:201], v[64:67]
	v_mfma_f32_16x16x32_bf16 v[64:67], v[174:177], v[202:205], v[16:19]
	v_mfma_f32_16x16x32_bf16 v[16:19], v[60:63], v[206:209], v[32:35]
	v_mfma_f32_16x16x32_bf16 v[60:63], v[160:163], v[210:213], v[16:19]
	v_mfma_f32_16x16x32_bf16 v[16:19], v[170:173], v[206:209], v[36:39]
	v_mfma_f32_16x16x32_bf16 v[56:59], v[174:177], v[210:213], v[16:19]
	s_setprio 0
	s_add_i32 s48, s48, 2
	s_addk_i32 s8, 0x100
	s_addk_i32 s9, 0x100
	s_cmp_gt_u32 s48, 29
	s_cbranch_scc0 .Lrot_2813
	s_barrier
	s_and_b64 vcc, exec, s[26:27]
	s_cbranch_vccz .LBB0_2816
	s_barrier

; template <class Epi, class Sched, bool ALIGN_EPI = false, bool SP2 = false>
; __device__ __forceinline__ void gemm_phase(PG8_LAS unsigned char* lds, const Gemm g, const Sched& S, const Epi& E, const int wid  ) {
;     ...
;         const bool has_next = S.next(ui + 1, nxt); nxt.same = (has_next && nxt.pm == cur.pm) ? 1 : 0;
;         const unsigned nA = has_next ? (unsigned)g.asel(nxt.pn) * (unsigned)g.a_stride + (unsigned)nxt.pm * tstep : cA, nB = has_next ? (unsigned)nxt.pn * tstep : cB;
;         for (int t = 0; t < nt; t += 2) {
;             const bool last = (t == nt - 2);
;             const unsigned a1 = cA + (unsigned)(t + 1) * kstep;
;             const unsigned a2 = last ? nA : cA + (unsigned)(t + 2) * kstep, b2 = last ? nB : cB + (unsigned)(t + 2) * kstep;
;             const unsigned a3 = a2 + kstep, b3 = b2 + kstep;
;     ...
; #pragma unroll
;         for (int a = 0; a < 2; ++a)
; #pragma unroll
;             for (int b = 0; b < 2; ++b)
; #pragma unroll
;                 for (int m = 0; m < 4; ++m)
; #pragma unroll
;                     for (int n = 0; n < 2; ++n) acc[a][b][m][n] = (f32x4){0.f, 0.f, 0.f, 0.f};
;         cur = nxt; cA = nA; cB = nB; ++ui;
.LBB0_4015:
	s_lshl_b32 s70, s69, 20
	s_and_b64 s[14:15], s[4:5], exec
	s_cselect_b32 s33, s70, s41
	s_lshl_b32 s71, s68, 20
	s_and_b64 s[14:15], s[4:5], exec
	v_mov_b32_e32 v0, 0
	s_cselect_b32 s40, s71, s73
	s_add_i32 s41, s41, 0x80080
	s_add_i32 s72, s73, 0x100
	s_mov_b32 s73, -2
	s_waitcnt lgkmcnt(0)
	v_mov_b32_e32 v1, v0
	v_mov_b32_e32 v2, v0
	v_mov_b32_e32 v3, v0
	v_mov_b32_e32 v4, v0
	v_mov_b32_e32 v5, v0
	s_waitcnt lgkmcnt(6)
	v_mov_b32_e32 v6, v0
	v_mov_b32_e32 v7, v0
	s_waitcnt lgkmcnt(1)
	v_mov_b32_e32 v16, v0
	v_mov_b32_e32 v17, v0
	s_waitcnt lgkmcnt(0)
	v_mov_b32_e32 v18, v0
	v_mov_b32_e32 v19, v0
	v_mov_b32_e32 v20, v0
	v_mov_b32_e32 v21, v0
	v_mov_b32_e32 v22, v0
	v_mov_b32_e32 v23, v0
	v_mov_b32_e32 v32, v0
	v_mov_b32_e32 v33, v0
	v_mov_b32_e32 v34, v0
	v_mov_b32_e32 v35, v0
	v_mov_b32_e32 v36, v0
	v_mov_b32_e32 v37, v0
	v_mov_b32_e32 v38, v0
	v_mov_b32_e32 v39, v0
	v_mov_b32_e32 v48, v0
	v_mov_b32_e32 v49, v0
	v_mov_b32_e32 v50, v0
	v_mov_b32_e32 v51, v0
	v_mov_b32_e32 v52, v0
	v_mov_b32_e32 v53, v0
	v_mov_b32_e32 v54, v0
	v_mov_b32_e32 v55, v0
	v_mov_b32_e32 v8, v0
	v_mov_b32_e32 v9, v0
	v_mov_b32_e32 v10, v0
	v_mov_b32_e32 v11, v0
	v_mov_b32_e32 v12, v0
	v_mov_b32_e32 v13, v0
	v_mov_b32_e32 v14, v0
	v_mov_b32_e32 v15, v0
	v_mov_b32_e32 v24, v0
	v_mov_b32_e32 v25, v0
	v_mov_b32_e32 v26, v0
	v_mov_b32_e32 v27, v0
	v_mov_b32_e32 v28, v0
	v_mov_b32_e32 v29, v0
	v_mov_b32_e32 v30, v0
	v_mov_b32_e32 v31, v0
	v_mov_b32_e32 v40, v0
	v_mov_b32_e32 v41, v0
	v_mov_b32_e32 v42, v0
	v_mov_b32_e32 v43, v0
	v_mov_b32_e32 v44, v0
	v_mov_b32_e32 v45, v0
	v_mov_b32_e32 v46, v0
	v_mov_b32_e32 v47, v0
	v_mov_b32_e32 v56, v0
	v_mov_b32_e32 v57, v0
	v_mov_b32_e32 v58, v0
	v_mov_b32_e32 v59, v0
	v_mov_b32_e32 v60, v0
	v_mov_b32_e32 v61, v0
	v_mov_b32_e32 v62, v0
	v_mov_b32_e32 v63, v0
	v_mov_b32_e32 v64, v0
	v_mov_b32_e32 v65, v0
	v_mov_b32_e32 v66, v0
	v_mov_b32_e32 v67, v0
	v_mov_b32_e32 v68, v0
	v_mov_b32_e32 v69, v0
	v_mov_b32_e32 v70, v0
	v_mov_b32_e32 v71, v0
	v_mov_b32_e32 v80, v0
	v_mov_b32_e32 v81, v0
	v_mov_b32_e32 v82, v0
	v_mov_b32_e32 v83, v0
	v_mov_b32_e32 v84, v0
	v_mov_b32_e32 v85, v0
	v_mov_b32_e32 v86, v0
	v_mov_b32_e32 v87, v0
	v_mov_b32_e32 v96, v0
	v_mov_b32_e32 v97, v0
	v_mov_b32_e32 v98, v0
	v_mov_b32_e32 v99, v0
	v_mov_b32_e32 v100, v0
	v_mov_b32_e32 v101, v0
	v_mov_b32_e32 v102, v0
	v_mov_b32_e32 v103, v0
	v_mov_b32_e32 v112, v0
	v_mov_b32_e32 v113, v0
	v_mov_b32_e32 v114, v0
	v_mov_b32_e32 v115, v0
	v_mov_b32_e32 v116, v0
	v_mov_b32_e32 v117, v0
	v_mov_b32_e32 v118, v0
	v_mov_b32_e32 v119, v0
	v_mov_b32_e32 v72, v0
	v_mov_b32_e32 v73, v0
	v_mov_b32_e32 v74, v0
	v_mov_b32_e32 v75, v0
	v_mov_b32_e32 v76, v0
	v_mov_b32_e32 v77, v0
	v_mov_b32_e32 v78, v0
	v_mov_b32_e32 v79, v0
	v_mov_b32_e32 v88, v0
	v_mov_b32_e32 v89, v0
	v_mov_b32_e32 v90, v0
	v_mov_b32_e32 v91, v0
	v_mov_b32_e32 v92, v0
	v_mov_b32_e32 v93, v0
	v_mov_b32_e32 v94, v0
	v_mov_b32_e32 v95, v0
	v_mov_b32_e32 v104, v0
	v_mov_b32_e32 v105, v0
	v_mov_b32_e32 v106, v0
	v_mov_b32_e32 v107, v0
	v_mov_b32_e32 v108, v0
	v_mov_b32_e32 v109, v0
	v_mov_b32_e32 v110, v0
	v_mov_b32_e32 v111, v0
	v_mov_b32_e32 v120, v0
	v_mov_b32_e32 v121, v0
	v_mov_b32_e32 v122, v0
	v_mov_b32_e32 v123, v0
	v_mov_b32_e32 v124, v0
	v_mov_b32_e32 v125, v0
	v_mov_b32_e32 v126, v0
	v_mov_b32_e32 v127, v0
	s_branch .LBB0_4016

; #define PG8_STAGE(bufoff, soff, voff) do { _Pragma("unroll") for (int _i = 0; _i < 2; ++_i) \
;         __builtin_amdgcn_raw_ptr_buffer_load_lds(rs_##voff, (PG8_LAS unsigned*)(lds + (bufoff) + ldsw + _i * 8192), 16, (int)(voff)[_i], (int)(soff), 0, 0); } while (0)
; #define PG8_LDA(dst, b, h) do { _Pragma("unroll") for (int m = 0; m < 4; ++m) _Pragma("unroll") for (int k = 0; k < 2; ++k) dst[m][k] = *(const PG8_LAS bf16x8*)(lds + PG8_SA(b, h) + aoff + m * 2048 + k * 1024); } while (0)
; #define PG8_LDB(dst, b, h) do { _Pragma("unroll") for (int n = 0; n < 2; ++n) _Pragma("unroll") for (int k = 0; k < 2; ++k) dst[n][k] = *(const PG8_LAS bf16x8*)(lds + PG8_SB(b, h) + boff + n * 2048 + k * 1024); } while (0)
; #define PG8_MMA(ai, bj, At, Bt) do { __builtin_amdgcn_s_setprio(1); _Pragma("unroll") for (int m = 0; m < 4; ++m) _Pragma("unroll") for (int n = 0; n < 2; ++n) _Pragma("unroll") for (int k = 0; k < 2; ++k) \
;         acc[ai][bj][m][n] = __builtin_amdgcn_mfma_f32_16x16x32_bf16(Bt[n][k], At[m][k], acc[ai][bj][m][n], 0, 0, 0); __builtin_amdgcn_s_setprio(0); } while (0)
; #define PG8_WAIT_V(n) asm volatile("s_waitcnt vmcnt(" #n ")" ::: "memory")
; #define PG8_WAIT_L(n) asm volatile("s_waitcnt lgkmcnt(" #n ")" ::: "memory")
; template <class Epi, class Sched, bool ALIGN_EPI = false, bool SP2 = false>
; __device__ __forceinline__ void gemm_phase(PG8_LAS unsigned char* lds, const Gemm g, const Sched& S, const Epi& E, const int wid  ) {
;     ...
;             const bool last = (t == nt - 2);
;             const unsigned a1 = cA + (unsigned)(t + 1) * kstep;
;             const unsigned a2 = last ? nA : cA + (unsigned)(t + 2) * kstep, b2 = last ? nB : cB + (unsigned)(t + 2) * kstep;
;             const unsigned a3 = a2 + kstep, b3 = b2 + kstep;
;             if (last && has_next) S.a_ready(nxt);
;             if constexpr (SP2) {
;             PG8_LDB(B0, 0, 0); PG8_LDB(B1, 0, 1); PG8_SCHED; PG8_LDA(At, 0, 0); PG8_STAGE(PG8_SA(1, 1), a1 + hstep, voffA);
;             PG8_WAIT_V(8); PG8_WAIT_L(0); PG8_BAR; PG8_MMA(0, 0, At, B0); PG8_MMA(0, 1, At, B1); PG8_BAR; PG8_SCHED;
;             PG8_LDA(At, 0, 1); PG8_STAGE(PG8_SB(0, 0), b2, voffB); PG8_STAGE(PG8_SB(0, 1), b2 + hstep, voffB); PG8_STAGE(PG8_SA(0, 0), a2, voffA);
;             PG8_WAIT_V(8); PG8_WAIT_L(0); PG8_BAR; PG8_MMA(1, 0, At, B0); PG8_MMA(1, 1, At, B1); PG8_BAR; PG8_SCHED;
.LBB0_4016:
	ds_read_b128 v[132:135], v152
	ds_read_b128 v[136:139], v152 offset:1024
	ds_read_b128 v[140:143], v152 offset:2048
	ds_read_b128 v[158:161], v152 offset:3072
	ds_read_b128 v[162:165], v153
	ds_read_b128 v[166:169], v153 offset:1024
	ds_read_b128 v[170:173], v153 offset:2048
	ds_read_b128 v[174:177], v153 offset:3072
	s_add_i32 s14, s41, 0xfff80080
	s_cmp_eq_u32 s73, 28
	s_cselect_b32 s76, s33, s14
	s_cselect_b32 s75, s40, s72
	s_or_b32 s74, s76, 0x80
	s_mov_b32 m0, s60
	ds_read_b128 v[178:181], v154
	ds_read_b128 v[182:185], v154 offset:1024
	ds_read_b128 v[186:189], v154 offset:2048
	ds_read_b128 v[190:193], v154 offset:3072
	ds_read_b128 v[194:197], v154 offset:4096
	ds_read_b128 v[198:201], v154 offset:5120
	ds_read_b128 v[202:205], v154 offset:6144
	ds_read_b128 v[206:209], v154 offset:7168
	buffer_load_dwordx4 v146, s[8:11], s41 offen lds
	s_mov_b32 m0, s61
	s_nop 0
	buffer_load_dwordx4 v148, s[8:11], s41 offen lds
	s_waitcnt vmcnt(8)
	s_waitcnt lgkmcnt(0)
	s_barrier
	s_setprio 1
	s_waitcnt lgkmcnt(7)
	v_mfma_f32_16x16x32_bf16 v[124:127], v[132:135], v[178:181], v[124:127]
	v_mfma_f32_16x16x32_bf16 v[120:123], v[140:143], v[178:181], v[120:123]
	s_waitcnt lgkmcnt(5)
	v_mfma_f32_16x16x32_bf16 v[108:111], v[132:135], v[186:189], v[108:111]
	v_mfma_f32_16x16x32_bf16 v[104:107], v[140:143], v[186:189], v[104:107]
	s_waitcnt lgkmcnt(3)
	v_mfma_f32_16x16x32_bf16 v[92:95], v[132:135], v[194:197], v[92:95]
	v_mfma_f32_16x16x32_bf16 v[88:91], v[140:143], v[194:197], v[88:91]
	s_waitcnt lgkmcnt(1)
	v_mfma_f32_16x16x32_bf16 v[76:79], v[132:135], v[202:205], v[76:79]
	v_mfma_f32_16x16x32_bf16 v[72:75], v[140:143], v[202:205], v[72:75]
	v_mfma_f32_16x16x32_bf16 v[124:127], v[136:139], v[182:185], v[124:127]
	v_mfma_f32_16x16x32_bf16 v[120:123], v[158:161], v[182:185], v[120:123]
	v_mfma_f32_16x16x32_bf16 v[108:111], v[136:139], v[190:193], v[108:111]
	v_mfma_f32_16x16x32_bf16 v[104:107], v[158:161], v[190:193], v[104:107]
	v_mfma_f32_16x16x32_bf16 v[92:95], v[136:139], v[198:201], v[92:95]
	v_mfma_f32_16x16x32_bf16 v[88:91], v[158:161], v[198:201], v[88:91]
	s_waitcnt lgkmcnt(0)
	v_mfma_f32_16x16x32_bf16 v[76:79], v[136:139], v[206:209], v[76:79]
	v_mfma_f32_16x16x32_bf16 v[72:75], v[158:161], v[206:209], v[72:75]
	s_setprio 0
	s_setprio 1
	v_mfma_f32_16x16x32_bf16 v[116:119], v[162:165], v[178:181], v[116:119]
	v_mfma_f32_16x16x32_bf16 v[112:115], v[170:173], v[178:181], v[112:115]
	v_mfma_f32_16x16x32_bf16 v[100:103], v[162:165], v[186:189], v[100:103]
	v_mfma_f32_16x16x32_bf16 v[96:99], v[170:173], v[186:189], v[96:99]
	v_mfma_f32_16x16x32_bf16 v[84:87], v[162:165], v[194:197], v[84:87]
	v_mfma_f32_16x16x32_bf16 v[80:83], v[170:173], v[194:197], v[80:83]
	v_mfma_f32_16x16x32_bf16 v[68:71], v[162:165], v[202:205], v[68:71]
	v_mfma_f32_16x16x32_bf16 v[64:67], v[170:173], v[202:205], v[64:67]
	v_mfma_f32_16x16x32_bf16 v[116:119], v[166:169], v[182:185], v[116:119]
	v_mfma_f32_16x16x32_bf16 v[112:115], v[174:177], v[182:185], v[112:115]
	v_mfma_f32_16x16x32_bf16 v[100:103], v[166:169], v[190:193], v[100:103]
	v_mfma_f32_16x16x32_bf16 v[96:99], v[174:177], v[190:193], v[96:99]
	v_mfma_f32_16x16x32_bf16 v[84:87], v[166:169], v[198:201], v[84:87]
	v_mfma_f32_16x16x32_bf16 v[80:83], v[174:177], v[198:201], v[80:83]
	v_mfma_f32_16x16x32_bf16 v[68:71], v[166:169], v[206:209], v[68:71]
	v_mfma_f32_16x16x32_bf16 v[64:67], v[174:177], v[206:209], v[64:67]
	s_setprio 0
	s_barrier
	s_mov_b32 m0, s35
	s_mov_b32 s14, s10
	s_mov_b32 s15, s11
	ds_read_b128 v[178:181], v154 offset:16384
	ds_read_b128 v[182:185], v154 offset:17408
	ds_read_b128 v[186:189], v154 offset:18432
	ds_read_b128 v[190:193], v154 offset:19456
	ds_read_b128 v[194:197], v154 offset:20480
	ds_read_b128 v[198:201], v154 offset:21504
	ds_read_b128 v[202:205], v154 offset:22528
	ds_read_b128 v[206:209], v154 offset:23552
	buffer_load_dwordx4 v147, s[12:15], s75 offen lds
	s_mov_b32 m0, s42
	s_add_i32 s77, s75, 0x80000
	buffer_load_dwordx4 v149, s[12:15], s75 offen lds
	s_mov_b32 m0, s43
	s_nop 0
	buffer_load_dwordx4 v147, s[12:15], s77 offen lds
	s_mov_b32 m0, s44
	s_nop 0
	buffer_load_dwordx4 v149, s[12:15], s77 offen lds
	s_mov_b32 m0, s34
	s_nop 0
	buffer_load_dwordx4 v146, s[8:11], s76 offen lds
	s_mov_b32 m0, s45
	s_nop 0
	buffer_load_dwordx4 v148, s[8:11], s76 offen lds
	s_waitcnt vmcnt(8)
	s_waitcnt lgkmcnt(0)
	s_barrier
	s_setprio 1
	s_waitcnt lgkmcnt(7)
	v_mfma_f32_16x16x32_bf16 v[60:63], v[132:135], v[178:181], v[60:63]
	v_mfma_f32_16x16x32_bf16 v[56:59], v[140:143], v[178:181], v[56:59]
	s_waitcnt lgkmcnt(5)
	v_mfma_f32_16x16x32_bf16 v[44:47], v[132:135], v[186:189], v[44:47]
	v_mfma_f32_16x16x32_bf16 v[40:43], v[140:143], v[186:189], v[40:43]
	s_waitcnt lgkmcnt(3)
	v_mfma_f32_16x16x32_bf16 v[28:31], v[132:135], v[194:197], v[28:31]
	v_mfma_f32_16x16x32_bf16 v[24:27], v[140:143], v[194:197], v[24:27]
	s_waitcnt lgkmcnt(1)
	v_mfma_f32_16x16x32_bf16 v[12:15], v[132:135], v[202:205], v[12:15]
	v_mfma_f32_16x16x32_bf16 v[8:11], v[140:143], v[202:205], v[8:11]
	v_mfma_f32_16x16x32_bf16 v[60:63], v[136:139], v[182:185], v[60:63]
	v_mfma_f32_16x16x32_bf16 v[56:59], v[158:161], v[182:185], v[56:59]
	v_mfma_f32_16x16x32_bf16 v[44:47], v[136:139], v[190:193], v[44:47]
	v_mfma_f32_16x16x32_bf16 v[40:43], v[158:161], v[190:193], v[40:43]
	v_mfma_f32_16x16x32_bf16 v[28:31], v[136:139], v[198:201], v[28:31]
	v_mfma_f32_16x16x32_bf16 v[24:27], v[158:161], v[198:201], v[24:27]
	s_waitcnt lgkmcnt(0)
	v_mfma_f32_16x16x32_bf16 v[12:15], v[136:139], v[206:209], v[12:15]
	v_mfma_f32_16x16x32_bf16 v[8:11], v[158:161], v[206:209], v[8:11]
	s_setprio 0
	s_setprio 1
	v_mfma_f32_16x16x32_bf16 v[52:55], v[162:165], v[178:181], v[52:55]
	v_mfma_f32_16x16x32_bf16 v[48:51], v[170:173], v[178:181], v[48:51]
	v_mfma_f32_16x16x32_bf16 v[36:39], v[162:165], v[186:189], v[36:39]
	v_mfma_f32_16x16x32_bf16 v[32:35], v[170:173], v[186:189], v[32:35]
	v_mfma_f32_16x16x32_bf16 v[20:23], v[162:165], v[194:197], v[20:23]
	v_mfma_f32_16x16x32_bf16 v[16:19], v[170:173], v[194:197], v[16:19]
	v_mfma_f32_16x16x32_bf16 v[4:7], v[162:165], v[202:205], v[4:7]
	v_mfma_f32_16x16x32_bf16 v[0:3], v[170:173], v[202:205], v[0:3]
	v_mfma_f32_16x16x32_bf16 v[52:55], v[166:169], v[182:185], v[52:55]
	v_mfma_f32_16x16x32_bf16 v[48:51], v[174:177], v[182:185], v[48:51]
	v_mfma_f32_16x16x32_bf16 v[36:39], v[166:169], v[190:193], v[36:39]
	v_mfma_f32_16x16x32_bf16 v[32:35], v[174:177], v[190:193], v[32:35]
	v_mfma_f32_16x16x32_bf16 v[20:23], v[166:169], v[198:201], v[20:23]
	v_mfma_f32_16x16x32_bf16 v[16:19], v[174:177], v[198:201], v[16:19]
	v_mfma_f32_16x16x32_bf16 v[4:7], v[166:169], v[206:209], v[4:7]
	v_mfma_f32_16x16x32_bf16 v[0:3], v[174:177], v[206:209], v[0:3]
	s_setprio 0
	s_barrier
; #define PG8_STAGE(bufoff, soff, voff) do { _Pragma("unroll") for (int _i = 0; _i < 2; ++_i) \
;         __builtin_amdgcn_raw_ptr_buffer_load_lds(rs_##voff, (PG8_LAS unsigned*)(lds + (bufoff) + ldsw + _i * 8192), 16, (int)(voff)[_i], (int)(soff), 0, 0); } while (0)
; #define PG8_LDA(dst, b, h) do { _Pragma("unroll") for (int m = 0; m < 4; ++m) _Pragma("unroll") for (int k = 0; k < 2; ++k) dst[m][k] = *(const PG8_LAS bf16x8*)(lds + PG8_SA(b, h) + aoff + m * 2048 + k * 1024); } while (0)
; #define PG8_LDB(dst, b, h) do { _Pragma("unroll") for (int n = 0; n < 2; ++n) _Pragma("unroll") for (int k = 0; k < 2; ++k) dst[n][k] = *(const PG8_LAS bf16x8*)(lds + PG8_SB(b, h) + boff + n * 2048 + k * 1024); } while (0)
; #define PG8_MMA(ai, bj, At, Bt) do { __builtin_amdgcn_s_setprio(1); _Pragma("unroll") for (int m = 0; m < 4; ++m) _Pragma("unroll") for (int n = 0; n < 2; ++n) _Pragma("unroll") for (int k = 0; k < 2; ++k) \
;         acc[ai][bj][m][n] = __builtin_amdgcn_mfma_f32_16x16x32_bf16(Bt[n][k], At[m][k], acc[ai][bj][m][n], 0, 0, 0); __builtin_amdgcn_s_setprio(0); } while (0)
; #define PG8_WAIT_V(n) asm volatile("s_waitcnt vmcnt(" #n ")" ::: "memory")
; #define PG8_WAIT_L(n) asm volatile("s_waitcnt lgkmcnt(" #n ")" ::: "memory")
; #define PG8_BAR __builtin_amdgcn_s_barrier()
; #define PG8_SCHED __builtin_amdgcn_sched_barrier(0)
; template <class Epi, class Sched, bool ALIGN_EPI = false, bool SP2 = false>
; __device__ __forceinline__ void gemm_phase(PG8_LAS unsigned char* lds, const Gemm g, const Sched& S, const Epi& E, const int wid  ) {
;     ...
;             PG8_LDB(B0, 1, 0); PG8_LDB(B1, 1, 1); PG8_SCHED; PG8_LDA(At, 1, 0); PG8_STAGE(PG8_SA(0, 1), a2 + hstep, voffA);
;             PG8_WAIT_V(8); PG8_WAIT_L(0); PG8_BAR; PG8_MMA(0, 0, At, B0); PG8_MMA(0, 1, At, B1); PG8_BAR; PG8_SCHED;
;             PG8_LDA(At, 1, 1); PG8_STAGE(PG8_SB(1, 0), b3, voffB); PG8_STAGE(PG8_SB(1, 1), b3 + hstep, voffB); PG8_STAGE(PG8_SA(1, 0), a3, voffA);
;             PG8_WAIT_V(8); PG8_WAIT_L(0); PG8_BAR; PG8_MMA(1, 0, At, B0); PG8_MMA(1, 1, At, B1); PG8_BAR; PG8_SCHED;
;     ...
;         if constexpr (ALIGN_EPI) { if (wr == 0) PG8_BAR; }
	ds_read_b128 v[132:135], v155
	ds_read_b128 v[136:139], v155 offset:1024
	ds_read_b128 v[140:143], v155 offset:2048
	ds_read_b128 v[158:161], v155 offset:3072
	ds_read_b128 v[162:165], v156
	ds_read_b128 v[166:169], v156 offset:1024
	ds_read_b128 v[170:173], v156 offset:2048
	ds_read_b128 v[174:177], v156 offset:3072
	s_add_i32 s76, s76, 0x80000
	s_mov_b32 m0, s46
	ds_read_b128 v[178:181], v154 offset:32768
	ds_read_b128 v[182:185], v154 offset:33792
	ds_read_b128 v[186:189], v154 offset:34816
	ds_read_b128 v[190:193], v154 offset:35840
	ds_read_b128 v[194:197], v154 offset:36864
	ds_read_b128 v[198:201], v154 offset:37888
	ds_read_b128 v[202:205], v154 offset:38912
	ds_read_b128 v[206:209], v154 offset:39936
	buffer_load_dwordx4 v146, s[8:11], s76 offen lds
	s_mov_b32 m0, s48
	s_nop 0
	buffer_load_dwordx4 v148, s[8:11], s76 offen lds
	s_waitcnt vmcnt(8)
	s_waitcnt lgkmcnt(0)
	s_barrier
	s_setprio 1
	s_waitcnt lgkmcnt(7)
	v_mfma_f32_16x16x32_bf16 v[124:127], v[132:135], v[178:181], v[124:127]
	v_mfma_f32_16x16x32_bf16 v[120:123], v[140:143], v[178:181], v[120:123]
	s_waitcnt lgkmcnt(5)
	v_mfma_f32_16x16x32_bf16 v[108:111], v[132:135], v[186:189], v[108:111]
	v_mfma_f32_16x16x32_bf16 v[104:107], v[140:143], v[186:189], v[104:107]
	s_waitcnt lgkmcnt(3)
	v_mfma_f32_16x16x32_bf16 v[92:95], v[132:135], v[194:197], v[92:95]
	v_mfma_f32_16x16x32_bf16 v[88:91], v[140:143], v[194:197], v[88:91]
	s_waitcnt lgkmcnt(1)
	v_mfma_f32_16x16x32_bf16 v[76:79], v[132:135], v[202:205], v[76:79]
	v_mfma_f32_16x16x32_bf16 v[72:75], v[140:143], v[202:205], v[72:75]
	v_mfma_f32_16x16x32_bf16 v[124:127], v[136:139], v[182:185], v[124:127]
	v_mfma_f32_16x16x32_bf16 v[120:123], v[158:161], v[182:185], v[120:123]
	v_mfma_f32_16x16x32_bf16 v[108:111], v[136:139], v[190:193], v[108:111]
	v_mfma_f32_16x16x32_bf16 v[104:107], v[158:161], v[190:193], v[104:107]
	v_mfma_f32_16x16x32_bf16 v[92:95], v[136:139], v[198:201], v[92:95]
	v_mfma_f32_16x16x32_bf16 v[88:91], v[158:161], v[198:201], v[88:91]
	s_waitcnt lgkmcnt(0)
	v_mfma_f32_16x16x32_bf16 v[76:79], v[136:139], v[206:209], v[76:79]
	v_mfma_f32_16x16x32_bf16 v[72:75], v[158:161], v[206:209], v[72:75]
	s_setprio 0
	s_setprio 1
	v_mfma_f32_16x16x32_bf16 v[116:119], v[162:165], v[178:181], v[116:119]
	v_mfma_f32_16x16x32_bf16 v[112:115], v[170:173], v[178:181], v[112:115]
	v_mfma_f32_16x16x32_bf16 v[100:103], v[162:165], v[186:189], v[100:103]
	v_mfma_f32_16x16x32_bf16 v[96:99], v[170:173], v[186:189], v[96:99]
	v_mfma_f32_16x16x32_bf16 v[84:87], v[162:165], v[194:197], v[84:87]
	v_mfma_f32_16x16x32_bf16 v[80:83], v[170:173], v[194:197], v[80:83]
	v_mfma_f32_16x16x32_bf16 v[68:71], v[162:165], v[202:205], v[68:71]
	v_mfma_f32_16x16x32_bf16 v[64:67], v[170:173], v[202:205], v[64:67]
	v_mfma_f32_16x16x32_bf16 v[116:119], v[166:169], v[182:185], v[116:119]
	v_mfma_f32_16x16x32_bf16 v[112:115], v[174:177], v[182:185], v[112:115]
	v_mfma_f32_16x16x32_bf16 v[100:103], v[166:169], v[190:193], v[100:103]
	v_mfma_f32_16x16x32_bf16 v[96:99], v[174:177], v[190:193], v[96:99]
	v_mfma_f32_16x16x32_bf16 v[84:87], v[166:169], v[198:201], v[84:87]
	v_mfma_f32_16x16x32_bf16 v[80:83], v[174:177], v[198:201], v[80:83]
	v_mfma_f32_16x16x32_bf16 v[68:71], v[166:169], v[206:209], v[68:71]
	v_mfma_f32_16x16x32_bf16 v[64:67], v[174:177], v[206:209], v[64:67]
	s_setprio 0
	s_barrier
	s_mov_b32 m0, s50
	s_or_b32 s76, s75, 0x80
	ds_read_b128 v[178:181], v154 offset:49152
	ds_read_b128 v[182:185], v154 offset:50176
	ds_read_b128 v[186:189], v154 offset:51200
	ds_read_b128 v[190:193], v154 offset:52224
	ds_read_b128 v[194:197], v154 offset:53248
	ds_read_b128 v[198:201], v154 offset:54272
	ds_read_b128 v[202:205], v154 offset:55296
	ds_read_b128 v[206:209], v154 offset:56320
	buffer_load_dwordx4 v147, s[12:15], s76 offen lds
	s_mov_b32 m0, s51
	s_add_i32 s75, s75, 0x80080
	buffer_load_dwordx4 v149, s[12:15], s76 offen lds
	s_mov_b32 m0, s55
	s_nop 0
	buffer_load_dwordx4 v147, s[12:15], s75 offen lds
	s_mov_b32 m0, s58
	s_nop 0
	buffer_load_dwordx4 v149, s[12:15], s75 offen lds
	s_mov_b32 m0, s53
	s_nop 0
	buffer_load_dwordx4 v146, s[8:11], s74 offen lds
	s_mov_b32 m0, s54
	s_nop 0
	buffer_load_dwordx4 v148, s[8:11], s74 offen lds
	s_waitcnt vmcnt(8)
	s_waitcnt lgkmcnt(0)
	s_barrier
	s_setprio 1
	s_waitcnt lgkmcnt(7)
	v_mfma_f32_16x16x32_bf16 v[60:63], v[132:135], v[178:181], v[60:63]
	v_mfma_f32_16x16x32_bf16 v[56:59], v[140:143], v[178:181], v[56:59]
	s_waitcnt lgkmcnt(5)
	v_mfma_f32_16x16x32_bf16 v[44:47], v[132:135], v[186:189], v[44:47]
	v_mfma_f32_16x16x32_bf16 v[40:43], v[140:143], v[186:189], v[40:43]
	s_waitcnt lgkmcnt(3)
	v_mfma_f32_16x16x32_bf16 v[28:31], v[132:135], v[194:197], v[28:31]
	v_mfma_f32_16x16x32_bf16 v[24:27], v[140:143], v[194:197], v[24:27]
	s_waitcnt lgkmcnt(1)
	v_mfma_f32_16x16x32_bf16 v[12:15], v[132:135], v[202:205], v[12:15]
	v_mfma_f32_16x16x32_bf16 v[8:11], v[140:143], v[202:205], v[8:11]
	v_mfma_f32_16x16x32_bf16 v[60:63], v[136:139], v[182:185], v[60:63]
	v_mfma_f32_16x16x32_bf16 v[56:59], v[158:161], v[182:185], v[56:59]
	v_mfma_f32_16x16x32_bf16 v[44:47], v[136:139], v[190:193], v[44:47]
	v_mfma_f32_16x16x32_bf16 v[40:43], v[158:161], v[190:193], v[40:43]
	v_mfma_f32_16x16x32_bf16 v[28:31], v[136:139], v[198:201], v[28:31]
	v_mfma_f32_16x16x32_bf16 v[24:27], v[158:161], v[198:201], v[24:27]
	s_waitcnt lgkmcnt(0)
	v_mfma_f32_16x16x32_bf16 v[12:15], v[136:139], v[206:209], v[12:15]
	v_mfma_f32_16x16x32_bf16 v[8:11], v[158:161], v[206:209], v[8:11]
	s_setprio 0
	s_setprio 1
	v_mfma_f32_16x16x32_bf16 v[52:55], v[162:165], v[178:181], v[52:55]
	v_mfma_f32_16x16x32_bf16 v[48:51], v[170:173], v[178:181], v[48:51]
	v_mfma_f32_16x16x32_bf16 v[36:39], v[162:165], v[186:189], v[36:39]
	v_mfma_f32_16x16x32_bf16 v[32:35], v[170:173], v[186:189], v[32:35]
	v_mfma_f32_16x16x32_bf16 v[20:23], v[162:165], v[194:197], v[20:23]
	v_mfma_f32_16x16x32_bf16 v[16:19], v[170:173], v[194:197], v[16:19]
	v_mfma_f32_16x16x32_bf16 v[4:7], v[162:165], v[202:205], v[4:7]
	v_mfma_f32_16x16x32_bf16 v[0:3], v[170:173], v[202:205], v[0:3]
	v_mfma_f32_16x16x32_bf16 v[52:55], v[166:169], v[182:185], v[52:55]
	v_mfma_f32_16x16x32_bf16 v[48:51], v[174:177], v[182:185], v[48:51]
	v_mfma_f32_16x16x32_bf16 v[36:39], v[166:169], v[190:193], v[36:39]
	v_mfma_f32_16x16x32_bf16 v[32:35], v[174:177], v[190:193], v[32:35]
	v_mfma_f32_16x16x32_bf16 v[20:23], v[166:169], v[198:201], v[20:23]
	v_mfma_f32_16x16x32_bf16 v[16:19], v[174:177], v[198:201], v[16:19]
	v_mfma_f32_16x16x32_bf16 v[4:7], v[166:169], v[206:209], v[4:7]
	v_mfma_f32_16x16x32_bf16 v[0:3], v[174:177], v[206:209], v[0:3]
	s_setprio 0
	s_add_i32 s73, s73, 2
	s_addk_i32 s41, 0x100
	s_addk_i32 s72, 0x100
	s_cmp_gt_u32 s73, 29
	s_cbranch_scc0 .Lrot_4016
	s_barrier
	s_and_b64 vcc, exec, s[26:27]
	s_cbranch_vccz .LBB0_4019
	s_barrier
